# FFN-in epilogue v2: two passes over row blocks (n outer), conv taps as v_fmac_f32_dpp with lane-masked halo weights (5 VALU per value instead of 7), gelu constants merged
# speedup vs baseline: 1.0164x; 1.0142x over previous
.LBB0_993:
	v_mov_b32_e32 v134, v192
	v_mov_b32_e32 v135, v192
	s_lshl_b32 s6, s30, 7
	v_bfe_i32 v128, v135, 7, 1
	v_and_b32_e32 v128, 0xb00, v128
	v_add_u32_e32 v128, s6, v128
	s_movk_i32 s7, 0x7f
	v_and_or_b32 v128, v135, s7, v128
	v_ashrrev_i32_e32 v129, 31, v128
	v_lshl_add_u64 v[130:131], v[128:129], 2, s[20:21]
	v_ashrrev_i32_e32 v129, 8, v135
	v_mad_i32_i24 v132, v129, s79, v128
	v_ashrrev_i32_e32 v133, 31, v132
	v_lshl_add_u64 v[132:133], v[132:133], 2, s[18:19]
	v_cmp_gt_i32_e32 vcc, 3, v129
	v_add_u32_e32 v129, 0x200, v135
	v_lshl_add_u32 v135, v135, 2, 0
	v_cndmask_b32_e32 v133, v131, v133, vcc
	v_cndmask_b32_e32 v132, v130, v132, vcc
	global_load_dword v132, v[132:133], off
	v_ashrrev_i32_e32 v133, 8, v129
	v_mad_i32_i24 v128, v133, s79, v128
	v_ashrrev_i32_e32 v129, 31, v128
	v_lshl_add_u64 v[128:129], v[128:129], 2, s[18:19]
	v_cmp_gt_i32_e32 vcc, 3, v133
	s_mulk_i32 s0, 0xfc
	v_lshrrev_b32_e32 v136, 1, v134
	v_cndmask_b32_e32 v129, v131, v129, vcc
	v_cndmask_b32_e32 v128, v130, v128, vcc
	global_load_dword v133, v[128:129], off
	v_add_u32_e32 v135, 0x20000, v135
	s_add_i32 s0, s66, s0
	v_and_b32_e32 v219, 15, v134
	v_and_or_b32 v134, v136, 24, s62
	v_add_u32_e32 v218, s0, v219
	v_or_b32_e32 v136, 0x80, v134
	v_or_b32_e32 v137, 4, v134
	v_or_b32_e32 v138, 0x84, v134
	v_cmp_lt_u32_e32 vcc, 1, v219
	v_or_b32_e32 v188, s6, v134
	v_cmp_gt_i32_e64 s[6:7], s58, v218
	v_lshlrev_b32_e32 v172, 2, v134
	v_lshlrev_b32_e32 v210, 2, v137
	v_lshlrev_b32_e32 v206, 2, v136
	v_lshlrev_b32_e32 v212, 2, v138
	v_ashrrev_i32_e32 v189, 31, v188
	s_and_b64 s[6:7], vcc, s[6:7]
	s_waitcnt vmcnt(0)
	ds_write2st64_b32 v135, v132, v133 offset1:8
	s_waitcnt lgkmcnt(0)
	s_barrier
	v_add_u32_e32 v203, 0x20000, v172
	ds_read_b128 v[128:131], v203 offset:0
	ds_read_b128 v[132:135], v203 offset:512
	ds_read_b128 v[136:139], v203 offset:1024
	ds_read_b128 v[140:143], v203 offset:1536
	ds_read_b128 v[144:147], v203 offset:2048
	ds_read_b128 v[148:151], v203 offset:2560
	ds_read_b128 v[152:155], v203 offset:3072
	ds_read_b128 v[156:159], v203 offset:3584
	v_lshl_add_u64 v[190:191], v[188:189], 1, s[16:17]
	s_waitcnt lgkmcnt(0)
	s_mov_b32 s6, 0x10001
	s_mov_b32 s7, 0x10001
	s_mov_b32 s10, 0x30003
	s_mov_b32 s11, 0x30003
	s_nop 0
	v_cndmask_b32_e64 v160, 0, v136, s[6:7]
	v_cndmask_b32_e64 v161, 0, v137, s[6:7]
	v_cndmask_b32_e64 v162, 0, v138, s[6:7]
	v_cndmask_b32_e64 v163, 0, v139, s[6:7]
	v_cndmask_b32_e64 v164, 0, v140, s[6:7]
	v_cndmask_b32_e64 v165, 0, v141, s[6:7]
	v_cndmask_b32_e64 v166, 0, v142, s[6:7]
	v_cndmask_b32_e64 v167, 0, v143, s[6:7]
	v_cndmask_b32_e64 v168, 0, v128, s[10:11]
	v_cndmask_b32_e64 v169, 0, v129, s[10:11]
	v_cndmask_b32_e64 v170, 0, v130, s[10:11]
	v_cndmask_b32_e64 v171, 0, v131, s[10:11]
	v_cndmask_b32_e64 v204, 0, v132, s[10:11]
	v_cndmask_b32_e64 v205, 0, v133, s[10:11]
	v_cndmask_b32_e64 v206, 0, v134, s[10:11]
	v_cndmask_b32_e64 v207, 0, v135, s[10:11]
	s_add_i32 s6, s0, 2079
	s_mul_hi_u32 s7, s6, s59
	s_lshr_b32 s7, s7, 7
	s_mulk_i32 s7, 0x810
	s_sub_i32 s6, s6, s7
	s_cmp_lt_u32 s6, 17
	s_cbranch_scc1 .Lffn1e_slow0_0
	v_fma_f32 v236, v124, v144, v152
	v_fma_f32 v237, v125, v145, v153
	v_fma_f32 v238, v126, v146, v154
	v_fma_f32 v239, v127, v147, v155
	v_fmac_f32_dpp v236, v124, v136 row_shr:1 row_mask:0xf bank_mask:0xf bound_ctrl:1
	v_fmac_f32_dpp v237, v125, v137 row_shr:1 row_mask:0xf bank_mask:0xf bound_ctrl:1
	v_fmac_f32_dpp v238, v126, v138 row_shr:1 row_mask:0xf bank_mask:0xf bound_ctrl:1
	v_fmac_f32_dpp v239, v127, v139 row_shr:1 row_mask:0xf bank_mask:0xf bound_ctrl:1
	v_fmac_f32_dpp v236, v124, v128 row_shr:2 row_mask:0xf bank_mask:0xf bound_ctrl:1
	v_fmac_f32_dpp v237, v125, v129 row_shr:2 row_mask:0xf bank_mask:0xf bound_ctrl:1
	v_fmac_f32_dpp v238, v126, v130 row_shr:2 row_mask:0xf bank_mask:0xf bound_ctrl:1
	v_fmac_f32_dpp v239, v127, v131 row_shr:2 row_mask:0xf bank_mask:0xf bound_ctrl:1
	v_fma_f32 v240, v116, v148, v156
	v_fma_f32 v241, v117, v149, v157
	v_fma_f32 v242, v118, v150, v158
	v_fma_f32 v243, v119, v151, v159
	v_fmac_f32_dpp v240, v116, v140 row_shr:1 row_mask:0xf bank_mask:0xf bound_ctrl:1
	v_fmac_f32_dpp v241, v117, v141 row_shr:1 row_mask:0xf bank_mask:0xf bound_ctrl:1
	v_fmac_f32_dpp v242, v118, v142 row_shr:1 row_mask:0xf bank_mask:0xf bound_ctrl:1
	v_fmac_f32_dpp v243, v119, v143 row_shr:1 row_mask:0xf bank_mask:0xf bound_ctrl:1
	v_fmac_f32_dpp v240, v116, v132 row_shr:2 row_mask:0xf bank_mask:0xf bound_ctrl:1
	v_fmac_f32_dpp v241, v117, v133 row_shr:2 row_mask:0xf bank_mask:0xf bound_ctrl:1
	v_fmac_f32_dpp v242, v118, v134 row_shr:2 row_mask:0xf bank_mask:0xf bound_ctrl:1
	v_fmac_f32_dpp v243, v119, v135 row_shr:2 row_mask:0xf bank_mask:0xf bound_ctrl:1
	v_mov_b32_e32 v228, 0xbdd2d3e8
	v_mul_f32_e32 v244, v236, v236
	v_mul_f32_e32 v245, v237, v237
	v_mul_f32_e32 v246, v238, v238
	v_mul_f32_e32 v247, v239, v239
	v_fmaak_f32 v244, v244, v228, 0xc0135761
	v_fmaak_f32 v245, v245, v228, 0xc0135761
	v_fmaak_f32 v246, v246, v228, 0xc0135761
	v_fmaak_f32 v247, v247, v228, 0xc0135761
	v_mul_f32_e32 v244, v236, v244
	v_mul_f32_e32 v245, v237, v245
	v_mul_f32_e32 v246, v238, v246
	v_mul_f32_e32 v247, v239, v247
	v_exp_f32_e32 v244, v244
	v_exp_f32_e32 v245, v245
	v_exp_f32_e32 v246, v246
	v_exp_f32_e32 v247, v247
	v_add_f32_e32 v244, 1.0, v244
	v_add_f32_e32 v245, 1.0, v245
	v_add_f32_e32 v246, 1.0, v246
	v_add_f32_e32 v247, 1.0, v247
	v_rcp_f32_e32 v244, v244
	v_rcp_f32_e32 v245, v245
	v_rcp_f32_e32 v246, v246
	v_rcp_f32_e32 v247, v247
	v_mul_f32_e32 v244, v236, v244
	v_mul_f32_e32 v245, v237, v245
	v_mul_f32_e32 v246, v238, v246
	v_mul_f32_e32 v247, v239, v247
	v_mul_f32_e32 v248, v240, v244
	v_mul_f32_e32 v249, v241, v245
	v_mul_f32_e32 v250, v242, v246
	v_mul_f32_e32 v251, v243, v247
	v_cvt_pk_bf16_f32 v208, v248, v249
	v_cvt_pk_bf16_f32 v209, v250, v251
.Lffn1e_join0_0:
	s_add_i32 s6, s0, 2095
	s_mul_hi_u32 s7, s6, s59
	s_lshr_b32 s7, s7, 7
	s_mulk_i32 s7, 0x810
	s_sub_i32 s6, s6, s7
	s_cmp_lt_u32 s6, 17
	s_cbranch_scc1 .Lffn1e_slow0_1
	s_cmp_lt_u32 s6, 33
	s_cbranch_scc1 .Lffn1e_old0_1
	v_fma_f32 v236, v108, v144, v152
	v_fma_f32 v237, v109, v145, v153
	v_fma_f32 v238, v110, v146, v154
	v_fma_f32 v239, v111, v147, v155
	v_fmac_f32_dpp v236, v108, v136 row_shr:1 row_mask:0xf bank_mask:0xf bound_ctrl:1
	v_fmac_f32_dpp v237, v109, v137 row_shr:1 row_mask:0xf bank_mask:0xf bound_ctrl:1
	v_fmac_f32_dpp v238, v110, v138 row_shr:1 row_mask:0xf bank_mask:0xf bound_ctrl:1
	v_fmac_f32_dpp v239, v111, v139 row_shr:1 row_mask:0xf bank_mask:0xf bound_ctrl:1
	v_fmac_f32_dpp v236, v108, v128 row_shr:2 row_mask:0xf bank_mask:0xf bound_ctrl:1
	v_fmac_f32_dpp v237, v109, v129 row_shr:2 row_mask:0xf bank_mask:0xf bound_ctrl:1
	v_fmac_f32_dpp v238, v110, v130 row_shr:2 row_mask:0xf bank_mask:0xf bound_ctrl:1
	v_fmac_f32_dpp v239, v111, v131 row_shr:2 row_mask:0xf bank_mask:0xf bound_ctrl:1
	v_fmac_f32_dpp v236, v124, v160 row_ror:1 row_mask:0xf bank_mask:0xf
	v_fmac_f32_dpp v237, v125, v161 row_ror:1 row_mask:0xf bank_mask:0xf
	v_fmac_f32_dpp v238, v126, v162 row_ror:1 row_mask:0xf bank_mask:0xf
	v_fmac_f32_dpp v239, v127, v163 row_ror:1 row_mask:0xf bank_mask:0xf
	v_fmac_f32_dpp v236, v124, v168 row_ror:2 row_mask:0xf bank_mask:0xf
	v_fmac_f32_dpp v237, v125, v169 row_ror:2 row_mask:0xf bank_mask:0xf
	v_fmac_f32_dpp v238, v126, v170 row_ror:2 row_mask:0xf bank_mask:0xf
	v_fmac_f32_dpp v239, v127, v171 row_ror:2 row_mask:0xf bank_mask:0xf
	v_fma_f32 v240, v100, v148, v156
	v_fma_f32 v241, v101, v149, v157
	v_fma_f32 v242, v102, v150, v158
	v_fma_f32 v243, v103, v151, v159
	v_fmac_f32_dpp v240, v100, v140 row_shr:1 row_mask:0xf bank_mask:0xf bound_ctrl:1
	v_fmac_f32_dpp v241, v101, v141 row_shr:1 row_mask:0xf bank_mask:0xf bound_ctrl:1
	v_fmac_f32_dpp v242, v102, v142 row_shr:1 row_mask:0xf bank_mask:0xf bound_ctrl:1
	v_fmac_f32_dpp v243, v103, v143 row_shr:1 row_mask:0xf bank_mask:0xf bound_ctrl:1
	v_fmac_f32_dpp v240, v100, v132 row_shr:2 row_mask:0xf bank_mask:0xf bound_ctrl:1
	v_fmac_f32_dpp v241, v101, v133 row_shr:2 row_mask:0xf bank_mask:0xf bound_ctrl:1
	v_fmac_f32_dpp v242, v102, v134 row_shr:2 row_mask:0xf bank_mask:0xf bound_ctrl:1
	v_fmac_f32_dpp v243, v103, v135 row_shr:2 row_mask:0xf bank_mask:0xf bound_ctrl:1
	v_fmac_f32_dpp v240, v116, v164 row_ror:1 row_mask:0xf bank_mask:0xf
	v_fmac_f32_dpp v241, v117, v165 row_ror:1 row_mask:0xf bank_mask:0xf
	v_fmac_f32_dpp v242, v118, v166 row_ror:1 row_mask:0xf bank_mask:0xf
	v_fmac_f32_dpp v243, v119, v167 row_ror:1 row_mask:0xf bank_mask:0xf
	v_fmac_f32_dpp v240, v116, v204 row_ror:2 row_mask:0xf bank_mask:0xf
	v_fmac_f32_dpp v241, v117, v205 row_ror:2 row_mask:0xf bank_mask:0xf
	v_fmac_f32_dpp v242, v118, v206 row_ror:2 row_mask:0xf bank_mask:0xf
	v_fmac_f32_dpp v243, v119, v207 row_ror:2 row_mask:0xf bank_mask:0xf
	v_mov_b32_e32 v228, 0xbdd2d3e8
	v_mul_f32_e32 v244, v236, v236
	v_mul_f32_e32 v245, v237, v237
	v_mul_f32_e32 v246, v238, v238
	v_mul_f32_e32 v247, v239, v239
	v_fmaak_f32 v244, v244, v228, 0xc0135761
	v_fmaak_f32 v245, v245, v228, 0xc0135761
	v_fmaak_f32 v246, v246, v228, 0xc0135761
	v_fmaak_f32 v247, v247, v228, 0xc0135761
	v_mul_f32_e32 v244, v236, v244
	v_mul_f32_e32 v245, v237, v245
	v_mul_f32_e32 v246, v238, v246
	v_mul_f32_e32 v247, v239, v247
	v_exp_f32_e32 v244, v244
	v_exp_f32_e32 v245, v245
	v_exp_f32_e32 v246, v246
	v_exp_f32_e32 v247, v247
	v_add_f32_e32 v244, 1.0, v244
	v_add_f32_e32 v245, 1.0, v245
	v_add_f32_e32 v246, 1.0, v246
	v_add_f32_e32 v247, 1.0, v247
	v_rcp_f32_e32 v244, v244
	v_rcp_f32_e32 v245, v245
	v_rcp_f32_e32 v246, v246
	v_rcp_f32_e32 v247, v247
	v_mul_f32_e32 v244, v236, v244
	v_mul_f32_e32 v245, v237, v245
	v_mul_f32_e32 v246, v238, v246
	v_mul_f32_e32 v247, v239, v247
	v_mul_f32_e32 v248, v240, v244
	v_mul_f32_e32 v249, v241, v245
	v_mul_f32_e32 v250, v242, v246
	v_mul_f32_e32 v251, v243, v247
	v_cvt_pk_bf16_f32 v210, v248, v249
	v_cvt_pk_bf16_f32 v211, v250, v251
.Lffn1e_join0_1:
	s_add_i32 s6, s0, 2111
	s_mul_hi_u32 s7, s6, s59
	s_lshr_b32 s7, s7, 7
	s_mulk_i32 s7, 0x810
	s_sub_i32 s6, s6, s7
	s_cmp_lt_u32 s6, 17
	s_cbranch_scc1 .Lffn1e_slow0_2
	s_cmp_lt_u32 s6, 33
	s_cbranch_scc1 .Lffn1e_old0_2
	v_fma_f32 v236, v92, v144, v152
	v_fma_f32 v237, v93, v145, v153
	v_fma_f32 v238, v94, v146, v154
	v_fma_f32 v239, v95, v147, v155
	v_fmac_f32_dpp v236, v92, v136 row_shr:1 row_mask:0xf bank_mask:0xf bound_ctrl:1
	v_fmac_f32_dpp v237, v93, v137 row_shr:1 row_mask:0xf bank_mask:0xf bound_ctrl:1
	v_fmac_f32_dpp v238, v94, v138 row_shr:1 row_mask:0xf bank_mask:0xf bound_ctrl:1
	v_fmac_f32_dpp v239, v95, v139 row_shr:1 row_mask:0xf bank_mask:0xf bound_ctrl:1
	v_fmac_f32_dpp v236, v92, v128 row_shr:2 row_mask:0xf bank_mask:0xf bound_ctrl:1
	v_fmac_f32_dpp v237, v93, v129 row_shr:2 row_mask:0xf bank_mask:0xf bound_ctrl:1
	v_fmac_f32_dpp v238, v94, v130 row_shr:2 row_mask:0xf bank_mask:0xf bound_ctrl:1
	v_fmac_f32_dpp v239, v95, v131 row_shr:2 row_mask:0xf bank_mask:0xf bound_ctrl:1
	v_fmac_f32_dpp v236, v108, v160 row_ror:1 row_mask:0xf bank_mask:0xf
	v_fmac_f32_dpp v237, v109, v161 row_ror:1 row_mask:0xf bank_mask:0xf
	v_fmac_f32_dpp v238, v110, v162 row_ror:1 row_mask:0xf bank_mask:0xf
	v_fmac_f32_dpp v239, v111, v163 row_ror:1 row_mask:0xf bank_mask:0xf
	v_fmac_f32_dpp v236, v108, v168 row_ror:2 row_mask:0xf bank_mask:0xf
	v_fmac_f32_dpp v237, v109, v169 row_ror:2 row_mask:0xf bank_mask:0xf
	v_fmac_f32_dpp v238, v110, v170 row_ror:2 row_mask:0xf bank_mask:0xf
	v_fmac_f32_dpp v239, v111, v171 row_ror:2 row_mask:0xf bank_mask:0xf
	v_fma_f32 v240, v84, v148, v156
	v_fma_f32 v241, v85, v149, v157
	v_fma_f32 v242, v86, v150, v158
	v_fma_f32 v243, v87, v151, v159
	v_fmac_f32_dpp v240, v84, v140 row_shr:1 row_mask:0xf bank_mask:0xf bound_ctrl:1
	v_fmac_f32_dpp v241, v85, v141 row_shr:1 row_mask:0xf bank_mask:0xf bound_ctrl:1
	v_fmac_f32_dpp v242, v86, v142 row_shr:1 row_mask:0xf bank_mask:0xf bound_ctrl:1
	v_fmac_f32_dpp v243, v87, v143 row_shr:1 row_mask:0xf bank_mask:0xf bound_ctrl:1
	v_fmac_f32_dpp v240, v84, v132 row_shr:2 row_mask:0xf bank_mask:0xf bound_ctrl:1
	v_fmac_f32_dpp v241, v85, v133 row_shr:2 row_mask:0xf bank_mask:0xf bound_ctrl:1
	v_fmac_f32_dpp v242, v86, v134 row_shr:2 row_mask:0xf bank_mask:0xf bound_ctrl:1
	v_fmac_f32_dpp v243, v87, v135 row_shr:2 row_mask:0xf bank_mask:0xf bound_ctrl:1
	v_fmac_f32_dpp v240, v100, v164 row_ror:1 row_mask:0xf bank_mask:0xf
	v_fmac_f32_dpp v241, v101, v165 row_ror:1 row_mask:0xf bank_mask:0xf
	v_fmac_f32_dpp v242, v102, v166 row_ror:1 row_mask:0xf bank_mask:0xf
	v_fmac_f32_dpp v243, v103, v167 row_ror:1 row_mask:0xf bank_mask:0xf
	v_fmac_f32_dpp v240, v100, v204 row_ror:2 row_mask:0xf bank_mask:0xf
	v_fmac_f32_dpp v241, v101, v205 row_ror:2 row_mask:0xf bank_mask:0xf
	v_fmac_f32_dpp v242, v102, v206 row_ror:2 row_mask:0xf bank_mask:0xf
	v_fmac_f32_dpp v243, v103, v207 row_ror:2 row_mask:0xf bank_mask:0xf
	v_mov_b32_e32 v228, 0xbdd2d3e8
	v_mul_f32_e32 v244, v236, v236
	v_mul_f32_e32 v245, v237, v237
	v_mul_f32_e32 v246, v238, v238
	v_mul_f32_e32 v247, v239, v239
	v_fmaak_f32 v244, v244, v228, 0xc0135761
	v_fmaak_f32 v245, v245, v228, 0xc0135761
	v_fmaak_f32 v246, v246, v228, 0xc0135761
	v_fmaak_f32 v247, v247, v228, 0xc0135761
	v_mul_f32_e32 v244, v236, v244
	v_mul_f32_e32 v245, v237, v245
	v_mul_f32_e32 v246, v238, v246
	v_mul_f32_e32 v247, v239, v247
	v_exp_f32_e32 v244, v244
	v_exp_f32_e32 v245, v245
	v_exp_f32_e32 v246, v246
	v_exp_f32_e32 v247, v247
	v_add_f32_e32 v244, 1.0, v244
	v_add_f32_e32 v245, 1.0, v245
	v_add_f32_e32 v246, 1.0, v246
	v_add_f32_e32 v247, 1.0, v247
	v_rcp_f32_e32 v244, v244
	v_rcp_f32_e32 v245, v245
	v_rcp_f32_e32 v246, v246
	v_rcp_f32_e32 v247, v247
	v_mul_f32_e32 v244, v236, v244
	v_mul_f32_e32 v245, v237, v245
	v_mul_f32_e32 v246, v238, v246
	v_mul_f32_e32 v247, v239, v247
	v_mul_f32_e32 v248, v240, v244
	v_mul_f32_e32 v249, v241, v245
	v_mul_f32_e32 v250, v242, v246
	v_mul_f32_e32 v251, v243, v247
	v_cvt_pk_bf16_f32 v212, v248, v249
	v_cvt_pk_bf16_f32 v213, v250, v251
.Lffn1e_join0_2:
	s_add_i32 s6, s0, 2127
	s_mul_hi_u32 s7, s6, s59
	s_lshr_b32 s7, s7, 7
	s_mulk_i32 s7, 0x810
	s_sub_i32 s6, s6, s7
	s_cmp_lt_u32 s6, 17
	s_cbranch_scc1 .Lffn1e_slow0_3
	s_cmp_lt_u32 s6, 33
	s_cbranch_scc1 .Lffn1e_old0_3
	v_fma_f32 v236, v76, v144, v152
	v_fma_f32 v237, v77, v145, v153
	v_fma_f32 v238, v78, v146, v154
	v_fma_f32 v239, v79, v147, v155
	v_fmac_f32_dpp v236, v76, v136 row_shr:1 row_mask:0xf bank_mask:0xf bound_ctrl:1
	v_fmac_f32_dpp v237, v77, v137 row_shr:1 row_mask:0xf bank_mask:0xf bound_ctrl:1
	v_fmac_f32_dpp v238, v78, v138 row_shr:1 row_mask:0xf bank_mask:0xf bound_ctrl:1
	v_fmac_f32_dpp v239, v79, v139 row_shr:1 row_mask:0xf bank_mask:0xf bound_ctrl:1
	v_fmac_f32_dpp v236, v76, v128 row_shr:2 row_mask:0xf bank_mask:0xf bound_ctrl:1
	v_fmac_f32_dpp v237, v77, v129 row_shr:2 row_mask:0xf bank_mask:0xf bound_ctrl:1
	v_fmac_f32_dpp v238, v78, v130 row_shr:2 row_mask:0xf bank_mask:0xf bound_ctrl:1
	v_fmac_f32_dpp v239, v79, v131 row_shr:2 row_mask:0xf bank_mask:0xf bound_ctrl:1
	v_fmac_f32_dpp v236, v92, v160 row_ror:1 row_mask:0xf bank_mask:0xf
	v_fmac_f32_dpp v237, v93, v161 row_ror:1 row_mask:0xf bank_mask:0xf
	v_fmac_f32_dpp v238, v94, v162 row_ror:1 row_mask:0xf bank_mask:0xf
	v_fmac_f32_dpp v239, v95, v163 row_ror:1 row_mask:0xf bank_mask:0xf
	v_fmac_f32_dpp v236, v92, v168 row_ror:2 row_mask:0xf bank_mask:0xf
	v_fmac_f32_dpp v237, v93, v169 row_ror:2 row_mask:0xf bank_mask:0xf
	v_fmac_f32_dpp v238, v94, v170 row_ror:2 row_mask:0xf bank_mask:0xf
	v_fmac_f32_dpp v239, v95, v171 row_ror:2 row_mask:0xf bank_mask:0xf
	v_fma_f32 v240, v68, v148, v156
	v_fma_f32 v241, v69, v149, v157
	v_fma_f32 v242, v70, v150, v158
	v_fma_f32 v243, v71, v151, v159
	v_fmac_f32_dpp v240, v68, v140 row_shr:1 row_mask:0xf bank_mask:0xf bound_ctrl:1
	v_fmac_f32_dpp v241, v69, v141 row_shr:1 row_mask:0xf bank_mask:0xf bound_ctrl:1
	v_fmac_f32_dpp v242, v70, v142 row_shr:1 row_mask:0xf bank_mask:0xf bound_ctrl:1
	v_fmac_f32_dpp v243, v71, v143 row_shr:1 row_mask:0xf bank_mask:0xf bound_ctrl:1
	v_fmac_f32_dpp v240, v68, v132 row_shr:2 row_mask:0xf bank_mask:0xf bound_ctrl:1
	v_fmac_f32_dpp v241, v69, v133 row_shr:2 row_mask:0xf bank_mask:0xf bound_ctrl:1
	v_fmac_f32_dpp v242, v70, v134 row_shr:2 row_mask:0xf bank_mask:0xf bound_ctrl:1
	v_fmac_f32_dpp v243, v71, v135 row_shr:2 row_mask:0xf bank_mask:0xf bound_ctrl:1
	v_fmac_f32_dpp v240, v84, v164 row_ror:1 row_mask:0xf bank_mask:0xf
	v_fmac_f32_dpp v241, v85, v165 row_ror:1 row_mask:0xf bank_mask:0xf
	v_fmac_f32_dpp v242, v86, v166 row_ror:1 row_mask:0xf bank_mask:0xf
	v_fmac_f32_dpp v243, v87, v167 row_ror:1 row_mask:0xf bank_mask:0xf
	v_fmac_f32_dpp v240, v84, v204 row_ror:2 row_mask:0xf bank_mask:0xf
	v_fmac_f32_dpp v241, v85, v205 row_ror:2 row_mask:0xf bank_mask:0xf
	v_fmac_f32_dpp v242, v86, v206 row_ror:2 row_mask:0xf bank_mask:0xf
	v_fmac_f32_dpp v243, v87, v207 row_ror:2 row_mask:0xf bank_mask:0xf
	v_mov_b32_e32 v228, 0xbdd2d3e8
	v_mul_f32_e32 v244, v236, v236
	v_mul_f32_e32 v245, v237, v237
	v_mul_f32_e32 v246, v238, v238
	v_mul_f32_e32 v247, v239, v239
	v_fmaak_f32 v244, v244, v228, 0xc0135761
	v_fmaak_f32 v245, v245, v228, 0xc0135761
	v_fmaak_f32 v246, v246, v228, 0xc0135761
	v_fmaak_f32 v247, v247, v228, 0xc0135761
	v_mul_f32_e32 v244, v236, v244
	v_mul_f32_e32 v245, v237, v245
	v_mul_f32_e32 v246, v238, v246
	v_mul_f32_e32 v247, v239, v247
	v_exp_f32_e32 v244, v244
	v_exp_f32_e32 v245, v245
	v_exp_f32_e32 v246, v246
	v_exp_f32_e32 v247, v247
	v_add_f32_e32 v244, 1.0, v244
	v_add_f32_e32 v245, 1.0, v245
	v_add_f32_e32 v246, 1.0, v246
	v_add_f32_e32 v247, 1.0, v247
	v_rcp_f32_e32 v244, v244
	v_rcp_f32_e32 v245, v245
	v_rcp_f32_e32 v246, v246
	v_rcp_f32_e32 v247, v247
	v_mul_f32_e32 v244, v236, v244
	v_mul_f32_e32 v245, v237, v245
	v_mul_f32_e32 v246, v238, v246
	v_mul_f32_e32 v247, v239, v247
	v_mul_f32_e32 v248, v240, v244
	v_mul_f32_e32 v249, v241, v245
	v_mul_f32_e32 v250, v242, v246
	v_mul_f32_e32 v251, v243, v247
	v_cvt_pk_bf16_f32 v214, v248, v249
	v_cvt_pk_bf16_f32 v215, v250, v251
.Lffn1e_join0_3:
	s_add_i32 s6, s0, 2143
	s_mul_hi_u32 s7, s6, s59
	s_lshr_b32 s7, s7, 7
	s_mulk_i32 s7, 0x810
	s_sub_i32 s6, s6, s7
	s_cmp_lt_u32 s6, 17
	s_cbranch_scc1 .Lffn1e_slow0_4
	s_cmp_lt_u32 s6, 33
	s_cbranch_scc1 .Lffn1e_old0_4
	v_fma_f32 v236, v60, v144, v152
	v_fma_f32 v237, v61, v145, v153
	v_fma_f32 v238, v62, v146, v154
	v_fma_f32 v239, v63, v147, v155
	v_fmac_f32_dpp v236, v60, v136 row_shr:1 row_mask:0xf bank_mask:0xf bound_ctrl:1
	v_fmac_f32_dpp v237, v61, v137 row_shr:1 row_mask:0xf bank_mask:0xf bound_ctrl:1
	v_fmac_f32_dpp v238, v62, v138 row_shr:1 row_mask:0xf bank_mask:0xf bound_ctrl:1
	v_fmac_f32_dpp v239, v63, v139 row_shr:1 row_mask:0xf bank_mask:0xf bound_ctrl:1
	v_fmac_f32_dpp v236, v60, v128 row_shr:2 row_mask:0xf bank_mask:0xf bound_ctrl:1
	v_fmac_f32_dpp v237, v61, v129 row_shr:2 row_mask:0xf bank_mask:0xf bound_ctrl:1
	v_fmac_f32_dpp v238, v62, v130 row_shr:2 row_mask:0xf bank_mask:0xf bound_ctrl:1
	v_fmac_f32_dpp v239, v63, v131 row_shr:2 row_mask:0xf bank_mask:0xf bound_ctrl:1
	v_fmac_f32_dpp v236, v76, v160 row_ror:1 row_mask:0xf bank_mask:0xf
	v_fmac_f32_dpp v237, v77, v161 row_ror:1 row_mask:0xf bank_mask:0xf
	v_fmac_f32_dpp v238, v78, v162 row_ror:1 row_mask:0xf bank_mask:0xf
	v_fmac_f32_dpp v239, v79, v163 row_ror:1 row_mask:0xf bank_mask:0xf
	v_fmac_f32_dpp v236, v76, v168 row_ror:2 row_mask:0xf bank_mask:0xf
	v_fmac_f32_dpp v237, v77, v169 row_ror:2 row_mask:0xf bank_mask:0xf
	v_fmac_f32_dpp v238, v78, v170 row_ror:2 row_mask:0xf bank_mask:0xf
	v_fmac_f32_dpp v239, v79, v171 row_ror:2 row_mask:0xf bank_mask:0xf
	v_fma_f32 v240, v52, v148, v156
	v_fma_f32 v241, v53, v149, v157
	v_fma_f32 v242, v54, v150, v158
	v_fma_f32 v243, v55, v151, v159
	v_fmac_f32_dpp v240, v52, v140 row_shr:1 row_mask:0xf bank_mask:0xf bound_ctrl:1
	v_fmac_f32_dpp v241, v53, v141 row_shr:1 row_mask:0xf bank_mask:0xf bound_ctrl:1
	v_fmac_f32_dpp v242, v54, v142 row_shr:1 row_mask:0xf bank_mask:0xf bound_ctrl:1
	v_fmac_f32_dpp v243, v55, v143 row_shr:1 row_mask:0xf bank_mask:0xf bound_ctrl:1
	v_fmac_f32_dpp v240, v52, v132 row_shr:2 row_mask:0xf bank_mask:0xf bound_ctrl:1
	v_fmac_f32_dpp v241, v53, v133 row_shr:2 row_mask:0xf bank_mask:0xf bound_ctrl:1
	v_fmac_f32_dpp v242, v54, v134 row_shr:2 row_mask:0xf bank_mask:0xf bound_ctrl:1
	v_fmac_f32_dpp v243, v55, v135 row_shr:2 row_mask:0xf bank_mask:0xf bound_ctrl:1
	v_fmac_f32_dpp v240, v68, v164 row_ror:1 row_mask:0xf bank_mask:0xf
	v_fmac_f32_dpp v241, v69, v165 row_ror:1 row_mask:0xf bank_mask:0xf
	v_fmac_f32_dpp v242, v70, v166 row_ror:1 row_mask:0xf bank_mask:0xf
	v_fmac_f32_dpp v243, v71, v167 row_ror:1 row_mask:0xf bank_mask:0xf
	v_fmac_f32_dpp v240, v68, v204 row_ror:2 row_mask:0xf bank_mask:0xf
	v_fmac_f32_dpp v241, v69, v205 row_ror:2 row_mask:0xf bank_mask:0xf
	v_fmac_f32_dpp v242, v70, v206 row_ror:2 row_mask:0xf bank_mask:0xf
	v_fmac_f32_dpp v243, v71, v207 row_ror:2 row_mask:0xf bank_mask:0xf
	v_mov_b32_e32 v228, 0xbdd2d3e8
	v_mul_f32_e32 v244, v236, v236
	v_mul_f32_e32 v245, v237, v237
	v_mul_f32_e32 v246, v238, v238
	v_mul_f32_e32 v247, v239, v239
	v_fmaak_f32 v244, v244, v228, 0xc0135761
	v_fmaak_f32 v245, v245, v228, 0xc0135761
	v_fmaak_f32 v246, v246, v228, 0xc0135761
	v_fmaak_f32 v247, v247, v228, 0xc0135761
	v_mul_f32_e32 v244, v236, v244
	v_mul_f32_e32 v245, v237, v245
	v_mul_f32_e32 v246, v238, v246
	v_mul_f32_e32 v247, v239, v247
	v_exp_f32_e32 v244, v244
	v_exp_f32_e32 v245, v245
	v_exp_f32_e32 v246, v246
	v_exp_f32_e32 v247, v247
	v_add_f32_e32 v244, 1.0, v244
	v_add_f32_e32 v245, 1.0, v245
	v_add_f32_e32 v246, 1.0, v246
	v_add_f32_e32 v247, 1.0, v247
	v_rcp_f32_e32 v244, v244
	v_rcp_f32_e32 v245, v245
	v_rcp_f32_e32 v246, v246
	v_rcp_f32_e32 v247, v247
	v_mul_f32_e32 v244, v236, v244
	v_mul_f32_e32 v245, v237, v245
	v_mul_f32_e32 v246, v238, v246
	v_mul_f32_e32 v247, v239, v247
	v_mul_f32_e32 v248, v240, v244
	v_mul_f32_e32 v249, v241, v245
	v_mul_f32_e32 v250, v242, v246
	v_mul_f32_e32 v251, v243, v247
	v_cvt_pk_bf16_f32 v216, v248, v249
	v_cvt_pk_bf16_f32 v217, v250, v251
.Lffn1e_join0_4:
	s_add_i32 s6, s0, 2159
	s_mul_hi_u32 s7, s6, s59
	s_lshr_b32 s7, s7, 7
	s_mulk_i32 s7, 0x810
	s_sub_i32 s6, s6, s7
	s_cmp_lt_u32 s6, 17
	s_cbranch_scc1 .Lffn1e_slow0_5
	s_cmp_lt_u32 s6, 33
	s_cbranch_scc1 .Lffn1e_old0_5
	v_fma_f32 v236, v44, v144, v152
	v_fma_f32 v237, v45, v145, v153
	v_fma_f32 v238, v46, v146, v154
	v_fma_f32 v239, v47, v147, v155
	v_fmac_f32_dpp v236, v44, v136 row_shr:1 row_mask:0xf bank_mask:0xf bound_ctrl:1
	v_fmac_f32_dpp v237, v45, v137 row_shr:1 row_mask:0xf bank_mask:0xf bound_ctrl:1
	v_fmac_f32_dpp v238, v46, v138 row_shr:1 row_mask:0xf bank_mask:0xf bound_ctrl:1
	v_fmac_f32_dpp v239, v47, v139 row_shr:1 row_mask:0xf bank_mask:0xf bound_ctrl:1
	v_fmac_f32_dpp v236, v44, v128 row_shr:2 row_mask:0xf bank_mask:0xf bound_ctrl:1
	v_fmac_f32_dpp v237, v45, v129 row_shr:2 row_mask:0xf bank_mask:0xf bound_ctrl:1
	v_fmac_f32_dpp v238, v46, v130 row_shr:2 row_mask:0xf bank_mask:0xf bound_ctrl:1
	v_fmac_f32_dpp v239, v47, v131 row_shr:2 row_mask:0xf bank_mask:0xf bound_ctrl:1
	v_fmac_f32_dpp v236, v60, v160 row_ror:1 row_mask:0xf bank_mask:0xf
	v_fmac_f32_dpp v237, v61, v161 row_ror:1 row_mask:0xf bank_mask:0xf
	v_fmac_f32_dpp v238, v62, v162 row_ror:1 row_mask:0xf bank_mask:0xf
	v_fmac_f32_dpp v239, v63, v163 row_ror:1 row_mask:0xf bank_mask:0xf
	v_fmac_f32_dpp v236, v60, v168 row_ror:2 row_mask:0xf bank_mask:0xf
	v_fmac_f32_dpp v237, v61, v169 row_ror:2 row_mask:0xf bank_mask:0xf
	v_fmac_f32_dpp v238, v62, v170 row_ror:2 row_mask:0xf bank_mask:0xf
	v_fmac_f32_dpp v239, v63, v171 row_ror:2 row_mask:0xf bank_mask:0xf
	v_fma_f32 v240, v36, v148, v156
	v_fma_f32 v241, v37, v149, v157
	v_fma_f32 v242, v38, v150, v158
	v_fma_f32 v243, v39, v151, v159
	v_fmac_f32_dpp v240, v36, v140 row_shr:1 row_mask:0xf bank_mask:0xf bound_ctrl:1
	v_fmac_f32_dpp v241, v37, v141 row_shr:1 row_mask:0xf bank_mask:0xf bound_ctrl:1
	v_fmac_f32_dpp v242, v38, v142 row_shr:1 row_mask:0xf bank_mask:0xf bound_ctrl:1
	v_fmac_f32_dpp v243, v39, v143 row_shr:1 row_mask:0xf bank_mask:0xf bound_ctrl:1
	v_fmac_f32_dpp v240, v36, v132 row_shr:2 row_mask:0xf bank_mask:0xf bound_ctrl:1
	v_fmac_f32_dpp v241, v37, v133 row_shr:2 row_mask:0xf bank_mask:0xf bound_ctrl:1
	v_fmac_f32_dpp v242, v38, v134 row_shr:2 row_mask:0xf bank_mask:0xf bound_ctrl:1
	v_fmac_f32_dpp v243, v39, v135 row_shr:2 row_mask:0xf bank_mask:0xf bound_ctrl:1
	v_fmac_f32_dpp v240, v52, v164 row_ror:1 row_mask:0xf bank_mask:0xf
	v_fmac_f32_dpp v241, v53, v165 row_ror:1 row_mask:0xf bank_mask:0xf
	v_fmac_f32_dpp v242, v54, v166 row_ror:1 row_mask:0xf bank_mask:0xf
	v_fmac_f32_dpp v243, v55, v167 row_ror:1 row_mask:0xf bank_mask:0xf
	v_fmac_f32_dpp v240, v52, v204 row_ror:2 row_mask:0xf bank_mask:0xf
	v_fmac_f32_dpp v241, v53, v205 row_ror:2 row_mask:0xf bank_mask:0xf
	v_fmac_f32_dpp v242, v54, v206 row_ror:2 row_mask:0xf bank_mask:0xf
	v_fmac_f32_dpp v243, v55, v207 row_ror:2 row_mask:0xf bank_mask:0xf
	v_mov_b32_e32 v228, 0xbdd2d3e8
	v_mul_f32_e32 v244, v236, v236
	v_mul_f32_e32 v245, v237, v237
	v_mul_f32_e32 v246, v238, v238
	v_mul_f32_e32 v247, v239, v239
	v_fmaak_f32 v244, v244, v228, 0xc0135761
	v_fmaak_f32 v245, v245, v228, 0xc0135761
	v_fmaak_f32 v246, v246, v228, 0xc0135761
	v_fmaak_f32 v247, v247, v228, 0xc0135761
	v_mul_f32_e32 v244, v236, v244
	v_mul_f32_e32 v245, v237, v245
	v_mul_f32_e32 v246, v238, v246
	v_mul_f32_e32 v247, v239, v247
	v_exp_f32_e32 v244, v244
	v_exp_f32_e32 v245, v245
	v_exp_f32_e32 v246, v246
	v_exp_f32_e32 v247, v247
	v_add_f32_e32 v244, 1.0, v244
	v_add_f32_e32 v245, 1.0, v245
	v_add_f32_e32 v246, 1.0, v246
	v_add_f32_e32 v247, 1.0, v247
	v_rcp_f32_e32 v244, v244
	v_rcp_f32_e32 v245, v245
	v_rcp_f32_e32 v246, v246
	v_rcp_f32_e32 v247, v247
	v_mul_f32_e32 v244, v236, v244
	v_mul_f32_e32 v245, v237, v245
	v_mul_f32_e32 v246, v238, v246
	v_mul_f32_e32 v247, v239, v247
	v_mul_f32_e32 v248, v240, v244
	v_mul_f32_e32 v249, v241, v245
	v_mul_f32_e32 v250, v242, v246
	v_mul_f32_e32 v251, v243, v247
	v_cvt_pk_bf16_f32 v220, v248, v249
	v_cvt_pk_bf16_f32 v221, v250, v251
.Lffn1e_join0_5:
	s_add_i32 s6, s0, 2175
	s_mul_hi_u32 s7, s6, s59
	s_lshr_b32 s7, s7, 7
	s_mulk_i32 s7, 0x810
	s_sub_i32 s6, s6, s7
	s_cmp_lt_u32 s6, 17
	s_cbranch_scc1 .Lffn1e_slow0_6
	s_cmp_lt_u32 s6, 33
	s_cbranch_scc1 .Lffn1e_old0_6
	v_fma_f32 v236, v28, v144, v152
	v_fma_f32 v237, v29, v145, v153
	v_fma_f32 v238, v30, v146, v154
	v_fma_f32 v239, v31, v147, v155
	v_fmac_f32_dpp v236, v28, v136 row_shr:1 row_mask:0xf bank_mask:0xf bound_ctrl:1
	v_fmac_f32_dpp v237, v29, v137 row_shr:1 row_mask:0xf bank_mask:0xf bound_ctrl:1
	v_fmac_f32_dpp v238, v30, v138 row_shr:1 row_mask:0xf bank_mask:0xf bound_ctrl:1
	v_fmac_f32_dpp v239, v31, v139 row_shr:1 row_mask:0xf bank_mask:0xf bound_ctrl:1
	v_fmac_f32_dpp v236, v28, v128 row_shr:2 row_mask:0xf bank_mask:0xf bound_ctrl:1
	v_fmac_f32_dpp v237, v29, v129 row_shr:2 row_mask:0xf bank_mask:0xf bound_ctrl:1
	v_fmac_f32_dpp v238, v30, v130 row_shr:2 row_mask:0xf bank_mask:0xf bound_ctrl:1
	v_fmac_f32_dpp v239, v31, v131 row_shr:2 row_mask:0xf bank_mask:0xf bound_ctrl:1
	v_fmac_f32_dpp v236, v44, v160 row_ror:1 row_mask:0xf bank_mask:0xf
	v_fmac_f32_dpp v237, v45, v161 row_ror:1 row_mask:0xf bank_mask:0xf
	v_fmac_f32_dpp v238, v46, v162 row_ror:1 row_mask:0xf bank_mask:0xf
	v_fmac_f32_dpp v239, v47, v163 row_ror:1 row_mask:0xf bank_mask:0xf
	v_fmac_f32_dpp v236, v44, v168 row_ror:2 row_mask:0xf bank_mask:0xf
	v_fmac_f32_dpp v237, v45, v169 row_ror:2 row_mask:0xf bank_mask:0xf
	v_fmac_f32_dpp v238, v46, v170 row_ror:2 row_mask:0xf bank_mask:0xf
	v_fmac_f32_dpp v239, v47, v171 row_ror:2 row_mask:0xf bank_mask:0xf
	v_fma_f32 v240, v20, v148, v156
	v_fma_f32 v241, v21, v149, v157
	v_fma_f32 v242, v22, v150, v158
	v_fma_f32 v243, v23, v151, v159
	v_fmac_f32_dpp v240, v20, v140 row_shr:1 row_mask:0xf bank_mask:0xf bound_ctrl:1
	v_fmac_f32_dpp v241, v21, v141 row_shr:1 row_mask:0xf bank_mask:0xf bound_ctrl:1
	v_fmac_f32_dpp v242, v22, v142 row_shr:1 row_mask:0xf bank_mask:0xf bound_ctrl:1
	v_fmac_f32_dpp v243, v23, v143 row_shr:1 row_mask:0xf bank_mask:0xf bound_ctrl:1
	v_fmac_f32_dpp v240, v20, v132 row_shr:2 row_mask:0xf bank_mask:0xf bound_ctrl:1
	v_fmac_f32_dpp v241, v21, v133 row_shr:2 row_mask:0xf bank_mask:0xf bound_ctrl:1
	v_fmac_f32_dpp v242, v22, v134 row_shr:2 row_mask:0xf bank_mask:0xf bound_ctrl:1
	v_fmac_f32_dpp v243, v23, v135 row_shr:2 row_mask:0xf bank_mask:0xf bound_ctrl:1
	v_fmac_f32_dpp v240, v36, v164 row_ror:1 row_mask:0xf bank_mask:0xf
	v_fmac_f32_dpp v241, v37, v165 row_ror:1 row_mask:0xf bank_mask:0xf
	v_fmac_f32_dpp v242, v38, v166 row_ror:1 row_mask:0xf bank_mask:0xf
	v_fmac_f32_dpp v243, v39, v167 row_ror:1 row_mask:0xf bank_mask:0xf
	v_fmac_f32_dpp v240, v36, v204 row_ror:2 row_mask:0xf bank_mask:0xf
	v_fmac_f32_dpp v241, v37, v205 row_ror:2 row_mask:0xf bank_mask:0xf
	v_fmac_f32_dpp v242, v38, v206 row_ror:2 row_mask:0xf bank_mask:0xf
	v_fmac_f32_dpp v243, v39, v207 row_ror:2 row_mask:0xf bank_mask:0xf
	v_mov_b32_e32 v228, 0xbdd2d3e8
	v_mul_f32_e32 v244, v236, v236
	v_mul_f32_e32 v245, v237, v237
	v_mul_f32_e32 v246, v238, v238
	v_mul_f32_e32 v247, v239, v239
	v_fmaak_f32 v244, v244, v228, 0xc0135761
	v_fmaak_f32 v245, v245, v228, 0xc0135761
	v_fmaak_f32 v246, v246, v228, 0xc0135761
	v_fmaak_f32 v247, v247, v228, 0xc0135761
	v_mul_f32_e32 v244, v236, v244
	v_mul_f32_e32 v245, v237, v245
	v_mul_f32_e32 v246, v238, v246
	v_mul_f32_e32 v247, v239, v247
	v_exp_f32_e32 v244, v244
	v_exp_f32_e32 v245, v245
	v_exp_f32_e32 v246, v246
	v_exp_f32_e32 v247, v247
	v_add_f32_e32 v244, 1.0, v244
	v_add_f32_e32 v245, 1.0, v245
	v_add_f32_e32 v246, 1.0, v246
	v_add_f32_e32 v247, 1.0, v247
	v_rcp_f32_e32 v244, v244
	v_rcp_f32_e32 v245, v245
	v_rcp_f32_e32 v246, v246
	v_rcp_f32_e32 v247, v247
	v_mul_f32_e32 v244, v236, v244
	v_mul_f32_e32 v245, v237, v245
	v_mul_f32_e32 v246, v238, v246
	v_mul_f32_e32 v247, v239, v247
	v_mul_f32_e32 v248, v240, v244
	v_mul_f32_e32 v249, v241, v245
	v_mul_f32_e32 v250, v242, v246
	v_mul_f32_e32 v251, v243, v247
	v_cvt_pk_bf16_f32 v222, v248, v249
	v_cvt_pk_bf16_f32 v223, v250, v251
.Lffn1e_join0_6:
	s_add_i32 s6, s0, 2191
	s_mul_hi_u32 s7, s6, s59
	s_lshr_b32 s7, s7, 7
	s_mulk_i32 s7, 0x810
	s_sub_i32 s6, s6, s7
	s_cmp_lt_u32 s6, 17
	s_cbranch_scc1 .Lffn1e_slow0_7
	s_cmp_lt_u32 s6, 33
	s_cbranch_scc1 .Lffn1e_old0_7
	v_fma_f32 v236, v4, v144, v152
	v_fma_f32 v237, v5, v145, v153
	v_fma_f32 v238, v6, v146, v154
	v_fma_f32 v239, v7, v147, v155
	v_fmac_f32_dpp v236, v4, v136 row_shr:1 row_mask:0xf bank_mask:0xf bound_ctrl:1
	v_fmac_f32_dpp v237, v5, v137 row_shr:1 row_mask:0xf bank_mask:0xf bound_ctrl:1
	v_fmac_f32_dpp v238, v6, v138 row_shr:1 row_mask:0xf bank_mask:0xf bound_ctrl:1
	v_fmac_f32_dpp v239, v7, v139 row_shr:1 row_mask:0xf bank_mask:0xf bound_ctrl:1
	v_fmac_f32_dpp v236, v4, v128 row_shr:2 row_mask:0xf bank_mask:0xf bound_ctrl:1
	v_fmac_f32_dpp v237, v5, v129 row_shr:2 row_mask:0xf bank_mask:0xf bound_ctrl:1
	v_fmac_f32_dpp v238, v6, v130 row_shr:2 row_mask:0xf bank_mask:0xf bound_ctrl:1
	v_fmac_f32_dpp v239, v7, v131 row_shr:2 row_mask:0xf bank_mask:0xf bound_ctrl:1
	v_fmac_f32_dpp v236, v28, v160 row_ror:1 row_mask:0xf bank_mask:0xf
	v_fmac_f32_dpp v237, v29, v161 row_ror:1 row_mask:0xf bank_mask:0xf
	v_fmac_f32_dpp v238, v30, v162 row_ror:1 row_mask:0xf bank_mask:0xf
	v_fmac_f32_dpp v239, v31, v163 row_ror:1 row_mask:0xf bank_mask:0xf
	v_fmac_f32_dpp v236, v28, v168 row_ror:2 row_mask:0xf bank_mask:0xf
	v_fmac_f32_dpp v237, v29, v169 row_ror:2 row_mask:0xf bank_mask:0xf
	v_fmac_f32_dpp v238, v30, v170 row_ror:2 row_mask:0xf bank_mask:0xf
	v_fmac_f32_dpp v239, v31, v171 row_ror:2 row_mask:0xf bank_mask:0xf
	v_fma_f32 v240, v8, v148, v156
	v_fma_f32 v241, v9, v149, v157
	v_fma_f32 v242, v10, v150, v158
	v_fma_f32 v243, v11, v151, v159
	v_fmac_f32_dpp v240, v8, v140 row_shr:1 row_mask:0xf bank_mask:0xf bound_ctrl:1
	v_fmac_f32_dpp v241, v9, v141 row_shr:1 row_mask:0xf bank_mask:0xf bound_ctrl:1
	v_fmac_f32_dpp v242, v10, v142 row_shr:1 row_mask:0xf bank_mask:0xf bound_ctrl:1
	v_fmac_f32_dpp v243, v11, v143 row_shr:1 row_mask:0xf bank_mask:0xf bound_ctrl:1
	v_fmac_f32_dpp v240, v8, v132 row_shr:2 row_mask:0xf bank_mask:0xf bound_ctrl:1
	v_fmac_f32_dpp v241, v9, v133 row_shr:2 row_mask:0xf bank_mask:0xf bound_ctrl:1
	v_fmac_f32_dpp v242, v10, v134 row_shr:2 row_mask:0xf bank_mask:0xf bound_ctrl:1
	v_fmac_f32_dpp v243, v11, v135 row_shr:2 row_mask:0xf bank_mask:0xf bound_ctrl:1
	v_fmac_f32_dpp v240, v20, v164 row_ror:1 row_mask:0xf bank_mask:0xf
	v_fmac_f32_dpp v241, v21, v165 row_ror:1 row_mask:0xf bank_mask:0xf
	v_fmac_f32_dpp v242, v22, v166 row_ror:1 row_mask:0xf bank_mask:0xf
	v_fmac_f32_dpp v243, v23, v167 row_ror:1 row_mask:0xf bank_mask:0xf
	v_fmac_f32_dpp v240, v20, v204 row_ror:2 row_mask:0xf bank_mask:0xf
	v_fmac_f32_dpp v241, v21, v205 row_ror:2 row_mask:0xf bank_mask:0xf
	v_fmac_f32_dpp v242, v22, v206 row_ror:2 row_mask:0xf bank_mask:0xf
	v_fmac_f32_dpp v243, v23, v207 row_ror:2 row_mask:0xf bank_mask:0xf
	v_mov_b32_e32 v228, 0xbdd2d3e8
	v_mul_f32_e32 v244, v236, v236
	v_mul_f32_e32 v245, v237, v237
	v_mul_f32_e32 v246, v238, v238
	v_mul_f32_e32 v247, v239, v239
	v_fmaak_f32 v244, v244, v228, 0xc0135761
	v_fmaak_f32 v245, v245, v228, 0xc0135761
	v_fmaak_f32 v246, v246, v228, 0xc0135761
	v_fmaak_f32 v247, v247, v228, 0xc0135761
	v_mul_f32_e32 v244, v236, v244
	v_mul_f32_e32 v245, v237, v245
	v_mul_f32_e32 v246, v238, v246
	v_mul_f32_e32 v247, v239, v247
	v_exp_f32_e32 v244, v244
	v_exp_f32_e32 v245, v245
	v_exp_f32_e32 v246, v246
	v_exp_f32_e32 v247, v247
	v_add_f32_e32 v244, 1.0, v244
	v_add_f32_e32 v245, 1.0, v245
	v_add_f32_e32 v246, 1.0, v246
	v_add_f32_e32 v247, 1.0, v247
	v_rcp_f32_e32 v244, v244
	v_rcp_f32_e32 v245, v245
	v_rcp_f32_e32 v246, v246
	v_rcp_f32_e32 v247, v247
	v_mul_f32_e32 v244, v236, v244
	v_mul_f32_e32 v245, v237, v245
	v_mul_f32_e32 v246, v238, v246
	v_mul_f32_e32 v247, v239, v247
	v_mul_f32_e32 v248, v240, v244
	v_mul_f32_e32 v249, v241, v245
	v_mul_f32_e32 v250, v242, v246
	v_mul_f32_e32 v251, v243, v247
	v_cvt_pk_bf16_f32 v224, v248, v249
	v_cvt_pk_bf16_f32 v225, v250, v251
.Lffn1e_join0_7:
	v_add_u32_e32 v203, 0x20000, v172
	ds_read_b128 v[128:131], v203 offset:16
	ds_read_b128 v[132:135], v203 offset:528
	ds_read_b128 v[136:139], v203 offset:1040
	ds_read_b128 v[140:143], v203 offset:1552
	ds_read_b128 v[144:147], v203 offset:2064
	ds_read_b128 v[148:151], v203 offset:2576
	ds_read_b128 v[152:155], v203 offset:3088
	ds_read_b128 v[156:159], v203 offset:3600
	s_waitcnt lgkmcnt(0)
	s_mov_b32 s6, 0x10001
	s_mov_b32 s7, 0x10001
	s_mov_b32 s10, 0x30003
	s_mov_b32 s11, 0x30003
	s_nop 0
	v_cndmask_b32_e64 v160, 0, v136, s[6:7]
	v_cndmask_b32_e64 v161, 0, v137, s[6:7]
	v_cndmask_b32_e64 v162, 0, v138, s[6:7]
	v_cndmask_b32_e64 v163, 0, v139, s[6:7]
	v_cndmask_b32_e64 v164, 0, v140, s[6:7]
	v_cndmask_b32_e64 v165, 0, v141, s[6:7]
	v_cndmask_b32_e64 v166, 0, v142, s[6:7]
	v_cndmask_b32_e64 v167, 0, v143, s[6:7]
	v_cndmask_b32_e64 v168, 0, v128, s[10:11]
	v_cndmask_b32_e64 v169, 0, v129, s[10:11]
	v_cndmask_b32_e64 v170, 0, v130, s[10:11]
	v_cndmask_b32_e64 v171, 0, v131, s[10:11]
	v_cndmask_b32_e64 v204, 0, v132, s[10:11]
	v_cndmask_b32_e64 v205, 0, v133, s[10:11]
	v_cndmask_b32_e64 v206, 0, v134, s[10:11]
	v_cndmask_b32_e64 v207, 0, v135, s[10:11]
	s_add_i32 s6, s0, 2079
	s_mul_hi_u32 s7, s6, s59
	s_lshr_b32 s7, s7, 7
	s_mulk_i32 s7, 0x810
	s_sub_i32 s6, s6, s7
	s_cmp_lt_u32 s6, 17
	s_cbranch_scc1 .Lffn1e_slow1_0
	v_fma_f32 v236, v120, v144, v152
	v_fma_f32 v237, v121, v145, v153
	v_fma_f32 v238, v122, v146, v154
	v_fma_f32 v239, v123, v147, v155
	v_fmac_f32_dpp v236, v120, v136 row_shr:1 row_mask:0xf bank_mask:0xf bound_ctrl:1
	v_fmac_f32_dpp v237, v121, v137 row_shr:1 row_mask:0xf bank_mask:0xf bound_ctrl:1
	v_fmac_f32_dpp v238, v122, v138 row_shr:1 row_mask:0xf bank_mask:0xf bound_ctrl:1
	v_fmac_f32_dpp v239, v123, v139 row_shr:1 row_mask:0xf bank_mask:0xf bound_ctrl:1
	v_fmac_f32_dpp v236, v120, v128 row_shr:2 row_mask:0xf bank_mask:0xf bound_ctrl:1
	v_fmac_f32_dpp v237, v121, v129 row_shr:2 row_mask:0xf bank_mask:0xf bound_ctrl:1
	v_fmac_f32_dpp v238, v122, v130 row_shr:2 row_mask:0xf bank_mask:0xf bound_ctrl:1
	v_fmac_f32_dpp v239, v123, v131 row_shr:2 row_mask:0xf bank_mask:0xf bound_ctrl:1
	v_fma_f32 v240, v112, v148, v156
	v_fma_f32 v241, v113, v149, v157
	v_fma_f32 v242, v114, v150, v158
	v_fma_f32 v243, v115, v151, v159
	v_fmac_f32_dpp v240, v112, v140 row_shr:1 row_mask:0xf bank_mask:0xf bound_ctrl:1
	v_fmac_f32_dpp v241, v113, v141 row_shr:1 row_mask:0xf bank_mask:0xf bound_ctrl:1
	v_fmac_f32_dpp v242, v114, v142 row_shr:1 row_mask:0xf bank_mask:0xf bound_ctrl:1
	v_fmac_f32_dpp v243, v115, v143 row_shr:1 row_mask:0xf bank_mask:0xf bound_ctrl:1
	v_fmac_f32_dpp v240, v112, v132 row_shr:2 row_mask:0xf bank_mask:0xf bound_ctrl:1
	v_fmac_f32_dpp v241, v113, v133 row_shr:2 row_mask:0xf bank_mask:0xf bound_ctrl:1
	v_fmac_f32_dpp v242, v114, v134 row_shr:2 row_mask:0xf bank_mask:0xf bound_ctrl:1
	v_fmac_f32_dpp v243, v115, v135 row_shr:2 row_mask:0xf bank_mask:0xf bound_ctrl:1
	v_mov_b32_e32 v228, 0xbdd2d3e8
	v_mul_f32_e32 v244, v236, v236
	v_mul_f32_e32 v245, v237, v237
	v_mul_f32_e32 v246, v238, v238
	v_mul_f32_e32 v247, v239, v239
	v_fmaak_f32 v244, v244, v228, 0xc0135761
	v_fmaak_f32 v245, v245, v228, 0xc0135761
	v_fmaak_f32 v246, v246, v228, 0xc0135761
	v_fmaak_f32 v247, v247, v228, 0xc0135761
	v_mul_f32_e32 v244, v236, v244
	v_mul_f32_e32 v245, v237, v245
	v_mul_f32_e32 v246, v238, v246
	v_mul_f32_e32 v247, v239, v247
	v_exp_f32_e32 v244, v244
	v_exp_f32_e32 v245, v245
	v_exp_f32_e32 v246, v246
	v_exp_f32_e32 v247, v247
	v_add_f32_e32 v244, 1.0, v244
	v_add_f32_e32 v245, 1.0, v245
	v_add_f32_e32 v246, 1.0, v246
	v_add_f32_e32 v247, 1.0, v247
	v_rcp_f32_e32 v244, v244
	v_rcp_f32_e32 v245, v245
	v_rcp_f32_e32 v246, v246
	v_rcp_f32_e32 v247, v247
	v_mul_f32_e32 v244, v236, v244
	v_mul_f32_e32 v245, v237, v245
	v_mul_f32_e32 v246, v238, v246
	v_mul_f32_e32 v247, v239, v247
	v_mul_f32_e32 v248, v240, v244
	v_mul_f32_e32 v249, v241, v245
	v_mul_f32_e32 v250, v242, v246
	v_mul_f32_e32 v251, v243, v247
	v_mov_b32_e32 v180, v208
	v_mov_b32_e32 v181, v209
	v_cvt_pk_bf16_f32 v182, v248, v249
	v_cvt_pk_bf16_f32 v183, v250, v251
.Lffn1e_join1_0:
	v_mad_i64_i32 v[226:227], vcc, v218, s79, v[190:191]
	v_cmp_lt_u32_e64 s[8:9], 1, v219
	v_cmp_gt_i32_e32 vcc, s58, v218
	s_nop 1
	s_and_b64 vcc, vcc, s[8:9]
	s_and_saveexec_b64 s[10:11], vcc
	global_store_dwordx4 v[226:227], v[180:183], off sc1
	s_mov_b64 exec, s[10:11]
	s_add_i32 s6, s0, 2095
	s_mul_hi_u32 s7, s6, s59
	s_lshr_b32 s7, s7, 7
	s_mulk_i32 s7, 0x810
	s_sub_i32 s6, s6, s7
	s_cmp_lt_u32 s6, 17
	s_cbranch_scc1 .Lffn1e_slow1_1
	s_cmp_lt_u32 s6, 33
	s_cbranch_scc1 .Lffn1e_old1_1
	v_fma_f32 v236, v104, v144, v152
	v_fma_f32 v237, v105, v145, v153
	v_fma_f32 v238, v106, v146, v154
	v_fma_f32 v239, v107, v147, v155
	v_fmac_f32_dpp v236, v104, v136 row_shr:1 row_mask:0xf bank_mask:0xf bound_ctrl:1
	v_fmac_f32_dpp v237, v105, v137 row_shr:1 row_mask:0xf bank_mask:0xf bound_ctrl:1
	v_fmac_f32_dpp v238, v106, v138 row_shr:1 row_mask:0xf bank_mask:0xf bound_ctrl:1
	v_fmac_f32_dpp v239, v107, v139 row_shr:1 row_mask:0xf bank_mask:0xf bound_ctrl:1
	v_fmac_f32_dpp v236, v104, v128 row_shr:2 row_mask:0xf bank_mask:0xf bound_ctrl:1
	v_fmac_f32_dpp v237, v105, v129 row_shr:2 row_mask:0xf bank_mask:0xf bound_ctrl:1
	v_fmac_f32_dpp v238, v106, v130 row_shr:2 row_mask:0xf bank_mask:0xf bound_ctrl:1
	v_fmac_f32_dpp v239, v107, v131 row_shr:2 row_mask:0xf bank_mask:0xf bound_ctrl:1
	v_fmac_f32_dpp v236, v120, v160 row_ror:1 row_mask:0xf bank_mask:0xf
	v_fmac_f32_dpp v237, v121, v161 row_ror:1 row_mask:0xf bank_mask:0xf
	v_fmac_f32_dpp v238, v122, v162 row_ror:1 row_mask:0xf bank_mask:0xf
	v_fmac_f32_dpp v239, v123, v163 row_ror:1 row_mask:0xf bank_mask:0xf
	v_fmac_f32_dpp v236, v120, v168 row_ror:2 row_mask:0xf bank_mask:0xf
	v_fmac_f32_dpp v237, v121, v169 row_ror:2 row_mask:0xf bank_mask:0xf
	v_fmac_f32_dpp v238, v122, v170 row_ror:2 row_mask:0xf bank_mask:0xf
	v_fmac_f32_dpp v239, v123, v171 row_ror:2 row_mask:0xf bank_mask:0xf
	v_fma_f32 v240, v96, v148, v156
	v_fma_f32 v241, v97, v149, v157
	v_fma_f32 v242, v98, v150, v158
	v_fma_f32 v243, v99, v151, v159
	v_fmac_f32_dpp v240, v96, v140 row_shr:1 row_mask:0xf bank_mask:0xf bound_ctrl:1
	v_fmac_f32_dpp v241, v97, v141 row_shr:1 row_mask:0xf bank_mask:0xf bound_ctrl:1
	v_fmac_f32_dpp v242, v98, v142 row_shr:1 row_mask:0xf bank_mask:0xf bound_ctrl:1
	v_fmac_f32_dpp v243, v99, v143 row_shr:1 row_mask:0xf bank_mask:0xf bound_ctrl:1
	v_fmac_f32_dpp v240, v96, v132 row_shr:2 row_mask:0xf bank_mask:0xf bound_ctrl:1
	v_fmac_f32_dpp v241, v97, v133 row_shr:2 row_mask:0xf bank_mask:0xf bound_ctrl:1
	v_fmac_f32_dpp v242, v98, v134 row_shr:2 row_mask:0xf bank_mask:0xf bound_ctrl:1
	v_fmac_f32_dpp v243, v99, v135 row_shr:2 row_mask:0xf bank_mask:0xf bound_ctrl:1
	v_fmac_f32_dpp v240, v112, v164 row_ror:1 row_mask:0xf bank_mask:0xf
	v_fmac_f32_dpp v241, v113, v165 row_ror:1 row_mask:0xf bank_mask:0xf
	v_fmac_f32_dpp v242, v114, v166 row_ror:1 row_mask:0xf bank_mask:0xf
	v_fmac_f32_dpp v243, v115, v167 row_ror:1 row_mask:0xf bank_mask:0xf
	v_fmac_f32_dpp v240, v112, v204 row_ror:2 row_mask:0xf bank_mask:0xf
	v_fmac_f32_dpp v241, v113, v205 row_ror:2 row_mask:0xf bank_mask:0xf
	v_fmac_f32_dpp v242, v114, v206 row_ror:2 row_mask:0xf bank_mask:0xf
	v_fmac_f32_dpp v243, v115, v207 row_ror:2 row_mask:0xf bank_mask:0xf
	v_mov_b32_e32 v228, 0xbdd2d3e8
	v_mul_f32_e32 v244, v236, v236
	v_mul_f32_e32 v245, v237, v237
	v_mul_f32_e32 v246, v238, v238
	v_mul_f32_e32 v247, v239, v239
	v_fmaak_f32 v244, v244, v228, 0xc0135761
	v_fmaak_f32 v245, v245, v228, 0xc0135761
	v_fmaak_f32 v246, v246, v228, 0xc0135761
	v_fmaak_f32 v247, v247, v228, 0xc0135761
	v_mul_f32_e32 v244, v236, v244
	v_mul_f32_e32 v245, v237, v245
	v_mul_f32_e32 v246, v238, v246
	v_mul_f32_e32 v247, v239, v247
	v_exp_f32_e32 v244, v244
	v_exp_f32_e32 v245, v245
	v_exp_f32_e32 v246, v246
	v_exp_f32_e32 v247, v247
	v_add_f32_e32 v244, 1.0, v244
	v_add_f32_e32 v245, 1.0, v245
	v_add_f32_e32 v246, 1.0, v246
	v_add_f32_e32 v247, 1.0, v247
	v_rcp_f32_e32 v244, v244
	v_rcp_f32_e32 v245, v245
	v_rcp_f32_e32 v246, v246
	v_rcp_f32_e32 v247, v247
	v_mul_f32_e32 v244, v236, v244
	v_mul_f32_e32 v245, v237, v245
	v_mul_f32_e32 v246, v238, v246
	v_mul_f32_e32 v247, v239, v247
	v_mul_f32_e32 v248, v240, v244
	v_mul_f32_e32 v249, v241, v245
	v_mul_f32_e32 v250, v242, v246
	v_mul_f32_e32 v251, v243, v247
	v_mov_b32_e32 v180, v210
	v_mov_b32_e32 v181, v211
	v_cvt_pk_bf16_f32 v182, v248, v249
	v_cvt_pk_bf16_f32 v183, v250, v251
.Lffn1e_join1_1:
	v_add_u32_e32 v252, 16, v218
	v_mad_i64_i32 v[226:227], vcc, v252, s79, v[190:191]
	v_cmp_gt_i32_e32 vcc, s58, v252
	s_nop 1
	s_and_saveexec_b64 s[10:11], vcc
	global_store_dwordx4 v[226:227], v[180:183], off sc1
	s_mov_b64 exec, s[10:11]
	s_add_i32 s6, s0, 2111
	s_mul_hi_u32 s7, s6, s59
	s_lshr_b32 s7, s7, 7
	s_mulk_i32 s7, 0x810
	s_sub_i32 s6, s6, s7
	s_cmp_lt_u32 s6, 17
	s_cbranch_scc1 .Lffn1e_slow1_2
	s_cmp_lt_u32 s6, 33
	s_cbranch_scc1 .Lffn1e_old1_2
	v_fma_f32 v236, v88, v144, v152
	v_fma_f32 v237, v89, v145, v153
	v_fma_f32 v238, v90, v146, v154
	v_fma_f32 v239, v91, v147, v155
	v_fmac_f32_dpp v236, v88, v136 row_shr:1 row_mask:0xf bank_mask:0xf bound_ctrl:1
	v_fmac_f32_dpp v237, v89, v137 row_shr:1 row_mask:0xf bank_mask:0xf bound_ctrl:1
	v_fmac_f32_dpp v238, v90, v138 row_shr:1 row_mask:0xf bank_mask:0xf bound_ctrl:1
	v_fmac_f32_dpp v239, v91, v139 row_shr:1 row_mask:0xf bank_mask:0xf bound_ctrl:1
	v_fmac_f32_dpp v236, v88, v128 row_shr:2 row_mask:0xf bank_mask:0xf bound_ctrl:1
	v_fmac_f32_dpp v237, v89, v129 row_shr:2 row_mask:0xf bank_mask:0xf bound_ctrl:1
	v_fmac_f32_dpp v238, v90, v130 row_shr:2 row_mask:0xf bank_mask:0xf bound_ctrl:1
	v_fmac_f32_dpp v239, v91, v131 row_shr:2 row_mask:0xf bank_mask:0xf bound_ctrl:1
	v_fmac_f32_dpp v236, v104, v160 row_ror:1 row_mask:0xf bank_mask:0xf
	v_fmac_f32_dpp v237, v105, v161 row_ror:1 row_mask:0xf bank_mask:0xf
	v_fmac_f32_dpp v238, v106, v162 row_ror:1 row_mask:0xf bank_mask:0xf
	v_fmac_f32_dpp v239, v107, v163 row_ror:1 row_mask:0xf bank_mask:0xf
	v_fmac_f32_dpp v236, v104, v168 row_ror:2 row_mask:0xf bank_mask:0xf
	v_fmac_f32_dpp v237, v105, v169 row_ror:2 row_mask:0xf bank_mask:0xf
	v_fmac_f32_dpp v238, v106, v170 row_ror:2 row_mask:0xf bank_mask:0xf
	v_fmac_f32_dpp v239, v107, v171 row_ror:2 row_mask:0xf bank_mask:0xf
	v_fma_f32 v240, v80, v148, v156
	v_fma_f32 v241, v81, v149, v157
	v_fma_f32 v242, v82, v150, v158
	v_fma_f32 v243, v83, v151, v159
	v_fmac_f32_dpp v240, v80, v140 row_shr:1 row_mask:0xf bank_mask:0xf bound_ctrl:1
	v_fmac_f32_dpp v241, v81, v141 row_shr:1 row_mask:0xf bank_mask:0xf bound_ctrl:1
	v_fmac_f32_dpp v242, v82, v142 row_shr:1 row_mask:0xf bank_mask:0xf bound_ctrl:1
	v_fmac_f32_dpp v243, v83, v143 row_shr:1 row_mask:0xf bank_mask:0xf bound_ctrl:1
	v_fmac_f32_dpp v240, v80, v132 row_shr:2 row_mask:0xf bank_mask:0xf bound_ctrl:1
	v_fmac_f32_dpp v241, v81, v133 row_shr:2 row_mask:0xf bank_mask:0xf bound_ctrl:1
	v_fmac_f32_dpp v242, v82, v134 row_shr:2 row_mask:0xf bank_mask:0xf bound_ctrl:1
	v_fmac_f32_dpp v243, v83, v135 row_shr:2 row_mask:0xf bank_mask:0xf bound_ctrl:1
	v_fmac_f32_dpp v240, v96, v164 row_ror:1 row_mask:0xf bank_mask:0xf
	v_fmac_f32_dpp v241, v97, v165 row_ror:1 row_mask:0xf bank_mask:0xf
	v_fmac_f32_dpp v242, v98, v166 row_ror:1 row_mask:0xf bank_mask:0xf
	v_fmac_f32_dpp v243, v99, v167 row_ror:1 row_mask:0xf bank_mask:0xf
	v_fmac_f32_dpp v240, v96, v204 row_ror:2 row_mask:0xf bank_mask:0xf
	v_fmac_f32_dpp v241, v97, v205 row_ror:2 row_mask:0xf bank_mask:0xf
	v_fmac_f32_dpp v242, v98, v206 row_ror:2 row_mask:0xf bank_mask:0xf
	v_fmac_f32_dpp v243, v99, v207 row_ror:2 row_mask:0xf bank_mask:0xf
	v_mov_b32_e32 v228, 0xbdd2d3e8
	v_mul_f32_e32 v244, v236, v236
	v_mul_f32_e32 v245, v237, v237
	v_mul_f32_e32 v246, v238, v238
	v_mul_f32_e32 v247, v239, v239
	v_fmaak_f32 v244, v244, v228, 0xc0135761
	v_fmaak_f32 v245, v245, v228, 0xc0135761
	v_fmaak_f32 v246, v246, v228, 0xc0135761
	v_fmaak_f32 v247, v247, v228, 0xc0135761
	v_mul_f32_e32 v244, v236, v244
	v_mul_f32_e32 v245, v237, v245
	v_mul_f32_e32 v246, v238, v246
	v_mul_f32_e32 v247, v239, v247
	v_exp_f32_e32 v244, v244
	v_exp_f32_e32 v245, v245
	v_exp_f32_e32 v246, v246
	v_exp_f32_e32 v247, v247
	v_add_f32_e32 v244, 1.0, v244
	v_add_f32_e32 v245, 1.0, v245
	v_add_f32_e32 v246, 1.0, v246
	v_add_f32_e32 v247, 1.0, v247
	v_rcp_f32_e32 v244, v244
	v_rcp_f32_e32 v245, v245
	v_rcp_f32_e32 v246, v246
	v_rcp_f32_e32 v247, v247
	v_mul_f32_e32 v244, v236, v244
	v_mul_f32_e32 v245, v237, v245
	v_mul_f32_e32 v246, v238, v246
	v_mul_f32_e32 v247, v239, v247
	v_mul_f32_e32 v248, v240, v244
	v_mul_f32_e32 v249, v241, v245
	v_mul_f32_e32 v250, v242, v246
	v_mul_f32_e32 v251, v243, v247
	v_mov_b32_e32 v180, v212
	v_mov_b32_e32 v181, v213
	v_cvt_pk_bf16_f32 v182, v248, v249
	v_cvt_pk_bf16_f32 v183, v250, v251
.Lffn1e_join1_2:
	v_add_u32_e32 v252, 32, v218
	v_mad_i64_i32 v[226:227], vcc, v252, s79, v[190:191]
	v_cmp_gt_i32_e32 vcc, s58, v252
	s_nop 1
	s_and_saveexec_b64 s[10:11], vcc
	global_store_dwordx4 v[226:227], v[180:183], off sc1
	s_mov_b64 exec, s[10:11]
	s_add_i32 s6, s0, 2127
	s_mul_hi_u32 s7, s6, s59
	s_lshr_b32 s7, s7, 7
	s_mulk_i32 s7, 0x810
	s_sub_i32 s6, s6, s7
	s_cmp_lt_u32 s6, 17
	s_cbranch_scc1 .Lffn1e_slow1_3
	s_cmp_lt_u32 s6, 33
	s_cbranch_scc1 .Lffn1e_old1_3
	v_fma_f32 v236, v72, v144, v152
	v_fma_f32 v237, v73, v145, v153
	v_fma_f32 v238, v74, v146, v154
	v_fma_f32 v239, v75, v147, v155
	v_fmac_f32_dpp v236, v72, v136 row_shr:1 row_mask:0xf bank_mask:0xf bound_ctrl:1
	v_fmac_f32_dpp v237, v73, v137 row_shr:1 row_mask:0xf bank_mask:0xf bound_ctrl:1
	v_fmac_f32_dpp v238, v74, v138 row_shr:1 row_mask:0xf bank_mask:0xf bound_ctrl:1
	v_fmac_f32_dpp v239, v75, v139 row_shr:1 row_mask:0xf bank_mask:0xf bound_ctrl:1
	v_fmac_f32_dpp v236, v72, v128 row_shr:2 row_mask:0xf bank_mask:0xf bound_ctrl:1
	v_fmac_f32_dpp v237, v73, v129 row_shr:2 row_mask:0xf bank_mask:0xf bound_ctrl:1
	v_fmac_f32_dpp v238, v74, v130 row_shr:2 row_mask:0xf bank_mask:0xf bound_ctrl:1
	v_fmac_f32_dpp v239, v75, v131 row_shr:2 row_mask:0xf bank_mask:0xf bound_ctrl:1
	v_fmac_f32_dpp v236, v88, v160 row_ror:1 row_mask:0xf bank_mask:0xf
	v_fmac_f32_dpp v237, v89, v161 row_ror:1 row_mask:0xf bank_mask:0xf
	v_fmac_f32_dpp v238, v90, v162 row_ror:1 row_mask:0xf bank_mask:0xf
	v_fmac_f32_dpp v239, v91, v163 row_ror:1 row_mask:0xf bank_mask:0xf
	v_fmac_f32_dpp v236, v88, v168 row_ror:2 row_mask:0xf bank_mask:0xf
	v_fmac_f32_dpp v237, v89, v169 row_ror:2 row_mask:0xf bank_mask:0xf
	v_fmac_f32_dpp v238, v90, v170 row_ror:2 row_mask:0xf bank_mask:0xf
	v_fmac_f32_dpp v239, v91, v171 row_ror:2 row_mask:0xf bank_mask:0xf
	v_fma_f32 v240, v64, v148, v156
	v_fma_f32 v241, v65, v149, v157
	v_fma_f32 v242, v66, v150, v158
	v_fma_f32 v243, v67, v151, v159
	v_fmac_f32_dpp v240, v64, v140 row_shr:1 row_mask:0xf bank_mask:0xf bound_ctrl:1
	v_fmac_f32_dpp v241, v65, v141 row_shr:1 row_mask:0xf bank_mask:0xf bound_ctrl:1
	v_fmac_f32_dpp v242, v66, v142 row_shr:1 row_mask:0xf bank_mask:0xf bound_ctrl:1
	v_fmac_f32_dpp v243, v67, v143 row_shr:1 row_mask:0xf bank_mask:0xf bound_ctrl:1
	v_fmac_f32_dpp v240, v64, v132 row_shr:2 row_mask:0xf bank_mask:0xf bound_ctrl:1
	v_fmac_f32_dpp v241, v65, v133 row_shr:2 row_mask:0xf bank_mask:0xf bound_ctrl:1
	v_fmac_f32_dpp v242, v66, v134 row_shr:2 row_mask:0xf bank_mask:0xf bound_ctrl:1
	v_fmac_f32_dpp v243, v67, v135 row_shr:2 row_mask:0xf bank_mask:0xf bound_ctrl:1
	v_fmac_f32_dpp v240, v80, v164 row_ror:1 row_mask:0xf bank_mask:0xf
	v_fmac_f32_dpp v241, v81, v165 row_ror:1 row_mask:0xf bank_mask:0xf
	v_fmac_f32_dpp v242, v82, v166 row_ror:1 row_mask:0xf bank_mask:0xf
	v_fmac_f32_dpp v243, v83, v167 row_ror:1 row_mask:0xf bank_mask:0xf
	v_fmac_f32_dpp v240, v80, v204 row_ror:2 row_mask:0xf bank_mask:0xf
	v_fmac_f32_dpp v241, v81, v205 row_ror:2 row_mask:0xf bank_mask:0xf
	v_fmac_f32_dpp v242, v82, v206 row_ror:2 row_mask:0xf bank_mask:0xf
	v_fmac_f32_dpp v243, v83, v207 row_ror:2 row_mask:0xf bank_mask:0xf
	v_mov_b32_e32 v228, 0xbdd2d3e8
	v_mul_f32_e32 v244, v236, v236
	v_mul_f32_e32 v245, v237, v237
	v_mul_f32_e32 v246, v238, v238
	v_mul_f32_e32 v247, v239, v239
	v_fmaak_f32 v244, v244, v228, 0xc0135761
	v_fmaak_f32 v245, v245, v228, 0xc0135761
	v_fmaak_f32 v246, v246, v228, 0xc0135761
	v_fmaak_f32 v247, v247, v228, 0xc0135761
	v_mul_f32_e32 v244, v236, v244
	v_mul_f32_e32 v245, v237, v245
	v_mul_f32_e32 v246, v238, v246
	v_mul_f32_e32 v247, v239, v247
	v_exp_f32_e32 v244, v244
	v_exp_f32_e32 v245, v245
	v_exp_f32_e32 v246, v246
	v_exp_f32_e32 v247, v247
	v_add_f32_e32 v244, 1.0, v244
	v_add_f32_e32 v245, 1.0, v245
	v_add_f32_e32 v246, 1.0, v246
	v_add_f32_e32 v247, 1.0, v247
	v_rcp_f32_e32 v244, v244
	v_rcp_f32_e32 v245, v245
	v_rcp_f32_e32 v246, v246
	v_rcp_f32_e32 v247, v247
	v_mul_f32_e32 v244, v236, v244
	v_mul_f32_e32 v245, v237, v245
	v_mul_f32_e32 v246, v238, v246
	v_mul_f32_e32 v247, v239, v247
	v_mul_f32_e32 v248, v240, v244
	v_mul_f32_e32 v249, v241, v245
	v_mul_f32_e32 v250, v242, v246
	v_mul_f32_e32 v251, v243, v247
	v_mov_b32_e32 v180, v214
	v_mov_b32_e32 v181, v215
	v_cvt_pk_bf16_f32 v182, v248, v249
	v_cvt_pk_bf16_f32 v183, v250, v251
.Lffn1e_join1_3:
	v_add_u32_e32 v252, 48, v218
	v_mad_i64_i32 v[226:227], vcc, v252, s79, v[190:191]
	v_cmp_gt_i32_e32 vcc, s58, v252
	s_nop 1
	s_and_saveexec_b64 s[10:11], vcc
	global_store_dwordx4 v[226:227], v[180:183], off sc1
	s_mov_b64 exec, s[10:11]
	s_add_i32 s6, s0, 2143
	s_mul_hi_u32 s7, s6, s59
	s_lshr_b32 s7, s7, 7
	s_mulk_i32 s7, 0x810
	s_sub_i32 s6, s6, s7
	s_cmp_lt_u32 s6, 17
	s_cbranch_scc1 .Lffn1e_slow1_4
	s_cmp_lt_u32 s6, 33
	s_cbranch_scc1 .Lffn1e_old1_4
	v_fma_f32 v236, v56, v144, v152
	v_fma_f32 v237, v57, v145, v153
	v_fma_f32 v238, v58, v146, v154
	v_fma_f32 v239, v59, v147, v155
	v_fmac_f32_dpp v236, v56, v136 row_shr:1 row_mask:0xf bank_mask:0xf bound_ctrl:1
	v_fmac_f32_dpp v237, v57, v137 row_shr:1 row_mask:0xf bank_mask:0xf bound_ctrl:1
	v_fmac_f32_dpp v238, v58, v138 row_shr:1 row_mask:0xf bank_mask:0xf bound_ctrl:1
	v_fmac_f32_dpp v239, v59, v139 row_shr:1 row_mask:0xf bank_mask:0xf bound_ctrl:1
	v_fmac_f32_dpp v236, v56, v128 row_shr:2 row_mask:0xf bank_mask:0xf bound_ctrl:1
	v_fmac_f32_dpp v237, v57, v129 row_shr:2 row_mask:0xf bank_mask:0xf bound_ctrl:1
	v_fmac_f32_dpp v238, v58, v130 row_shr:2 row_mask:0xf bank_mask:0xf bound_ctrl:1
	v_fmac_f32_dpp v239, v59, v131 row_shr:2 row_mask:0xf bank_mask:0xf bound_ctrl:1
	v_fmac_f32_dpp v236, v72, v160 row_ror:1 row_mask:0xf bank_mask:0xf
	v_fmac_f32_dpp v237, v73, v161 row_ror:1 row_mask:0xf bank_mask:0xf
	v_fmac_f32_dpp v238, v74, v162 row_ror:1 row_mask:0xf bank_mask:0xf
	v_fmac_f32_dpp v239, v75, v163 row_ror:1 row_mask:0xf bank_mask:0xf
	v_fmac_f32_dpp v236, v72, v168 row_ror:2 row_mask:0xf bank_mask:0xf
	v_fmac_f32_dpp v237, v73, v169 row_ror:2 row_mask:0xf bank_mask:0xf
	v_fmac_f32_dpp v238, v74, v170 row_ror:2 row_mask:0xf bank_mask:0xf
	v_fmac_f32_dpp v239, v75, v171 row_ror:2 row_mask:0xf bank_mask:0xf
	v_fma_f32 v240, v48, v148, v156
	v_fma_f32 v241, v49, v149, v157
	v_fma_f32 v242, v50, v150, v158
	v_fma_f32 v243, v51, v151, v159
	v_fmac_f32_dpp v240, v48, v140 row_shr:1 row_mask:0xf bank_mask:0xf bound_ctrl:1
	v_fmac_f32_dpp v241, v49, v141 row_shr:1 row_mask:0xf bank_mask:0xf bound_ctrl:1
	v_fmac_f32_dpp v242, v50, v142 row_shr:1 row_mask:0xf bank_mask:0xf bound_ctrl:1
	v_fmac_f32_dpp v243, v51, v143 row_shr:1 row_mask:0xf bank_mask:0xf bound_ctrl:1
	v_fmac_f32_dpp v240, v48, v132 row_shr:2 row_mask:0xf bank_mask:0xf bound_ctrl:1
	v_fmac_f32_dpp v241, v49, v133 row_shr:2 row_mask:0xf bank_mask:0xf bound_ctrl:1
	v_fmac_f32_dpp v242, v50, v134 row_shr:2 row_mask:0xf bank_mask:0xf bound_ctrl:1
	v_fmac_f32_dpp v243, v51, v135 row_shr:2 row_mask:0xf bank_mask:0xf bound_ctrl:1
	v_fmac_f32_dpp v240, v64, v164 row_ror:1 row_mask:0xf bank_mask:0xf
	v_fmac_f32_dpp v241, v65, v165 row_ror:1 row_mask:0xf bank_mask:0xf
	v_fmac_f32_dpp v242, v66, v166 row_ror:1 row_mask:0xf bank_mask:0xf
	v_fmac_f32_dpp v243, v67, v167 row_ror:1 row_mask:0xf bank_mask:0xf
	v_fmac_f32_dpp v240, v64, v204 row_ror:2 row_mask:0xf bank_mask:0xf
	v_fmac_f32_dpp v241, v65, v205 row_ror:2 row_mask:0xf bank_mask:0xf
	v_fmac_f32_dpp v242, v66, v206 row_ror:2 row_mask:0xf bank_mask:0xf
	v_fmac_f32_dpp v243, v67, v207 row_ror:2 row_mask:0xf bank_mask:0xf
	v_mov_b32_e32 v228, 0xbdd2d3e8
	v_mul_f32_e32 v244, v236, v236
	v_mul_f32_e32 v245, v237, v237
	v_mul_f32_e32 v246, v238, v238
	v_mul_f32_e32 v247, v239, v239
	v_fmaak_f32 v244, v244, v228, 0xc0135761
	v_fmaak_f32 v245, v245, v228, 0xc0135761
	v_fmaak_f32 v246, v246, v228, 0xc0135761
	v_fmaak_f32 v247, v247, v228, 0xc0135761
	v_mul_f32_e32 v244, v236, v244
	v_mul_f32_e32 v245, v237, v245
	v_mul_f32_e32 v246, v238, v246
	v_mul_f32_e32 v247, v239, v247
	v_exp_f32_e32 v244, v244
	v_exp_f32_e32 v245, v245
	v_exp_f32_e32 v246, v246
	v_exp_f32_e32 v247, v247
	v_add_f32_e32 v244, 1.0, v244
	v_add_f32_e32 v245, 1.0, v245
	v_add_f32_e32 v246, 1.0, v246
	v_add_f32_e32 v247, 1.0, v247
	v_rcp_f32_e32 v244, v244
	v_rcp_f32_e32 v245, v245
	v_rcp_f32_e32 v246, v246
	v_rcp_f32_e32 v247, v247
	v_mul_f32_e32 v244, v236, v244
	v_mul_f32_e32 v245, v237, v245
	v_mul_f32_e32 v246, v238, v246
	v_mul_f32_e32 v247, v239, v247
	v_mul_f32_e32 v248, v240, v244
	v_mul_f32_e32 v249, v241, v245
	v_mul_f32_e32 v250, v242, v246
	v_mul_f32_e32 v251, v243, v247
	v_mov_b32_e32 v180, v216
	v_mov_b32_e32 v181, v217
	v_cvt_pk_bf16_f32 v182, v248, v249
	v_cvt_pk_bf16_f32 v183, v250, v251
.Lffn1e_join1_4:
	v_add_u32_e32 v252, 64, v218
	v_mad_i64_i32 v[226:227], vcc, v252, s79, v[190:191]
	v_cmp_gt_i32_e32 vcc, s58, v252
	s_nop 1
	s_and_saveexec_b64 s[10:11], vcc
	global_store_dwordx4 v[226:227], v[180:183], off sc1
	s_mov_b64 exec, s[10:11]
	s_add_i32 s6, s0, 2159
	s_mul_hi_u32 s7, s6, s59
	s_lshr_b32 s7, s7, 7
	s_mulk_i32 s7, 0x810
	s_sub_i32 s6, s6, s7
	s_cmp_lt_u32 s6, 17
	s_cbranch_scc1 .Lffn1e_slow1_5
	s_cmp_lt_u32 s6, 33
	s_cbranch_scc1 .Lffn1e_old1_5
	v_fma_f32 v236, v40, v144, v152
	v_fma_f32 v237, v41, v145, v153
	v_fma_f32 v238, v42, v146, v154
	v_fma_f32 v239, v43, v147, v155
	v_fmac_f32_dpp v236, v40, v136 row_shr:1 row_mask:0xf bank_mask:0xf bound_ctrl:1
	v_fmac_f32_dpp v237, v41, v137 row_shr:1 row_mask:0xf bank_mask:0xf bound_ctrl:1
	v_fmac_f32_dpp v238, v42, v138 row_shr:1 row_mask:0xf bank_mask:0xf bound_ctrl:1
	v_fmac_f32_dpp v239, v43, v139 row_shr:1 row_mask:0xf bank_mask:0xf bound_ctrl:1
	v_fmac_f32_dpp v236, v40, v128 row_shr:2 row_mask:0xf bank_mask:0xf bound_ctrl:1
	v_fmac_f32_dpp v237, v41, v129 row_shr:2 row_mask:0xf bank_mask:0xf bound_ctrl:1
	v_fmac_f32_dpp v238, v42, v130 row_shr:2 row_mask:0xf bank_mask:0xf bound_ctrl:1
	v_fmac_f32_dpp v239, v43, v131 row_shr:2 row_mask:0xf bank_mask:0xf bound_ctrl:1
	v_fmac_f32_dpp v236, v56, v160 row_ror:1 row_mask:0xf bank_mask:0xf
	v_fmac_f32_dpp v237, v57, v161 row_ror:1 row_mask:0xf bank_mask:0xf
	v_fmac_f32_dpp v238, v58, v162 row_ror:1 row_mask:0xf bank_mask:0xf
	v_fmac_f32_dpp v239, v59, v163 row_ror:1 row_mask:0xf bank_mask:0xf
	v_fmac_f32_dpp v236, v56, v168 row_ror:2 row_mask:0xf bank_mask:0xf
	v_fmac_f32_dpp v237, v57, v169 row_ror:2 row_mask:0xf bank_mask:0xf
	v_fmac_f32_dpp v238, v58, v170 row_ror:2 row_mask:0xf bank_mask:0xf
	v_fmac_f32_dpp v239, v59, v171 row_ror:2 row_mask:0xf bank_mask:0xf
	v_fma_f32 v240, v32, v148, v156
	v_fma_f32 v241, v33, v149, v157
	v_fma_f32 v242, v34, v150, v158
	v_fma_f32 v243, v35, v151, v159
	v_fmac_f32_dpp v240, v32, v140 row_shr:1 row_mask:0xf bank_mask:0xf bound_ctrl:1
	v_fmac_f32_dpp v241, v33, v141 row_shr:1 row_mask:0xf bank_mask:0xf bound_ctrl:1
	v_fmac_f32_dpp v242, v34, v142 row_shr:1 row_mask:0xf bank_mask:0xf bound_ctrl:1
	v_fmac_f32_dpp v243, v35, v143 row_shr:1 row_mask:0xf bank_mask:0xf bound_ctrl:1
	v_fmac_f32_dpp v240, v32, v132 row_shr:2 row_mask:0xf bank_mask:0xf bound_ctrl:1
	v_fmac_f32_dpp v241, v33, v133 row_shr:2 row_mask:0xf bank_mask:0xf bound_ctrl:1
	v_fmac_f32_dpp v242, v34, v134 row_shr:2 row_mask:0xf bank_mask:0xf bound_ctrl:1
	v_fmac_f32_dpp v243, v35, v135 row_shr:2 row_mask:0xf bank_mask:0xf bound_ctrl:1
	v_fmac_f32_dpp v240, v48, v164 row_ror:1 row_mask:0xf bank_mask:0xf
	v_fmac_f32_dpp v241, v49, v165 row_ror:1 row_mask:0xf bank_mask:0xf
	v_fmac_f32_dpp v242, v50, v166 row_ror:1 row_mask:0xf bank_mask:0xf
	v_fmac_f32_dpp v243, v51, v167 row_ror:1 row_mask:0xf bank_mask:0xf
	v_fmac_f32_dpp v240, v48, v204 row_ror:2 row_mask:0xf bank_mask:0xf
	v_fmac_f32_dpp v241, v49, v205 row_ror:2 row_mask:0xf bank_mask:0xf
	v_fmac_f32_dpp v242, v50, v206 row_ror:2 row_mask:0xf bank_mask:0xf
	v_fmac_f32_dpp v243, v51, v207 row_ror:2 row_mask:0xf bank_mask:0xf
	v_mov_b32_e32 v228, 0xbdd2d3e8
	v_mul_f32_e32 v244, v236, v236
	v_mul_f32_e32 v245, v237, v237
	v_mul_f32_e32 v246, v238, v238
	v_mul_f32_e32 v247, v239, v239
	v_fmaak_f32 v244, v244, v228, 0xc0135761
	v_fmaak_f32 v245, v245, v228, 0xc0135761
	v_fmaak_f32 v246, v246, v228, 0xc0135761
	v_fmaak_f32 v247, v247, v228, 0xc0135761
	v_mul_f32_e32 v244, v236, v244
	v_mul_f32_e32 v245, v237, v245
	v_mul_f32_e32 v246, v238, v246
	v_mul_f32_e32 v247, v239, v247
	v_exp_f32_e32 v244, v244
	v_exp_f32_e32 v245, v245
	v_exp_f32_e32 v246, v246
	v_exp_f32_e32 v247, v247
	v_add_f32_e32 v244, 1.0, v244
	v_add_f32_e32 v245, 1.0, v245
	v_add_f32_e32 v246, 1.0, v246
	v_add_f32_e32 v247, 1.0, v247
	v_rcp_f32_e32 v244, v244
	v_rcp_f32_e32 v245, v245
	v_rcp_f32_e32 v246, v246
	v_rcp_f32_e32 v247, v247
	v_mul_f32_e32 v244, v236, v244
	v_mul_f32_e32 v245, v237, v245
	v_mul_f32_e32 v246, v238, v246
	v_mul_f32_e32 v247, v239, v247
	v_mul_f32_e32 v248, v240, v244
	v_mul_f32_e32 v249, v241, v245
	v_mul_f32_e32 v250, v242, v246
	v_mul_f32_e32 v251, v243, v247
	v_mov_b32_e32 v180, v220
	v_mov_b32_e32 v181, v221
	v_cvt_pk_bf16_f32 v182, v248, v249
	v_cvt_pk_bf16_f32 v183, v250, v251
.Lffn1e_join1_5:
	v_add_u32_e32 v252, 80, v218
	v_mad_i64_i32 v[226:227], vcc, v252, s79, v[190:191]
	v_cmp_gt_i32_e32 vcc, s58, v252
	s_nop 1
	s_and_saveexec_b64 s[10:11], vcc
	global_store_dwordx4 v[226:227], v[180:183], off sc1
	s_mov_b64 exec, s[10:11]
	s_add_i32 s6, s0, 2175
	s_mul_hi_u32 s7, s6, s59
	s_lshr_b32 s7, s7, 7
	s_mulk_i32 s7, 0x810
	s_sub_i32 s6, s6, s7
	s_cmp_lt_u32 s6, 17
	s_cbranch_scc1 .Lffn1e_slow1_6
	s_cmp_lt_u32 s6, 33
	s_cbranch_scc1 .Lffn1e_old1_6
	v_fma_f32 v236, v24, v144, v152
	v_fma_f32 v237, v25, v145, v153
	v_fma_f32 v238, v26, v146, v154
	v_fma_f32 v239, v27, v147, v155
	v_fmac_f32_dpp v236, v24, v136 row_shr:1 row_mask:0xf bank_mask:0xf bound_ctrl:1
	v_fmac_f32_dpp v237, v25, v137 row_shr:1 row_mask:0xf bank_mask:0xf bound_ctrl:1
	v_fmac_f32_dpp v238, v26, v138 row_shr:1 row_mask:0xf bank_mask:0xf bound_ctrl:1
	v_fmac_f32_dpp v239, v27, v139 row_shr:1 row_mask:0xf bank_mask:0xf bound_ctrl:1
	v_fmac_f32_dpp v236, v24, v128 row_shr:2 row_mask:0xf bank_mask:0xf bound_ctrl:1
	v_fmac_f32_dpp v237, v25, v129 row_shr:2 row_mask:0xf bank_mask:0xf bound_ctrl:1
	v_fmac_f32_dpp v238, v26, v130 row_shr:2 row_mask:0xf bank_mask:0xf bound_ctrl:1
	v_fmac_f32_dpp v239, v27, v131 row_shr:2 row_mask:0xf bank_mask:0xf bound_ctrl:1
	v_fmac_f32_dpp v236, v40, v160 row_ror:1 row_mask:0xf bank_mask:0xf
	v_fmac_f32_dpp v237, v41, v161 row_ror:1 row_mask:0xf bank_mask:0xf
	v_fmac_f32_dpp v238, v42, v162 row_ror:1 row_mask:0xf bank_mask:0xf
	v_fmac_f32_dpp v239, v43, v163 row_ror:1 row_mask:0xf bank_mask:0xf
	v_fmac_f32_dpp v236, v40, v168 row_ror:2 row_mask:0xf bank_mask:0xf
	v_fmac_f32_dpp v237, v41, v169 row_ror:2 row_mask:0xf bank_mask:0xf
	v_fmac_f32_dpp v238, v42, v170 row_ror:2 row_mask:0xf bank_mask:0xf
	v_fmac_f32_dpp v239, v43, v171 row_ror:2 row_mask:0xf bank_mask:0xf
	v_fma_f32 v240, v16, v148, v156
	v_fma_f32 v241, v17, v149, v157
	v_fma_f32 v242, v18, v150, v158
	v_fma_f32 v243, v19, v151, v159
	v_fmac_f32_dpp v240, v16, v140 row_shr:1 row_mask:0xf bank_mask:0xf bound_ctrl:1
	v_fmac_f32_dpp v241, v17, v141 row_shr:1 row_mask:0xf bank_mask:0xf bound_ctrl:1
	v_fmac_f32_dpp v242, v18, v142 row_shr:1 row_mask:0xf bank_mask:0xf bound_ctrl:1
	v_fmac_f32_dpp v243, v19, v143 row_shr:1 row_mask:0xf bank_mask:0xf bound_ctrl:1
	v_fmac_f32_dpp v240, v16, v132 row_shr:2 row_mask:0xf bank_mask:0xf bound_ctrl:1
	v_fmac_f32_dpp v241, v17, v133 row_shr:2 row_mask:0xf bank_mask:0xf bound_ctrl:1
	v_fmac_f32_dpp v242, v18, v134 row_shr:2 row_mask:0xf bank_mask:0xf bound_ctrl:1
	v_fmac_f32_dpp v243, v19, v135 row_shr:2 row_mask:0xf bank_mask:0xf bound_ctrl:1
	v_fmac_f32_dpp v240, v32, v164 row_ror:1 row_mask:0xf bank_mask:0xf
	v_fmac_f32_dpp v241, v33, v165 row_ror:1 row_mask:0xf bank_mask:0xf
	v_fmac_f32_dpp v242, v34, v166 row_ror:1 row_mask:0xf bank_mask:0xf
	v_fmac_f32_dpp v243, v35, v167 row_ror:1 row_mask:0xf bank_mask:0xf
	v_fmac_f32_dpp v240, v32, v204 row_ror:2 row_mask:0xf bank_mask:0xf
	v_fmac_f32_dpp v241, v33, v205 row_ror:2 row_mask:0xf bank_mask:0xf
	v_fmac_f32_dpp v242, v34, v206 row_ror:2 row_mask:0xf bank_mask:0xf
	v_fmac_f32_dpp v243, v35, v207 row_ror:2 row_mask:0xf bank_mask:0xf
	v_mov_b32_e32 v228, 0xbdd2d3e8
	v_mul_f32_e32 v244, v236, v236
	v_mul_f32_e32 v245, v237, v237
	v_mul_f32_e32 v246, v238, v238
	v_mul_f32_e32 v247, v239, v239
	v_fmaak_f32 v244, v244, v228, 0xc0135761
	v_fmaak_f32 v245, v245, v228, 0xc0135761
	v_fmaak_f32 v246, v246, v228, 0xc0135761
	v_fmaak_f32 v247, v247, v228, 0xc0135761
	v_mul_f32_e32 v244, v236, v244
	v_mul_f32_e32 v245, v237, v245
	v_mul_f32_e32 v246, v238, v246
	v_mul_f32_e32 v247, v239, v247
	v_exp_f32_e32 v244, v244
	v_exp_f32_e32 v245, v245
	v_exp_f32_e32 v246, v246
	v_exp_f32_e32 v247, v247
	v_add_f32_e32 v244, 1.0, v244
	v_add_f32_e32 v245, 1.0, v245
	v_add_f32_e32 v246, 1.0, v246
	v_add_f32_e32 v247, 1.0, v247
	v_rcp_f32_e32 v244, v244
	v_rcp_f32_e32 v245, v245
	v_rcp_f32_e32 v246, v246
	v_rcp_f32_e32 v247, v247
	v_mul_f32_e32 v244, v236, v244
	v_mul_f32_e32 v245, v237, v245
	v_mul_f32_e32 v246, v238, v246
	v_mul_f32_e32 v247, v239, v247
	v_mul_f32_e32 v248, v240, v244
	v_mul_f32_e32 v249, v241, v245
	v_mul_f32_e32 v250, v242, v246
	v_mul_f32_e32 v251, v243, v247
	v_mov_b32_e32 v180, v222
	v_mov_b32_e32 v181, v223
	v_cvt_pk_bf16_f32 v182, v248, v249
	v_cvt_pk_bf16_f32 v183, v250, v251
.Lffn1e_join1_6:
	v_add_u32_e32 v252, 96, v218
	v_mad_i64_i32 v[226:227], vcc, v252, s79, v[190:191]
	v_cmp_gt_i32_e32 vcc, s58, v252
	s_nop 1
	s_and_saveexec_b64 s[10:11], vcc
	global_store_dwordx4 v[226:227], v[180:183], off sc1
	s_mov_b64 exec, s[10:11]
	s_add_i32 s6, s0, 2191
	s_mul_hi_u32 s7, s6, s59
	s_lshr_b32 s7, s7, 7
	s_mulk_i32 s7, 0x810
	s_sub_i32 s6, s6, s7
	s_cmp_lt_u32 s6, 17
	s_cbranch_scc1 .Lffn1e_slow1_7
	s_cmp_lt_u32 s6, 33
	s_cbranch_scc1 .Lffn1e_old1_7
	v_fma_f32 v236, v12, v144, v152
	v_fma_f32 v237, v13, v145, v153
	v_fma_f32 v238, v14, v146, v154
	v_fma_f32 v239, v15, v147, v155
	v_fmac_f32_dpp v236, v12, v136 row_shr:1 row_mask:0xf bank_mask:0xf bound_ctrl:1
	v_fmac_f32_dpp v237, v13, v137 row_shr:1 row_mask:0xf bank_mask:0xf bound_ctrl:1
	v_fmac_f32_dpp v238, v14, v138 row_shr:1 row_mask:0xf bank_mask:0xf bound_ctrl:1
	v_fmac_f32_dpp v239, v15, v139 row_shr:1 row_mask:0xf bank_mask:0xf bound_ctrl:1
	v_fmac_f32_dpp v236, v12, v128 row_shr:2 row_mask:0xf bank_mask:0xf bound_ctrl:1
	v_fmac_f32_dpp v237, v13, v129 row_shr:2 row_mask:0xf bank_mask:0xf bound_ctrl:1
	v_fmac_f32_dpp v238, v14, v130 row_shr:2 row_mask:0xf bank_mask:0xf bound_ctrl:1
	v_fmac_f32_dpp v239, v15, v131 row_shr:2 row_mask:0xf bank_mask:0xf bound_ctrl:1
	v_fmac_f32_dpp v236, v24, v160 row_ror:1 row_mask:0xf bank_mask:0xf
	v_fmac_f32_dpp v237, v25, v161 row_ror:1 row_mask:0xf bank_mask:0xf
	v_fmac_f32_dpp v238, v26, v162 row_ror:1 row_mask:0xf bank_mask:0xf
	v_fmac_f32_dpp v239, v27, v163 row_ror:1 row_mask:0xf bank_mask:0xf
	v_fmac_f32_dpp v236, v24, v168 row_ror:2 row_mask:0xf bank_mask:0xf
	v_fmac_f32_dpp v237, v25, v169 row_ror:2 row_mask:0xf bank_mask:0xf
	v_fmac_f32_dpp v238, v26, v170 row_ror:2 row_mask:0xf bank_mask:0xf
	v_fmac_f32_dpp v239, v27, v171 row_ror:2 row_mask:0xf bank_mask:0xf
	v_fma_f32 v240, v0, v148, v156
	v_fma_f32 v241, v1, v149, v157
	v_fma_f32 v242, v2, v150, v158
	v_fma_f32 v243, v3, v151, v159
	v_fmac_f32_dpp v240, v0, v140 row_shr:1 row_mask:0xf bank_mask:0xf bound_ctrl:1
	v_fmac_f32_dpp v241, v1, v141 row_shr:1 row_mask:0xf bank_mask:0xf bound_ctrl:1
	v_fmac_f32_dpp v242, v2, v142 row_shr:1 row_mask:0xf bank_mask:0xf bound_ctrl:1
	v_fmac_f32_dpp v243, v3, v143 row_shr:1 row_mask:0xf bank_mask:0xf bound_ctrl:1
	v_fmac_f32_dpp v240, v0, v132 row_shr:2 row_mask:0xf bank_mask:0xf bound_ctrl:1
	v_fmac_f32_dpp v241, v1, v133 row_shr:2 row_mask:0xf bank_mask:0xf bound_ctrl:1
	v_fmac_f32_dpp v242, v2, v134 row_shr:2 row_mask:0xf bank_mask:0xf bound_ctrl:1
	v_fmac_f32_dpp v243, v3, v135 row_shr:2 row_mask:0xf bank_mask:0xf bound_ctrl:1
	v_fmac_f32_dpp v240, v16, v164 row_ror:1 row_mask:0xf bank_mask:0xf
	v_fmac_f32_dpp v241, v17, v165 row_ror:1 row_mask:0xf bank_mask:0xf
	v_fmac_f32_dpp v242, v18, v166 row_ror:1 row_mask:0xf bank_mask:0xf
	v_fmac_f32_dpp v243, v19, v167 row_ror:1 row_mask:0xf bank_mask:0xf
	v_fmac_f32_dpp v240, v16, v204 row_ror:2 row_mask:0xf bank_mask:0xf
	v_fmac_f32_dpp v241, v17, v205 row_ror:2 row_mask:0xf bank_mask:0xf
	v_fmac_f32_dpp v242, v18, v206 row_ror:2 row_mask:0xf bank_mask:0xf
	v_fmac_f32_dpp v243, v19, v207 row_ror:2 row_mask:0xf bank_mask:0xf
	v_mov_b32_e32 v228, 0xbdd2d3e8
	v_mul_f32_e32 v244, v236, v236
	v_mul_f32_e32 v245, v237, v237
	v_mul_f32_e32 v246, v238, v238
	v_mul_f32_e32 v247, v239, v239
	v_fmaak_f32 v244, v244, v228, 0xc0135761
	v_fmaak_f32 v245, v245, v228, 0xc0135761
	v_fmaak_f32 v246, v246, v228, 0xc0135761
	v_fmaak_f32 v247, v247, v228, 0xc0135761
	v_mul_f32_e32 v244, v236, v244
	v_mul_f32_e32 v245, v237, v245
	v_mul_f32_e32 v246, v238, v246
	v_mul_f32_e32 v247, v239, v247
	v_exp_f32_e32 v244, v244
	v_exp_f32_e32 v245, v245
	v_exp_f32_e32 v246, v246
	v_exp_f32_e32 v247, v247
	v_add_f32_e32 v244, 1.0, v244
	v_add_f32_e32 v245, 1.0, v245
	v_add_f32_e32 v246, 1.0, v246
	v_add_f32_e32 v247, 1.0, v247
	v_rcp_f32_e32 v244, v244
	v_rcp_f32_e32 v245, v245
	v_rcp_f32_e32 v246, v246
	v_rcp_f32_e32 v247, v247
	v_mul_f32_e32 v244, v236, v244
	v_mul_f32_e32 v245, v237, v245
	v_mul_f32_e32 v246, v238, v246
	v_mul_f32_e32 v247, v239, v247
	v_mul_f32_e32 v248, v240, v244
	v_mul_f32_e32 v249, v241, v245
	v_mul_f32_e32 v250, v242, v246
	v_mul_f32_e32 v251, v243, v247
	v_mov_b32_e32 v180, v224
	v_mov_b32_e32 v181, v225
	v_cvt_pk_bf16_f32 v182, v248, v249
	v_cvt_pk_bf16_f32 v183, v250, v251
.Lffn1e_join1_7:
	v_add_u32_e32 v252, 112, v218
	v_mad_i64_i32 v[226:227], vcc, v252, s79, v[190:191]
	v_cmp_gt_i32_e32 vcc, s58, v252
	s_nop 1
	s_and_saveexec_b64 s[10:11], vcc
	global_store_dwordx4 v[226:227], v[180:183], off sc1
	s_mov_b64 exec, s[10:11]
	s_branch .Lffn1e_done
.Lffn1e_slow0_0:
	v_add_u32_e32 v189, 2064, v218
	v_mul_hi_u32 v203, v189, s59
	v_lshrrev_b32_e32 v203, 7, v203
	v_mul_u32_u24_e32 v203, 0x810, v203
	v_sub_u32_e32 v189, v189, v203
	v_cmp_lt_u32_e32 vcc, 0, v189
	v_cmp_lt_u32_e64 s[8:9], 1, v189
	s_nop 1
	v_mov_b32_dpp v228, v124 row_shr:1 row_mask:0xf bank_mask:0xf bound_ctrl:1
	v_mov_b32_dpp v229, v124 row_shr:2 row_mask:0xf bank_mask:0xf bound_ctrl:1
	v_mov_b32_dpp v230, v125 row_shr:1 row_mask:0xf bank_mask:0xf bound_ctrl:1
	v_mov_b32_dpp v231, v125 row_shr:2 row_mask:0xf bank_mask:0xf bound_ctrl:1
	v_mov_b32_dpp v232, v126 row_shr:1 row_mask:0xf bank_mask:0xf bound_ctrl:1
	v_mov_b32_dpp v233, v126 row_shr:2 row_mask:0xf bank_mask:0xf bound_ctrl:1
	v_mov_b32_dpp v234, v127 row_shr:1 row_mask:0xf bank_mask:0xf bound_ctrl:1
	v_mov_b32_dpp v235, v127 row_shr:2 row_mask:0xf bank_mask:0xf bound_ctrl:1
	v_cndmask_b32_e64 v228, 0, v228, vcc
	v_cndmask_b32_e64 v229, 0, v229, s[8:9]
	v_cndmask_b32_e64 v230, 0, v230, vcc
	v_cndmask_b32_e64 v231, 0, v231, s[8:9]
	v_cndmask_b32_e64 v232, 0, v232, vcc
	v_cndmask_b32_e64 v233, 0, v233, s[8:9]
	v_cndmask_b32_e64 v234, 0, v234, vcc
	v_cndmask_b32_e64 v235, 0, v235, s[8:9]
	v_fma_f32 v236, v229, v128, v152
	v_fma_f32 v237, v231, v129, v153
	v_fma_f32 v238, v233, v130, v154
	v_fma_f32 v239, v235, v131, v155
	v_fmac_f32_e32 v236, v228, v136
	v_fmac_f32_e32 v237, v230, v137
	v_fmac_f32_e32 v238, v232, v138
	v_fmac_f32_e32 v239, v234, v139
	v_fmac_f32_e32 v236, v124, v144
	v_fmac_f32_e32 v237, v125, v145
	v_fmac_f32_e32 v238, v126, v146
	v_fmac_f32_e32 v239, v127, v147
	v_mov_b32_dpp v228, v116 row_shr:1 row_mask:0xf bank_mask:0xf bound_ctrl:1
	v_mov_b32_dpp v229, v116 row_shr:2 row_mask:0xf bank_mask:0xf bound_ctrl:1
	v_mov_b32_dpp v230, v117 row_shr:1 row_mask:0xf bank_mask:0xf bound_ctrl:1
	v_mov_b32_dpp v231, v117 row_shr:2 row_mask:0xf bank_mask:0xf bound_ctrl:1
	v_mov_b32_dpp v232, v118 row_shr:1 row_mask:0xf bank_mask:0xf bound_ctrl:1
	v_mov_b32_dpp v233, v118 row_shr:2 row_mask:0xf bank_mask:0xf bound_ctrl:1
	v_mov_b32_dpp v234, v119 row_shr:1 row_mask:0xf bank_mask:0xf bound_ctrl:1
	v_mov_b32_dpp v235, v119 row_shr:2 row_mask:0xf bank_mask:0xf bound_ctrl:1
	v_cndmask_b32_e64 v228, 0, v228, vcc
	v_cndmask_b32_e64 v229, 0, v229, s[8:9]
	v_cndmask_b32_e64 v230, 0, v230, vcc
	v_cndmask_b32_e64 v231, 0, v231, s[8:9]
	v_cndmask_b32_e64 v232, 0, v232, vcc
	v_cndmask_b32_e64 v233, 0, v233, s[8:9]
	v_cndmask_b32_e64 v234, 0, v234, vcc
	v_cndmask_b32_e64 v235, 0, v235, s[8:9]
	v_fma_f32 v240, v229, v132, v156
	v_fma_f32 v241, v231, v133, v157
	v_fma_f32 v242, v233, v134, v158
	v_fma_f32 v243, v235, v135, v159
	v_fmac_f32_e32 v240, v228, v140
	v_fmac_f32_e32 v241, v230, v141
	v_fmac_f32_e32 v242, v232, v142
	v_fmac_f32_e32 v243, v234, v143
	v_fmac_f32_e32 v240, v116, v148
	v_fmac_f32_e32 v241, v117, v149
	v_fmac_f32_e32 v242, v118, v150
	v_fmac_f32_e32 v243, v119, v151
	v_mov_b32_e32 v228, 0xbdd2d3e8
	v_mul_f32_e32 v244, v236, v236
	v_mul_f32_e32 v245, v237, v237
	v_mul_f32_e32 v246, v238, v238
	v_mul_f32_e32 v247, v239, v239
	v_fmaak_f32 v244, v244, v228, 0xc0135761
	v_fmaak_f32 v245, v245, v228, 0xc0135761
	v_fmaak_f32 v246, v246, v228, 0xc0135761
	v_fmaak_f32 v247, v247, v228, 0xc0135761
	v_mul_f32_e32 v244, v236, v244
	v_mul_f32_e32 v245, v237, v245
	v_mul_f32_e32 v246, v238, v246
	v_mul_f32_e32 v247, v239, v247
	v_exp_f32_e32 v244, v244
	v_exp_f32_e32 v245, v245
	v_exp_f32_e32 v246, v246
	v_exp_f32_e32 v247, v247
	v_add_f32_e32 v244, 1.0, v244
	v_add_f32_e32 v245, 1.0, v245
	v_add_f32_e32 v246, 1.0, v246
	v_add_f32_e32 v247, 1.0, v247
	v_rcp_f32_e32 v244, v244
	v_rcp_f32_e32 v245, v245
	v_rcp_f32_e32 v246, v246
	v_rcp_f32_e32 v247, v247
	v_mul_f32_e32 v244, v236, v244
	v_mul_f32_e32 v245, v237, v245
	v_mul_f32_e32 v246, v238, v246
	v_mul_f32_e32 v247, v239, v247
	v_mul_f32_e32 v248, v240, v244
	v_mul_f32_e32 v249, v241, v245
	v_mul_f32_e32 v250, v242, v246
	v_mul_f32_e32 v251, v243, v247
	v_cvt_pk_bf16_f32 v208, v248, v249
	v_cvt_pk_bf16_f32 v209, v250, v251
	s_branch .Lffn1e_join0_0
.Lffn1e_slow0_1:
	v_add_u32_e32 v189, 2080, v218
	v_mul_hi_u32 v203, v189, s59
	v_lshrrev_b32_e32 v203, 7, v203
	v_mul_u32_u24_e32 v203, 0x810, v203
	v_sub_u32_e32 v189, v189, v203
	v_cmp_lt_u32_e32 vcc, 0, v189
	v_cmp_lt_u32_e64 s[8:9], 1, v189
	s_nop 1
	v_mov_b32_dpp v228, v124 row_ror:1 row_mask:0xf bank_mask:0xf
	v_mov_b32_dpp v229, v124 row_ror:2 row_mask:0xf bank_mask:0xf
	v_mov_b32_dpp v230, v125 row_ror:1 row_mask:0xf bank_mask:0xf
	v_mov_b32_dpp v231, v125 row_ror:2 row_mask:0xf bank_mask:0xf
	v_mov_b32_dpp v232, v126 row_ror:1 row_mask:0xf bank_mask:0xf
	v_mov_b32_dpp v233, v126 row_ror:2 row_mask:0xf bank_mask:0xf
	v_mov_b32_dpp v234, v127 row_ror:1 row_mask:0xf bank_mask:0xf
	v_mov_b32_dpp v235, v127 row_ror:2 row_mask:0xf bank_mask:0xf
	v_mov_b32_dpp v228, v108 row_shr:1 row_mask:0xf bank_mask:0xf
	v_mov_b32_dpp v229, v108 row_shr:2 row_mask:0xf bank_mask:0xf
	v_mov_b32_dpp v230, v109 row_shr:1 row_mask:0xf bank_mask:0xf
	v_mov_b32_dpp v231, v109 row_shr:2 row_mask:0xf bank_mask:0xf
	v_mov_b32_dpp v232, v110 row_shr:1 row_mask:0xf bank_mask:0xf
	v_mov_b32_dpp v233, v110 row_shr:2 row_mask:0xf bank_mask:0xf
	v_mov_b32_dpp v234, v111 row_shr:1 row_mask:0xf bank_mask:0xf
	v_mov_b32_dpp v235, v111 row_shr:2 row_mask:0xf bank_mask:0xf
	v_cndmask_b32_e64 v228, 0, v228, vcc
	v_cndmask_b32_e64 v229, 0, v229, s[8:9]
	v_cndmask_b32_e64 v230, 0, v230, vcc
	v_cndmask_b32_e64 v231, 0, v231, s[8:9]
	v_cndmask_b32_e64 v232, 0, v232, vcc
	v_cndmask_b32_e64 v233, 0, v233, s[8:9]
	v_cndmask_b32_e64 v234, 0, v234, vcc
	v_cndmask_b32_e64 v235, 0, v235, s[8:9]
	v_fma_f32 v236, v229, v128, v152
	v_fma_f32 v237, v231, v129, v153
	v_fma_f32 v238, v233, v130, v154
	v_fma_f32 v239, v235, v131, v155
	v_fmac_f32_e32 v236, v228, v136
	v_fmac_f32_e32 v237, v230, v137
	v_fmac_f32_e32 v238, v232, v138
	v_fmac_f32_e32 v239, v234, v139
	v_fmac_f32_e32 v236, v108, v144
	v_fmac_f32_e32 v237, v109, v145
	v_fmac_f32_e32 v238, v110, v146
	v_fmac_f32_e32 v239, v111, v147
	v_mov_b32_dpp v228, v116 row_ror:1 row_mask:0xf bank_mask:0xf
	v_mov_b32_dpp v229, v116 row_ror:2 row_mask:0xf bank_mask:0xf
	v_mov_b32_dpp v230, v117 row_ror:1 row_mask:0xf bank_mask:0xf
	v_mov_b32_dpp v231, v117 row_ror:2 row_mask:0xf bank_mask:0xf
	v_mov_b32_dpp v232, v118 row_ror:1 row_mask:0xf bank_mask:0xf
	v_mov_b32_dpp v233, v118 row_ror:2 row_mask:0xf bank_mask:0xf
	v_mov_b32_dpp v234, v119 row_ror:1 row_mask:0xf bank_mask:0xf
	v_mov_b32_dpp v235, v119 row_ror:2 row_mask:0xf bank_mask:0xf
	v_mov_b32_dpp v228, v100 row_shr:1 row_mask:0xf bank_mask:0xf
	v_mov_b32_dpp v229, v100 row_shr:2 row_mask:0xf bank_mask:0xf
	v_mov_b32_dpp v230, v101 row_shr:1 row_mask:0xf bank_mask:0xf
	v_mov_b32_dpp v231, v101 row_shr:2 row_mask:0xf bank_mask:0xf
	v_mov_b32_dpp v232, v102 row_shr:1 row_mask:0xf bank_mask:0xf
	v_mov_b32_dpp v233, v102 row_shr:2 row_mask:0xf bank_mask:0xf
	v_mov_b32_dpp v234, v103 row_shr:1 row_mask:0xf bank_mask:0xf
	v_mov_b32_dpp v235, v103 row_shr:2 row_mask:0xf bank_mask:0xf
	v_cndmask_b32_e64 v228, 0, v228, vcc
	v_cndmask_b32_e64 v229, 0, v229, s[8:9]
	v_cndmask_b32_e64 v230, 0, v230, vcc
	v_cndmask_b32_e64 v231, 0, v231, s[8:9]
	v_cndmask_b32_e64 v232, 0, v232, vcc
	v_cndmask_b32_e64 v233, 0, v233, s[8:9]
	v_cndmask_b32_e64 v234, 0, v234, vcc
	v_cndmask_b32_e64 v235, 0, v235, s[8:9]
	v_fma_f32 v240, v229, v132, v156
	v_fma_f32 v241, v231, v133, v157
	v_fma_f32 v242, v233, v134, v158
	v_fma_f32 v243, v235, v135, v159
	v_fmac_f32_e32 v240, v228, v140
	v_fmac_f32_e32 v241, v230, v141
	v_fmac_f32_e32 v242, v232, v142
	v_fmac_f32_e32 v243, v234, v143
	v_fmac_f32_e32 v240, v100, v148
	v_fmac_f32_e32 v241, v101, v149
	v_fmac_f32_e32 v242, v102, v150
	v_fmac_f32_e32 v243, v103, v151
	v_mov_b32_e32 v228, 0xbdd2d3e8
	v_mul_f32_e32 v244, v236, v236
	v_mul_f32_e32 v245, v237, v237
	v_mul_f32_e32 v246, v238, v238
	v_mul_f32_e32 v247, v239, v239
	v_fmaak_f32 v244, v244, v228, 0xc0135761
	v_fmaak_f32 v245, v245, v228, 0xc0135761
	v_fmaak_f32 v246, v246, v228, 0xc0135761
	v_fmaak_f32 v247, v247, v228, 0xc0135761
	v_mul_f32_e32 v244, v236, v244
	v_mul_f32_e32 v245, v237, v245
	v_mul_f32_e32 v246, v238, v246
	v_mul_f32_e32 v247, v239, v247
	v_exp_f32_e32 v244, v244
	v_exp_f32_e32 v245, v245
	v_exp_f32_e32 v246, v246
	v_exp_f32_e32 v247, v247
	v_add_f32_e32 v244, 1.0, v244
	v_add_f32_e32 v245, 1.0, v245
	v_add_f32_e32 v246, 1.0, v246
	v_add_f32_e32 v247, 1.0, v247
	v_rcp_f32_e32 v244, v244
	v_rcp_f32_e32 v245, v245
	v_rcp_f32_e32 v246, v246
	v_rcp_f32_e32 v247, v247
	v_mul_f32_e32 v244, v236, v244
	v_mul_f32_e32 v245, v237, v245
	v_mul_f32_e32 v246, v238, v246
	v_mul_f32_e32 v247, v239, v247
	v_mul_f32_e32 v248, v240, v244
	v_mul_f32_e32 v249, v241, v245
	v_mul_f32_e32 v250, v242, v246
	v_mul_f32_e32 v251, v243, v247
	v_cvt_pk_bf16_f32 v210, v248, v249
	v_cvt_pk_bf16_f32 v211, v250, v251
	s_branch .Lffn1e_join0_1
.Lffn1e_old0_1:
	v_mov_b32_dpp v228, v124 row_ror:1 row_mask:0xf bank_mask:0xf
	v_mov_b32_dpp v229, v124 row_ror:2 row_mask:0xf bank_mask:0xf
	v_mov_b32_dpp v230, v125 row_ror:1 row_mask:0xf bank_mask:0xf
	v_mov_b32_dpp v231, v125 row_ror:2 row_mask:0xf bank_mask:0xf
	v_mov_b32_dpp v232, v126 row_ror:1 row_mask:0xf bank_mask:0xf
	v_mov_b32_dpp v233, v126 row_ror:2 row_mask:0xf bank_mask:0xf
	v_mov_b32_dpp v234, v127 row_ror:1 row_mask:0xf bank_mask:0xf
	v_mov_b32_dpp v235, v127 row_ror:2 row_mask:0xf bank_mask:0xf
	v_mov_b32_dpp v228, v108 row_shr:1 row_mask:0xf bank_mask:0xf
	v_mov_b32_dpp v229, v108 row_shr:2 row_mask:0xf bank_mask:0xf
	v_mov_b32_dpp v230, v109 row_shr:1 row_mask:0xf bank_mask:0xf
	v_mov_b32_dpp v231, v109 row_shr:2 row_mask:0xf bank_mask:0xf
	v_mov_b32_dpp v232, v110 row_shr:1 row_mask:0xf bank_mask:0xf
	v_mov_b32_dpp v233, v110 row_shr:2 row_mask:0xf bank_mask:0xf
	v_mov_b32_dpp v234, v111 row_shr:1 row_mask:0xf bank_mask:0xf
	v_mov_b32_dpp v235, v111 row_shr:2 row_mask:0xf bank_mask:0xf
	v_fma_f32 v236, v229, v128, v152
	v_fma_f32 v237, v231, v129, v153
	v_fma_f32 v238, v233, v130, v154
	v_fma_f32 v239, v235, v131, v155
	v_fmac_f32_e32 v236, v228, v136
	v_fmac_f32_e32 v237, v230, v137
	v_fmac_f32_e32 v238, v232, v138
	v_fmac_f32_e32 v239, v234, v139
	v_fmac_f32_e32 v236, v108, v144
	v_fmac_f32_e32 v237, v109, v145
	v_fmac_f32_e32 v238, v110, v146
	v_fmac_f32_e32 v239, v111, v147
	v_mov_b32_dpp v228, v116 row_ror:1 row_mask:0xf bank_mask:0xf
	v_mov_b32_dpp v229, v116 row_ror:2 row_mask:0xf bank_mask:0xf
	v_mov_b32_dpp v230, v117 row_ror:1 row_mask:0xf bank_mask:0xf
	v_mov_b32_dpp v231, v117 row_ror:2 row_mask:0xf bank_mask:0xf
	v_mov_b32_dpp v232, v118 row_ror:1 row_mask:0xf bank_mask:0xf
	v_mov_b32_dpp v233, v118 row_ror:2 row_mask:0xf bank_mask:0xf
	v_mov_b32_dpp v234, v119 row_ror:1 row_mask:0xf bank_mask:0xf
	v_mov_b32_dpp v235, v119 row_ror:2 row_mask:0xf bank_mask:0xf
	v_mov_b32_dpp v228, v100 row_shr:1 row_mask:0xf bank_mask:0xf
	v_mov_b32_dpp v229, v100 row_shr:2 row_mask:0xf bank_mask:0xf
	v_mov_b32_dpp v230, v101 row_shr:1 row_mask:0xf bank_mask:0xf
	v_mov_b32_dpp v231, v101 row_shr:2 row_mask:0xf bank_mask:0xf
	v_mov_b32_dpp v232, v102 row_shr:1 row_mask:0xf bank_mask:0xf
	v_mov_b32_dpp v233, v102 row_shr:2 row_mask:0xf bank_mask:0xf
	v_mov_b32_dpp v234, v103 row_shr:1 row_mask:0xf bank_mask:0xf
	v_mov_b32_dpp v235, v103 row_shr:2 row_mask:0xf bank_mask:0xf
	v_fma_f32 v240, v229, v132, v156
	v_fma_f32 v241, v231, v133, v157
	v_fma_f32 v242, v233, v134, v158
	v_fma_f32 v243, v235, v135, v159
	v_fmac_f32_e32 v240, v228, v140
	v_fmac_f32_e32 v241, v230, v141
	v_fmac_f32_e32 v242, v232, v142
	v_fmac_f32_e32 v243, v234, v143
	v_fmac_f32_e32 v240, v100, v148
	v_fmac_f32_e32 v241, v101, v149
	v_fmac_f32_e32 v242, v102, v150
	v_fmac_f32_e32 v243, v103, v151
	v_mov_b32_e32 v228, 0xbdd2d3e8
	v_mul_f32_e32 v244, v236, v236
	v_mul_f32_e32 v245, v237, v237
	v_mul_f32_e32 v246, v238, v238
	v_mul_f32_e32 v247, v239, v239
	v_fmaak_f32 v244, v244, v228, 0xc0135761
	v_fmaak_f32 v245, v245, v228, 0xc0135761
	v_fmaak_f32 v246, v246, v228, 0xc0135761
	v_fmaak_f32 v247, v247, v228, 0xc0135761
	v_mul_f32_e32 v244, v236, v244
	v_mul_f32_e32 v245, v237, v245
	v_mul_f32_e32 v246, v238, v246
	v_mul_f32_e32 v247, v239, v247
	v_exp_f32_e32 v244, v244
	v_exp_f32_e32 v245, v245
	v_exp_f32_e32 v246, v246
	v_exp_f32_e32 v247, v247
	v_add_f32_e32 v244, 1.0, v244
	v_add_f32_e32 v245, 1.0, v245
	v_add_f32_e32 v246, 1.0, v246
	v_add_f32_e32 v247, 1.0, v247
	v_rcp_f32_e32 v244, v244
	v_rcp_f32_e32 v245, v245
	v_rcp_f32_e32 v246, v246
	v_rcp_f32_e32 v247, v247
	v_mul_f32_e32 v244, v236, v244
	v_mul_f32_e32 v245, v237, v245
	v_mul_f32_e32 v246, v238, v246
	v_mul_f32_e32 v247, v239, v247
	v_mul_f32_e32 v248, v240, v244
	v_mul_f32_e32 v249, v241, v245
	v_mul_f32_e32 v250, v242, v246
	v_mul_f32_e32 v251, v243, v247
	v_cvt_pk_bf16_f32 v210, v248, v249
	v_cvt_pk_bf16_f32 v211, v250, v251
	s_branch .Lffn1e_join0_1
.Lffn1e_slow0_2:
	v_add_u32_e32 v189, 2096, v218
	v_mul_hi_u32 v203, v189, s59
	v_lshrrev_b32_e32 v203, 7, v203
	v_mul_u32_u24_e32 v203, 0x810, v203
	v_sub_u32_e32 v189, v189, v203
	v_cmp_lt_u32_e32 vcc, 0, v189
	v_cmp_lt_u32_e64 s[8:9], 1, v189
	s_nop 1
	v_mov_b32_dpp v228, v108 row_ror:1 row_mask:0xf bank_mask:0xf
	v_mov_b32_dpp v229, v108 row_ror:2 row_mask:0xf bank_mask:0xf
	v_mov_b32_dpp v230, v109 row_ror:1 row_mask:0xf bank_mask:0xf
	v_mov_b32_dpp v231, v109 row_ror:2 row_mask:0xf bank_mask:0xf
	v_mov_b32_dpp v232, v110 row_ror:1 row_mask:0xf bank_mask:0xf
	v_mov_b32_dpp v233, v110 row_ror:2 row_mask:0xf bank_mask:0xf
	v_mov_b32_dpp v234, v111 row_ror:1 row_mask:0xf bank_mask:0xf
	v_mov_b32_dpp v235, v111 row_ror:2 row_mask:0xf bank_mask:0xf
	v_mov_b32_dpp v228, v92 row_shr:1 row_mask:0xf bank_mask:0xf
	v_mov_b32_dpp v229, v92 row_shr:2 row_mask:0xf bank_mask:0xf
	v_mov_b32_dpp v230, v93 row_shr:1 row_mask:0xf bank_mask:0xf
	v_mov_b32_dpp v231, v93 row_shr:2 row_mask:0xf bank_mask:0xf
	v_mov_b32_dpp v232, v94 row_shr:1 row_mask:0xf bank_mask:0xf
	v_mov_b32_dpp v233, v94 row_shr:2 row_mask:0xf bank_mask:0xf
	v_mov_b32_dpp v234, v95 row_shr:1 row_mask:0xf bank_mask:0xf
	v_mov_b32_dpp v235, v95 row_shr:2 row_mask:0xf bank_mask:0xf
	v_cndmask_b32_e64 v228, 0, v228, vcc
	v_cndmask_b32_e64 v229, 0, v229, s[8:9]
	v_cndmask_b32_e64 v230, 0, v230, vcc
	v_cndmask_b32_e64 v231, 0, v231, s[8:9]
	v_cndmask_b32_e64 v232, 0, v232, vcc
	v_cndmask_b32_e64 v233, 0, v233, s[8:9]
	v_cndmask_b32_e64 v234, 0, v234, vcc
	v_cndmask_b32_e64 v235, 0, v235, s[8:9]
	v_fma_f32 v236, v229, v128, v152
	v_fma_f32 v237, v231, v129, v153
	v_fma_f32 v238, v233, v130, v154
	v_fma_f32 v239, v235, v131, v155
	v_fmac_f32_e32 v236, v228, v136
	v_fmac_f32_e32 v237, v230, v137
	v_fmac_f32_e32 v238, v232, v138
	v_fmac_f32_e32 v239, v234, v139
	v_fmac_f32_e32 v236, v92, v144
	v_fmac_f32_e32 v237, v93, v145
	v_fmac_f32_e32 v238, v94, v146
	v_fmac_f32_e32 v239, v95, v147
	v_mov_b32_dpp v228, v100 row_ror:1 row_mask:0xf bank_mask:0xf
	v_mov_b32_dpp v229, v100 row_ror:2 row_mask:0xf bank_mask:0xf
	v_mov_b32_dpp v230, v101 row_ror:1 row_mask:0xf bank_mask:0xf
	v_mov_b32_dpp v231, v101 row_ror:2 row_mask:0xf bank_mask:0xf
	v_mov_b32_dpp v232, v102 row_ror:1 row_mask:0xf bank_mask:0xf
	v_mov_b32_dpp v233, v102 row_ror:2 row_mask:0xf bank_mask:0xf
	v_mov_b32_dpp v234, v103 row_ror:1 row_mask:0xf bank_mask:0xf
	v_mov_b32_dpp v235, v103 row_ror:2 row_mask:0xf bank_mask:0xf
	v_mov_b32_dpp v228, v84 row_shr:1 row_mask:0xf bank_mask:0xf
	v_mov_b32_dpp v229, v84 row_shr:2 row_mask:0xf bank_mask:0xf
	v_mov_b32_dpp v230, v85 row_shr:1 row_mask:0xf bank_mask:0xf
	v_mov_b32_dpp v231, v85 row_shr:2 row_mask:0xf bank_mask:0xf
	v_mov_b32_dpp v232, v86 row_shr:1 row_mask:0xf bank_mask:0xf
	v_mov_b32_dpp v233, v86 row_shr:2 row_mask:0xf bank_mask:0xf
	v_mov_b32_dpp v234, v87 row_shr:1 row_mask:0xf bank_mask:0xf
	v_mov_b32_dpp v235, v87 row_shr:2 row_mask:0xf bank_mask:0xf
	v_cndmask_b32_e64 v228, 0, v228, vcc
	v_cndmask_b32_e64 v229, 0, v229, s[8:9]
	v_cndmask_b32_e64 v230, 0, v230, vcc
	v_cndmask_b32_e64 v231, 0, v231, s[8:9]
	v_cndmask_b32_e64 v232, 0, v232, vcc
	v_cndmask_b32_e64 v233, 0, v233, s[8:9]
	v_cndmask_b32_e64 v234, 0, v234, vcc
	v_cndmask_b32_e64 v235, 0, v235, s[8:9]
	v_fma_f32 v240, v229, v132, v156
	v_fma_f32 v241, v231, v133, v157
	v_fma_f32 v242, v233, v134, v158
	v_fma_f32 v243, v235, v135, v159
	v_fmac_f32_e32 v240, v228, v140
	v_fmac_f32_e32 v241, v230, v141
	v_fmac_f32_e32 v242, v232, v142
	v_fmac_f32_e32 v243, v234, v143
	v_fmac_f32_e32 v240, v84, v148
	v_fmac_f32_e32 v241, v85, v149
	v_fmac_f32_e32 v242, v86, v150
	v_fmac_f32_e32 v243, v87, v151
	v_mov_b32_e32 v228, 0xbdd2d3e8
	v_mul_f32_e32 v244, v236, v236
	v_mul_f32_e32 v245, v237, v237
	v_mul_f32_e32 v246, v238, v238
	v_mul_f32_e32 v247, v239, v239
	v_fmaak_f32 v244, v244, v228, 0xc0135761
	v_fmaak_f32 v245, v245, v228, 0xc0135761
	v_fmaak_f32 v246, v246, v228, 0xc0135761
	v_fmaak_f32 v247, v247, v228, 0xc0135761
	v_mul_f32_e32 v244, v236, v244
	v_mul_f32_e32 v245, v237, v245
	v_mul_f32_e32 v246, v238, v246
	v_mul_f32_e32 v247, v239, v247
	v_exp_f32_e32 v244, v244
	v_exp_f32_e32 v245, v245
	v_exp_f32_e32 v246, v246
	v_exp_f32_e32 v247, v247
	v_add_f32_e32 v244, 1.0, v244
	v_add_f32_e32 v245, 1.0, v245
	v_add_f32_e32 v246, 1.0, v246
	v_add_f32_e32 v247, 1.0, v247
	v_rcp_f32_e32 v244, v244
	v_rcp_f32_e32 v245, v245
	v_rcp_f32_e32 v246, v246
	v_rcp_f32_e32 v247, v247
	v_mul_f32_e32 v244, v236, v244
	v_mul_f32_e32 v245, v237, v245
	v_mul_f32_e32 v246, v238, v246
	v_mul_f32_e32 v247, v239, v247
	v_mul_f32_e32 v248, v240, v244
	v_mul_f32_e32 v249, v241, v245
	v_mul_f32_e32 v250, v242, v246
	v_mul_f32_e32 v251, v243, v247
	v_cvt_pk_bf16_f32 v212, v248, v249
	v_cvt_pk_bf16_f32 v213, v250, v251
	s_branch .Lffn1e_join0_2
.Lffn1e_old0_2:
	v_mov_b32_dpp v228, v108 row_ror:1 row_mask:0xf bank_mask:0xf
	v_mov_b32_dpp v229, v108 row_ror:2 row_mask:0xf bank_mask:0xf
	v_mov_b32_dpp v230, v109 row_ror:1 row_mask:0xf bank_mask:0xf
	v_mov_b32_dpp v231, v109 row_ror:2 row_mask:0xf bank_mask:0xf
	v_mov_b32_dpp v232, v110 row_ror:1 row_mask:0xf bank_mask:0xf
	v_mov_b32_dpp v233, v110 row_ror:2 row_mask:0xf bank_mask:0xf
	v_mov_b32_dpp v234, v111 row_ror:1 row_mask:0xf bank_mask:0xf
	v_mov_b32_dpp v235, v111 row_ror:2 row_mask:0xf bank_mask:0xf
	v_mov_b32_dpp v228, v92 row_shr:1 row_mask:0xf bank_mask:0xf
	v_mov_b32_dpp v229, v92 row_shr:2 row_mask:0xf bank_mask:0xf
	v_mov_b32_dpp v230, v93 row_shr:1 row_mask:0xf bank_mask:0xf
	v_mov_b32_dpp v231, v93 row_shr:2 row_mask:0xf bank_mask:0xf
	v_mov_b32_dpp v232, v94 row_shr:1 row_mask:0xf bank_mask:0xf
	v_mov_b32_dpp v233, v94 row_shr:2 row_mask:0xf bank_mask:0xf
	v_mov_b32_dpp v234, v95 row_shr:1 row_mask:0xf bank_mask:0xf
	v_mov_b32_dpp v235, v95 row_shr:2 row_mask:0xf bank_mask:0xf
	v_fma_f32 v236, v229, v128, v152
	v_fma_f32 v237, v231, v129, v153
	v_fma_f32 v238, v233, v130, v154
	v_fma_f32 v239, v235, v131, v155
	v_fmac_f32_e32 v236, v228, v136
	v_fmac_f32_e32 v237, v230, v137
	v_fmac_f32_e32 v238, v232, v138
	v_fmac_f32_e32 v239, v234, v139
	v_fmac_f32_e32 v236, v92, v144
	v_fmac_f32_e32 v237, v93, v145
	v_fmac_f32_e32 v238, v94, v146
	v_fmac_f32_e32 v239, v95, v147
	v_mov_b32_dpp v228, v100 row_ror:1 row_mask:0xf bank_mask:0xf
	v_mov_b32_dpp v229, v100 row_ror:2 row_mask:0xf bank_mask:0xf
	v_mov_b32_dpp v230, v101 row_ror:1 row_mask:0xf bank_mask:0xf
	v_mov_b32_dpp v231, v101 row_ror:2 row_mask:0xf bank_mask:0xf
	v_mov_b32_dpp v232, v102 row_ror:1 row_mask:0xf bank_mask:0xf
	v_mov_b32_dpp v233, v102 row_ror:2 row_mask:0xf bank_mask:0xf
	v_mov_b32_dpp v234, v103 row_ror:1 row_mask:0xf bank_mask:0xf
	v_mov_b32_dpp v235, v103 row_ror:2 row_mask:0xf bank_mask:0xf
	v_mov_b32_dpp v228, v84 row_shr:1 row_mask:0xf bank_mask:0xf
	v_mov_b32_dpp v229, v84 row_shr:2 row_mask:0xf bank_mask:0xf
	v_mov_b32_dpp v230, v85 row_shr:1 row_mask:0xf bank_mask:0xf
	v_mov_b32_dpp v231, v85 row_shr:2 row_mask:0xf bank_mask:0xf
	v_mov_b32_dpp v232, v86 row_shr:1 row_mask:0xf bank_mask:0xf
	v_mov_b32_dpp v233, v86 row_shr:2 row_mask:0xf bank_mask:0xf
	v_mov_b32_dpp v234, v87 row_shr:1 row_mask:0xf bank_mask:0xf
	v_mov_b32_dpp v235, v87 row_shr:2 row_mask:0xf bank_mask:0xf
	v_fma_f32 v240, v229, v132, v156
	v_fma_f32 v241, v231, v133, v157
	v_fma_f32 v242, v233, v134, v158
	v_fma_f32 v243, v235, v135, v159
	v_fmac_f32_e32 v240, v228, v140
	v_fmac_f32_e32 v241, v230, v141
	v_fmac_f32_e32 v242, v232, v142
	v_fmac_f32_e32 v243, v234, v143
	v_fmac_f32_e32 v240, v84, v148
	v_fmac_f32_e32 v241, v85, v149
	v_fmac_f32_e32 v242, v86, v150
	v_fmac_f32_e32 v243, v87, v151
	v_mov_b32_e32 v228, 0xbdd2d3e8
	v_mul_f32_e32 v244, v236, v236
	v_mul_f32_e32 v245, v237, v237
	v_mul_f32_e32 v246, v238, v238
	v_mul_f32_e32 v247, v239, v239
	v_fmaak_f32 v244, v244, v228, 0xc0135761
	v_fmaak_f32 v245, v245, v228, 0xc0135761
	v_fmaak_f32 v246, v246, v228, 0xc0135761
	v_fmaak_f32 v247, v247, v228, 0xc0135761
	v_mul_f32_e32 v244, v236, v244
	v_mul_f32_e32 v245, v237, v245
	v_mul_f32_e32 v246, v238, v246
	v_mul_f32_e32 v247, v239, v247
	v_exp_f32_e32 v244, v244
	v_exp_f32_e32 v245, v245
	v_exp_f32_e32 v246, v246
	v_exp_f32_e32 v247, v247
	v_add_f32_e32 v244, 1.0, v244
	v_add_f32_e32 v245, 1.0, v245
	v_add_f32_e32 v246, 1.0, v246
	v_add_f32_e32 v247, 1.0, v247
	v_rcp_f32_e32 v244, v244
	v_rcp_f32_e32 v245, v245
	v_rcp_f32_e32 v246, v246
	v_rcp_f32_e32 v247, v247
	v_mul_f32_e32 v244, v236, v244
	v_mul_f32_e32 v245, v237, v245
	v_mul_f32_e32 v246, v238, v246
	v_mul_f32_e32 v247, v239, v247
	v_mul_f32_e32 v248, v240, v244
	v_mul_f32_e32 v249, v241, v245
	v_mul_f32_e32 v250, v242, v246
	v_mul_f32_e32 v251, v243, v247
	v_cvt_pk_bf16_f32 v212, v248, v249
	v_cvt_pk_bf16_f32 v213, v250, v251
	s_branch .Lffn1e_join0_2
.Lffn1e_slow0_3:
	v_add_u32_e32 v189, 2112, v218
	v_mul_hi_u32 v203, v189, s59
	v_lshrrev_b32_e32 v203, 7, v203
	v_mul_u32_u24_e32 v203, 0x810, v203
	v_sub_u32_e32 v189, v189, v203
	v_cmp_lt_u32_e32 vcc, 0, v189
	v_cmp_lt_u32_e64 s[8:9], 1, v189
	s_nop 1
	v_mov_b32_dpp v228, v92 row_ror:1 row_mask:0xf bank_mask:0xf
	v_mov_b32_dpp v229, v92 row_ror:2 row_mask:0xf bank_mask:0xf
	v_mov_b32_dpp v230, v93 row_ror:1 row_mask:0xf bank_mask:0xf
	v_mov_b32_dpp v231, v93 row_ror:2 row_mask:0xf bank_mask:0xf
	v_mov_b32_dpp v232, v94 row_ror:1 row_mask:0xf bank_mask:0xf
	v_mov_b32_dpp v233, v94 row_ror:2 row_mask:0xf bank_mask:0xf
	v_mov_b32_dpp v234, v95 row_ror:1 row_mask:0xf bank_mask:0xf
	v_mov_b32_dpp v235, v95 row_ror:2 row_mask:0xf bank_mask:0xf
	v_mov_b32_dpp v228, v76 row_shr:1 row_mask:0xf bank_mask:0xf
	v_mov_b32_dpp v229, v76 row_shr:2 row_mask:0xf bank_mask:0xf
	v_mov_b32_dpp v230, v77 row_shr:1 row_mask:0xf bank_mask:0xf
	v_mov_b32_dpp v231, v77 row_shr:2 row_mask:0xf bank_mask:0xf
	v_mov_b32_dpp v232, v78 row_shr:1 row_mask:0xf bank_mask:0xf
	v_mov_b32_dpp v233, v78 row_shr:2 row_mask:0xf bank_mask:0xf
	v_mov_b32_dpp v234, v79 row_shr:1 row_mask:0xf bank_mask:0xf
	v_mov_b32_dpp v235, v79 row_shr:2 row_mask:0xf bank_mask:0xf
	v_cndmask_b32_e64 v228, 0, v228, vcc
	v_cndmask_b32_e64 v229, 0, v229, s[8:9]
	v_cndmask_b32_e64 v230, 0, v230, vcc
	v_cndmask_b32_e64 v231, 0, v231, s[8:9]
	v_cndmask_b32_e64 v232, 0, v232, vcc
	v_cndmask_b32_e64 v233, 0, v233, s[8:9]
	v_cndmask_b32_e64 v234, 0, v234, vcc
	v_cndmask_b32_e64 v235, 0, v235, s[8:9]
	v_fma_f32 v236, v229, v128, v152
	v_fma_f32 v237, v231, v129, v153
	v_fma_f32 v238, v233, v130, v154
	v_fma_f32 v239, v235, v131, v155
	v_fmac_f32_e32 v236, v228, v136
	v_fmac_f32_e32 v237, v230, v137
	v_fmac_f32_e32 v238, v232, v138
	v_fmac_f32_e32 v239, v234, v139
	v_fmac_f32_e32 v236, v76, v144
	v_fmac_f32_e32 v237, v77, v145
	v_fmac_f32_e32 v238, v78, v146
	v_fmac_f32_e32 v239, v79, v147
	v_mov_b32_dpp v228, v84 row_ror:1 row_mask:0xf bank_mask:0xf
	v_mov_b32_dpp v229, v84 row_ror:2 row_mask:0xf bank_mask:0xf
	v_mov_b32_dpp v230, v85 row_ror:1 row_mask:0xf bank_mask:0xf
	v_mov_b32_dpp v231, v85 row_ror:2 row_mask:0xf bank_mask:0xf
	v_mov_b32_dpp v232, v86 row_ror:1 row_mask:0xf bank_mask:0xf
	v_mov_b32_dpp v233, v86 row_ror:2 row_mask:0xf bank_mask:0xf
	v_mov_b32_dpp v234, v87 row_ror:1 row_mask:0xf bank_mask:0xf
	v_mov_b32_dpp v235, v87 row_ror:2 row_mask:0xf bank_mask:0xf
	v_mov_b32_dpp v228, v68 row_shr:1 row_mask:0xf bank_mask:0xf
	v_mov_b32_dpp v229, v68 row_shr:2 row_mask:0xf bank_mask:0xf
	v_mov_b32_dpp v230, v69 row_shr:1 row_mask:0xf bank_mask:0xf
	v_mov_b32_dpp v231, v69 row_shr:2 row_mask:0xf bank_mask:0xf
	v_mov_b32_dpp v232, v70 row_shr:1 row_mask:0xf bank_mask:0xf
	v_mov_b32_dpp v233, v70 row_shr:2 row_mask:0xf bank_mask:0xf
	v_mov_b32_dpp v234, v71 row_shr:1 row_mask:0xf bank_mask:0xf
	v_mov_b32_dpp v235, v71 row_shr:2 row_mask:0xf bank_mask:0xf
	v_cndmask_b32_e64 v228, 0, v228, vcc
	v_cndmask_b32_e64 v229, 0, v229, s[8:9]
	v_cndmask_b32_e64 v230, 0, v230, vcc
	v_cndmask_b32_e64 v231, 0, v231, s[8:9]
	v_cndmask_b32_e64 v232, 0, v232, vcc
	v_cndmask_b32_e64 v233, 0, v233, s[8:9]
	v_cndmask_b32_e64 v234, 0, v234, vcc
	v_cndmask_b32_e64 v235, 0, v235, s[8:9]
	v_fma_f32 v240, v229, v132, v156
	v_fma_f32 v241, v231, v133, v157
	v_fma_f32 v242, v233, v134, v158
	v_fma_f32 v243, v235, v135, v159
	v_fmac_f32_e32 v240, v228, v140
	v_fmac_f32_e32 v241, v230, v141
	v_fmac_f32_e32 v242, v232, v142
	v_fmac_f32_e32 v243, v234, v143
	v_fmac_f32_e32 v240, v68, v148
	v_fmac_f32_e32 v241, v69, v149
	v_fmac_f32_e32 v242, v70, v150
	v_fmac_f32_e32 v243, v71, v151
	v_mov_b32_e32 v228, 0xbdd2d3e8
	v_mul_f32_e32 v244, v236, v236
	v_mul_f32_e32 v245, v237, v237
	v_mul_f32_e32 v246, v238, v238
	v_mul_f32_e32 v247, v239, v239
	v_fmaak_f32 v244, v244, v228, 0xc0135761
	v_fmaak_f32 v245, v245, v228, 0xc0135761
	v_fmaak_f32 v246, v246, v228, 0xc0135761
	v_fmaak_f32 v247, v247, v228, 0xc0135761
	v_mul_f32_e32 v244, v236, v244
	v_mul_f32_e32 v245, v237, v245
	v_mul_f32_e32 v246, v238, v246
	v_mul_f32_e32 v247, v239, v247
	v_exp_f32_e32 v244, v244
	v_exp_f32_e32 v245, v245
	v_exp_f32_e32 v246, v246
	v_exp_f32_e32 v247, v247
	v_add_f32_e32 v244, 1.0, v244
	v_add_f32_e32 v245, 1.0, v245
	v_add_f32_e32 v246, 1.0, v246
	v_add_f32_e32 v247, 1.0, v247
	v_rcp_f32_e32 v244, v244
	v_rcp_f32_e32 v245, v245
	v_rcp_f32_e32 v246, v246
	v_rcp_f32_e32 v247, v247
	v_mul_f32_e32 v244, v236, v244
	v_mul_f32_e32 v245, v237, v245
	v_mul_f32_e32 v246, v238, v246
	v_mul_f32_e32 v247, v239, v247
	v_mul_f32_e32 v248, v240, v244
	v_mul_f32_e32 v249, v241, v245
	v_mul_f32_e32 v250, v242, v246
	v_mul_f32_e32 v251, v243, v247
	v_cvt_pk_bf16_f32 v214, v248, v249
	v_cvt_pk_bf16_f32 v215, v250, v251
	s_branch .Lffn1e_join0_3
.Lffn1e_old0_3:
	v_mov_b32_dpp v228, v92 row_ror:1 row_mask:0xf bank_mask:0xf
	v_mov_b32_dpp v229, v92 row_ror:2 row_mask:0xf bank_mask:0xf
	v_mov_b32_dpp v230, v93 row_ror:1 row_mask:0xf bank_mask:0xf
	v_mov_b32_dpp v231, v93 row_ror:2 row_mask:0xf bank_mask:0xf
	v_mov_b32_dpp v232, v94 row_ror:1 row_mask:0xf bank_mask:0xf
	v_mov_b32_dpp v233, v94 row_ror:2 row_mask:0xf bank_mask:0xf
	v_mov_b32_dpp v234, v95 row_ror:1 row_mask:0xf bank_mask:0xf
	v_mov_b32_dpp v235, v95 row_ror:2 row_mask:0xf bank_mask:0xf
	v_mov_b32_dpp v228, v76 row_shr:1 row_mask:0xf bank_mask:0xf
	v_mov_b32_dpp v229, v76 row_shr:2 row_mask:0xf bank_mask:0xf
	v_mov_b32_dpp v230, v77 row_shr:1 row_mask:0xf bank_mask:0xf
	v_mov_b32_dpp v231, v77 row_shr:2 row_mask:0xf bank_mask:0xf
	v_mov_b32_dpp v232, v78 row_shr:1 row_mask:0xf bank_mask:0xf
	v_mov_b32_dpp v233, v78 row_shr:2 row_mask:0xf bank_mask:0xf
	v_mov_b32_dpp v234, v79 row_shr:1 row_mask:0xf bank_mask:0xf
	v_mov_b32_dpp v235, v79 row_shr:2 row_mask:0xf bank_mask:0xf
	v_fma_f32 v236, v229, v128, v152
	v_fma_f32 v237, v231, v129, v153
	v_fma_f32 v238, v233, v130, v154
	v_fma_f32 v239, v235, v131, v155
	v_fmac_f32_e32 v236, v228, v136
	v_fmac_f32_e32 v237, v230, v137
	v_fmac_f32_e32 v238, v232, v138
	v_fmac_f32_e32 v239, v234, v139
	v_fmac_f32_e32 v236, v76, v144
	v_fmac_f32_e32 v237, v77, v145
	v_fmac_f32_e32 v238, v78, v146
	v_fmac_f32_e32 v239, v79, v147
	v_mov_b32_dpp v228, v84 row_ror:1 row_mask:0xf bank_mask:0xf
	v_mov_b32_dpp v229, v84 row_ror:2 row_mask:0xf bank_mask:0xf
	v_mov_b32_dpp v230, v85 row_ror:1 row_mask:0xf bank_mask:0xf
	v_mov_b32_dpp v231, v85 row_ror:2 row_mask:0xf bank_mask:0xf
	v_mov_b32_dpp v232, v86 row_ror:1 row_mask:0xf bank_mask:0xf
	v_mov_b32_dpp v233, v86 row_ror:2 row_mask:0xf bank_mask:0xf
	v_mov_b32_dpp v234, v87 row_ror:1 row_mask:0xf bank_mask:0xf
	v_mov_b32_dpp v235, v87 row_ror:2 row_mask:0xf bank_mask:0xf
	v_mov_b32_dpp v228, v68 row_shr:1 row_mask:0xf bank_mask:0xf
	v_mov_b32_dpp v229, v68 row_shr:2 row_mask:0xf bank_mask:0xf
	v_mov_b32_dpp v230, v69 row_shr:1 row_mask:0xf bank_mask:0xf
	v_mov_b32_dpp v231, v69 row_shr:2 row_mask:0xf bank_mask:0xf
	v_mov_b32_dpp v232, v70 row_shr:1 row_mask:0xf bank_mask:0xf
	v_mov_b32_dpp v233, v70 row_shr:2 row_mask:0xf bank_mask:0xf
	v_mov_b32_dpp v234, v71 row_shr:1 row_mask:0xf bank_mask:0xf
	v_mov_b32_dpp v235, v71 row_shr:2 row_mask:0xf bank_mask:0xf
	v_fma_f32 v240, v229, v132, v156
	v_fma_f32 v241, v231, v133, v157
	v_fma_f32 v242, v233, v134, v158
	v_fma_f32 v243, v235, v135, v159
	v_fmac_f32_e32 v240, v228, v140
	v_fmac_f32_e32 v241, v230, v141
	v_fmac_f32_e32 v242, v232, v142
	v_fmac_f32_e32 v243, v234, v143
	v_fmac_f32_e32 v240, v68, v148
	v_fmac_f32_e32 v241, v69, v149
	v_fmac_f32_e32 v242, v70, v150
	v_fmac_f32_e32 v243, v71, v151
	v_mov_b32_e32 v228, 0xbdd2d3e8
	v_mul_f32_e32 v244, v236, v236
	v_mul_f32_e32 v245, v237, v237
	v_mul_f32_e32 v246, v238, v238
	v_mul_f32_e32 v247, v239, v239
	v_fmaak_f32 v244, v244, v228, 0xc0135761
	v_fmaak_f32 v245, v245, v228, 0xc0135761
	v_fmaak_f32 v246, v246, v228, 0xc0135761
	v_fmaak_f32 v247, v247, v228, 0xc0135761
	v_mul_f32_e32 v244, v236, v244
	v_mul_f32_e32 v245, v237, v245
	v_mul_f32_e32 v246, v238, v246
	v_mul_f32_e32 v247, v239, v247
	v_exp_f32_e32 v244, v244
	v_exp_f32_e32 v245, v245
	v_exp_f32_e32 v246, v246
	v_exp_f32_e32 v247, v247
	v_add_f32_e32 v244, 1.0, v244
	v_add_f32_e32 v245, 1.0, v245
	v_add_f32_e32 v246, 1.0, v246
	v_add_f32_e32 v247, 1.0, v247
	v_rcp_f32_e32 v244, v244
	v_rcp_f32_e32 v245, v245
	v_rcp_f32_e32 v246, v246
	v_rcp_f32_e32 v247, v247
	v_mul_f32_e32 v244, v236, v244
	v_mul_f32_e32 v245, v237, v245
	v_mul_f32_e32 v246, v238, v246
	v_mul_f32_e32 v247, v239, v247
	v_mul_f32_e32 v248, v240, v244
	v_mul_f32_e32 v249, v241, v245
	v_mul_f32_e32 v250, v242, v246
	v_mul_f32_e32 v251, v243, v247
	v_cvt_pk_bf16_f32 v214, v248, v249
	v_cvt_pk_bf16_f32 v215, v250, v251
	s_branch .Lffn1e_join0_3
.Lffn1e_slow0_4:
	v_add_u32_e32 v189, 2128, v218
	v_mul_hi_u32 v203, v189, s59
	v_lshrrev_b32_e32 v203, 7, v203
	v_mul_u32_u24_e32 v203, 0x810, v203
	v_sub_u32_e32 v189, v189, v203
	v_cmp_lt_u32_e32 vcc, 0, v189
	v_cmp_lt_u32_e64 s[8:9], 1, v189
	s_nop 1
	v_mov_b32_dpp v228, v76 row_ror:1 row_mask:0xf bank_mask:0xf
	v_mov_b32_dpp v229, v76 row_ror:2 row_mask:0xf bank_mask:0xf
	v_mov_b32_dpp v230, v77 row_ror:1 row_mask:0xf bank_mask:0xf
	v_mov_b32_dpp v231, v77 row_ror:2 row_mask:0xf bank_mask:0xf
	v_mov_b32_dpp v232, v78 row_ror:1 row_mask:0xf bank_mask:0xf
	v_mov_b32_dpp v233, v78 row_ror:2 row_mask:0xf bank_mask:0xf
	v_mov_b32_dpp v234, v79 row_ror:1 row_mask:0xf bank_mask:0xf
	v_mov_b32_dpp v235, v79 row_ror:2 row_mask:0xf bank_mask:0xf
	v_mov_b32_dpp v228, v60 row_shr:1 row_mask:0xf bank_mask:0xf
	v_mov_b32_dpp v229, v60 row_shr:2 row_mask:0xf bank_mask:0xf
	v_mov_b32_dpp v230, v61 row_shr:1 row_mask:0xf bank_mask:0xf
	v_mov_b32_dpp v231, v61 row_shr:2 row_mask:0xf bank_mask:0xf
	v_mov_b32_dpp v232, v62 row_shr:1 row_mask:0xf bank_mask:0xf
	v_mov_b32_dpp v233, v62 row_shr:2 row_mask:0xf bank_mask:0xf
	v_mov_b32_dpp v234, v63 row_shr:1 row_mask:0xf bank_mask:0xf
	v_mov_b32_dpp v235, v63 row_shr:2 row_mask:0xf bank_mask:0xf
	v_cndmask_b32_e64 v228, 0, v228, vcc
	v_cndmask_b32_e64 v229, 0, v229, s[8:9]
	v_cndmask_b32_e64 v230, 0, v230, vcc
	v_cndmask_b32_e64 v231, 0, v231, s[8:9]
	v_cndmask_b32_e64 v232, 0, v232, vcc
	v_cndmask_b32_e64 v233, 0, v233, s[8:9]
	v_cndmask_b32_e64 v234, 0, v234, vcc
	v_cndmask_b32_e64 v235, 0, v235, s[8:9]
	v_fma_f32 v236, v229, v128, v152
	v_fma_f32 v237, v231, v129, v153
	v_fma_f32 v238, v233, v130, v154
	v_fma_f32 v239, v235, v131, v155
	v_fmac_f32_e32 v236, v228, v136
	v_fmac_f32_e32 v237, v230, v137
	v_fmac_f32_e32 v238, v232, v138
	v_fmac_f32_e32 v239, v234, v139
	v_fmac_f32_e32 v236, v60, v144
	v_fmac_f32_e32 v237, v61, v145
	v_fmac_f32_e32 v238, v62, v146
	v_fmac_f32_e32 v239, v63, v147
	v_mov_b32_dpp v228, v68 row_ror:1 row_mask:0xf bank_mask:0xf
	v_mov_b32_dpp v229, v68 row_ror:2 row_mask:0xf bank_mask:0xf
	v_mov_b32_dpp v230, v69 row_ror:1 row_mask:0xf bank_mask:0xf
	v_mov_b32_dpp v231, v69 row_ror:2 row_mask:0xf bank_mask:0xf
	v_mov_b32_dpp v232, v70 row_ror:1 row_mask:0xf bank_mask:0xf
	v_mov_b32_dpp v233, v70 row_ror:2 row_mask:0xf bank_mask:0xf
	v_mov_b32_dpp v234, v71 row_ror:1 row_mask:0xf bank_mask:0xf
	v_mov_b32_dpp v235, v71 row_ror:2 row_mask:0xf bank_mask:0xf
	v_mov_b32_dpp v228, v52 row_shr:1 row_mask:0xf bank_mask:0xf
	v_mov_b32_dpp v229, v52 row_shr:2 row_mask:0xf bank_mask:0xf
	v_mov_b32_dpp v230, v53 row_shr:1 row_mask:0xf bank_mask:0xf
	v_mov_b32_dpp v231, v53 row_shr:2 row_mask:0xf bank_mask:0xf
	v_mov_b32_dpp v232, v54 row_shr:1 row_mask:0xf bank_mask:0xf
	v_mov_b32_dpp v233, v54 row_shr:2 row_mask:0xf bank_mask:0xf
	v_mov_b32_dpp v234, v55 row_shr:1 row_mask:0xf bank_mask:0xf
	v_mov_b32_dpp v235, v55 row_shr:2 row_mask:0xf bank_mask:0xf
	v_cndmask_b32_e64 v228, 0, v228, vcc
	v_cndmask_b32_e64 v229, 0, v229, s[8:9]
	v_cndmask_b32_e64 v230, 0, v230, vcc
	v_cndmask_b32_e64 v231, 0, v231, s[8:9]
	v_cndmask_b32_e64 v232, 0, v232, vcc
	v_cndmask_b32_e64 v233, 0, v233, s[8:9]
	v_cndmask_b32_e64 v234, 0, v234, vcc
	v_cndmask_b32_e64 v235, 0, v235, s[8:9]
	v_fma_f32 v240, v229, v132, v156
	v_fma_f32 v241, v231, v133, v157
	v_fma_f32 v242, v233, v134, v158
	v_fma_f32 v243, v235, v135, v159
	v_fmac_f32_e32 v240, v228, v140
	v_fmac_f32_e32 v241, v230, v141
	v_fmac_f32_e32 v242, v232, v142
	v_fmac_f32_e32 v243, v234, v143
	v_fmac_f32_e32 v240, v52, v148
	v_fmac_f32_e32 v241, v53, v149
	v_fmac_f32_e32 v242, v54, v150
	v_fmac_f32_e32 v243, v55, v151
	v_mov_b32_e32 v228, 0xbdd2d3e8
	v_mul_f32_e32 v244, v236, v236
	v_mul_f32_e32 v245, v237, v237
	v_mul_f32_e32 v246, v238, v238
	v_mul_f32_e32 v247, v239, v239
	v_fmaak_f32 v244, v244, v228, 0xc0135761
	v_fmaak_f32 v245, v245, v228, 0xc0135761
	v_fmaak_f32 v246, v246, v228, 0xc0135761
	v_fmaak_f32 v247, v247, v228, 0xc0135761
	v_mul_f32_e32 v244, v236, v244
	v_mul_f32_e32 v245, v237, v245
	v_mul_f32_e32 v246, v238, v246
	v_mul_f32_e32 v247, v239, v247
	v_exp_f32_e32 v244, v244
	v_exp_f32_e32 v245, v245
	v_exp_f32_e32 v246, v246
	v_exp_f32_e32 v247, v247
	v_add_f32_e32 v244, 1.0, v244
	v_add_f32_e32 v245, 1.0, v245
	v_add_f32_e32 v246, 1.0, v246
	v_add_f32_e32 v247, 1.0, v247
	v_rcp_f32_e32 v244, v244
	v_rcp_f32_e32 v245, v245
	v_rcp_f32_e32 v246, v246
	v_rcp_f32_e32 v247, v247
	v_mul_f32_e32 v244, v236, v244
	v_mul_f32_e32 v245, v237, v245
	v_mul_f32_e32 v246, v238, v246
	v_mul_f32_e32 v247, v239, v247
	v_mul_f32_e32 v248, v240, v244
	v_mul_f32_e32 v249, v241, v245
	v_mul_f32_e32 v250, v242, v246
	v_mul_f32_e32 v251, v243, v247
	v_cvt_pk_bf16_f32 v216, v248, v249
	v_cvt_pk_bf16_f32 v217, v250, v251
	s_branch .Lffn1e_join0_4
.Lffn1e_old0_4:
	v_mov_b32_dpp v228, v76 row_ror:1 row_mask:0xf bank_mask:0xf
	v_mov_b32_dpp v229, v76 row_ror:2 row_mask:0xf bank_mask:0xf
	v_mov_b32_dpp v230, v77 row_ror:1 row_mask:0xf bank_mask:0xf
	v_mov_b32_dpp v231, v77 row_ror:2 row_mask:0xf bank_mask:0xf
	v_mov_b32_dpp v232, v78 row_ror:1 row_mask:0xf bank_mask:0xf
	v_mov_b32_dpp v233, v78 row_ror:2 row_mask:0xf bank_mask:0xf
	v_mov_b32_dpp v234, v79 row_ror:1 row_mask:0xf bank_mask:0xf
	v_mov_b32_dpp v235, v79 row_ror:2 row_mask:0xf bank_mask:0xf
	v_mov_b32_dpp v228, v60 row_shr:1 row_mask:0xf bank_mask:0xf
	v_mov_b32_dpp v229, v60 row_shr:2 row_mask:0xf bank_mask:0xf
	v_mov_b32_dpp v230, v61 row_shr:1 row_mask:0xf bank_mask:0xf
	v_mov_b32_dpp v231, v61 row_shr:2 row_mask:0xf bank_mask:0xf
	v_mov_b32_dpp v232, v62 row_shr:1 row_mask:0xf bank_mask:0xf
	v_mov_b32_dpp v233, v62 row_shr:2 row_mask:0xf bank_mask:0xf
	v_mov_b32_dpp v234, v63 row_shr:1 row_mask:0xf bank_mask:0xf
	v_mov_b32_dpp v235, v63 row_shr:2 row_mask:0xf bank_mask:0xf
	v_fma_f32 v236, v229, v128, v152
	v_fma_f32 v237, v231, v129, v153
	v_fma_f32 v238, v233, v130, v154
	v_fma_f32 v239, v235, v131, v155
	v_fmac_f32_e32 v236, v228, v136
	v_fmac_f32_e32 v237, v230, v137
	v_fmac_f32_e32 v238, v232, v138
	v_fmac_f32_e32 v239, v234, v139
	v_fmac_f32_e32 v236, v60, v144
	v_fmac_f32_e32 v237, v61, v145
	v_fmac_f32_e32 v238, v62, v146
	v_fmac_f32_e32 v239, v63, v147
	v_mov_b32_dpp v228, v68 row_ror:1 row_mask:0xf bank_mask:0xf
	v_mov_b32_dpp v229, v68 row_ror:2 row_mask:0xf bank_mask:0xf
	v_mov_b32_dpp v230, v69 row_ror:1 row_mask:0xf bank_mask:0xf
	v_mov_b32_dpp v231, v69 row_ror:2 row_mask:0xf bank_mask:0xf
	v_mov_b32_dpp v232, v70 row_ror:1 row_mask:0xf bank_mask:0xf
	v_mov_b32_dpp v233, v70 row_ror:2 row_mask:0xf bank_mask:0xf
	v_mov_b32_dpp v234, v71 row_ror:1 row_mask:0xf bank_mask:0xf
	v_mov_b32_dpp v235, v71 row_ror:2 row_mask:0xf bank_mask:0xf
	v_mov_b32_dpp v228, v52 row_shr:1 row_mask:0xf bank_mask:0xf
	v_mov_b32_dpp v229, v52 row_shr:2 row_mask:0xf bank_mask:0xf
	v_mov_b32_dpp v230, v53 row_shr:1 row_mask:0xf bank_mask:0xf
	v_mov_b32_dpp v231, v53 row_shr:2 row_mask:0xf bank_mask:0xf
	v_mov_b32_dpp v232, v54 row_shr:1 row_mask:0xf bank_mask:0xf
	v_mov_b32_dpp v233, v54 row_shr:2 row_mask:0xf bank_mask:0xf
	v_mov_b32_dpp v234, v55 row_shr:1 row_mask:0xf bank_mask:0xf
	v_mov_b32_dpp v235, v55 row_shr:2 row_mask:0xf bank_mask:0xf
	v_fma_f32 v240, v229, v132, v156
	v_fma_f32 v241, v231, v133, v157
	v_fma_f32 v242, v233, v134, v158
	v_fma_f32 v243, v235, v135, v159
	v_fmac_f32_e32 v240, v228, v140
	v_fmac_f32_e32 v241, v230, v141
	v_fmac_f32_e32 v242, v232, v142
	v_fmac_f32_e32 v243, v234, v143
	v_fmac_f32_e32 v240, v52, v148
	v_fmac_f32_e32 v241, v53, v149
	v_fmac_f32_e32 v242, v54, v150
	v_fmac_f32_e32 v243, v55, v151
	v_mov_b32_e32 v228, 0xbdd2d3e8
	v_mul_f32_e32 v244, v236, v236
	v_mul_f32_e32 v245, v237, v237
	v_mul_f32_e32 v246, v238, v238
	v_mul_f32_e32 v247, v239, v239
	v_fmaak_f32 v244, v244, v228, 0xc0135761
	v_fmaak_f32 v245, v245, v228, 0xc0135761
	v_fmaak_f32 v246, v246, v228, 0xc0135761
	v_fmaak_f32 v247, v247, v228, 0xc0135761
	v_mul_f32_e32 v244, v236, v244
	v_mul_f32_e32 v245, v237, v245
	v_mul_f32_e32 v246, v238, v246
	v_mul_f32_e32 v247, v239, v247
	v_exp_f32_e32 v244, v244
	v_exp_f32_e32 v245, v245
	v_exp_f32_e32 v246, v246
	v_exp_f32_e32 v247, v247
	v_add_f32_e32 v244, 1.0, v244
	v_add_f32_e32 v245, 1.0, v245
	v_add_f32_e32 v246, 1.0, v246
	v_add_f32_e32 v247, 1.0, v247
	v_rcp_f32_e32 v244, v244
	v_rcp_f32_e32 v245, v245
	v_rcp_f32_e32 v246, v246
	v_rcp_f32_e32 v247, v247
	v_mul_f32_e32 v244, v236, v244
	v_mul_f32_e32 v245, v237, v245
	v_mul_f32_e32 v246, v238, v246
	v_mul_f32_e32 v247, v239, v247
	v_mul_f32_e32 v248, v240, v244
	v_mul_f32_e32 v249, v241, v245
	v_mul_f32_e32 v250, v242, v246
	v_mul_f32_e32 v251, v243, v247
	v_cvt_pk_bf16_f32 v216, v248, v249
	v_cvt_pk_bf16_f32 v217, v250, v251
	s_branch .Lffn1e_join0_4
.Lffn1e_slow0_5:
	v_add_u32_e32 v189, 2144, v218
	v_mul_hi_u32 v203, v189, s59
	v_lshrrev_b32_e32 v203, 7, v203
	v_mul_u32_u24_e32 v203, 0x810, v203
	v_sub_u32_e32 v189, v189, v203
	v_cmp_lt_u32_e32 vcc, 0, v189
	v_cmp_lt_u32_e64 s[8:9], 1, v189
	s_nop 1
	v_mov_b32_dpp v228, v60 row_ror:1 row_mask:0xf bank_mask:0xf
	v_mov_b32_dpp v229, v60 row_ror:2 row_mask:0xf bank_mask:0xf
	v_mov_b32_dpp v230, v61 row_ror:1 row_mask:0xf bank_mask:0xf
	v_mov_b32_dpp v231, v61 row_ror:2 row_mask:0xf bank_mask:0xf
	v_mov_b32_dpp v232, v62 row_ror:1 row_mask:0xf bank_mask:0xf
	v_mov_b32_dpp v233, v62 row_ror:2 row_mask:0xf bank_mask:0xf
	v_mov_b32_dpp v234, v63 row_ror:1 row_mask:0xf bank_mask:0xf
	v_mov_b32_dpp v235, v63 row_ror:2 row_mask:0xf bank_mask:0xf
	v_mov_b32_dpp v228, v44 row_shr:1 row_mask:0xf bank_mask:0xf
	v_mov_b32_dpp v229, v44 row_shr:2 row_mask:0xf bank_mask:0xf
	v_mov_b32_dpp v230, v45 row_shr:1 row_mask:0xf bank_mask:0xf
	v_mov_b32_dpp v231, v45 row_shr:2 row_mask:0xf bank_mask:0xf
	v_mov_b32_dpp v232, v46 row_shr:1 row_mask:0xf bank_mask:0xf
	v_mov_b32_dpp v233, v46 row_shr:2 row_mask:0xf bank_mask:0xf
	v_mov_b32_dpp v234, v47 row_shr:1 row_mask:0xf bank_mask:0xf
	v_mov_b32_dpp v235, v47 row_shr:2 row_mask:0xf bank_mask:0xf
	v_cndmask_b32_e64 v228, 0, v228, vcc
	v_cndmask_b32_e64 v229, 0, v229, s[8:9]
	v_cndmask_b32_e64 v230, 0, v230, vcc
	v_cndmask_b32_e64 v231, 0, v231, s[8:9]
	v_cndmask_b32_e64 v232, 0, v232, vcc
	v_cndmask_b32_e64 v233, 0, v233, s[8:9]
	v_cndmask_b32_e64 v234, 0, v234, vcc
	v_cndmask_b32_e64 v235, 0, v235, s[8:9]
	v_fma_f32 v236, v229, v128, v152
	v_fma_f32 v237, v231, v129, v153
	v_fma_f32 v238, v233, v130, v154
	v_fma_f32 v239, v235, v131, v155
	v_fmac_f32_e32 v236, v228, v136
	v_fmac_f32_e32 v237, v230, v137
	v_fmac_f32_e32 v238, v232, v138
	v_fmac_f32_e32 v239, v234, v139
	v_fmac_f32_e32 v236, v44, v144
	v_fmac_f32_e32 v237, v45, v145
	v_fmac_f32_e32 v238, v46, v146
	v_fmac_f32_e32 v239, v47, v147
	v_mov_b32_dpp v228, v52 row_ror:1 row_mask:0xf bank_mask:0xf
	v_mov_b32_dpp v229, v52 row_ror:2 row_mask:0xf bank_mask:0xf
	v_mov_b32_dpp v230, v53 row_ror:1 row_mask:0xf bank_mask:0xf
	v_mov_b32_dpp v231, v53 row_ror:2 row_mask:0xf bank_mask:0xf
	v_mov_b32_dpp v232, v54 row_ror:1 row_mask:0xf bank_mask:0xf
	v_mov_b32_dpp v233, v54 row_ror:2 row_mask:0xf bank_mask:0xf
	v_mov_b32_dpp v234, v55 row_ror:1 row_mask:0xf bank_mask:0xf
	v_mov_b32_dpp v235, v55 row_ror:2 row_mask:0xf bank_mask:0xf
	v_mov_b32_dpp v228, v36 row_shr:1 row_mask:0xf bank_mask:0xf
	v_mov_b32_dpp v229, v36 row_shr:2 row_mask:0xf bank_mask:0xf
	v_mov_b32_dpp v230, v37 row_shr:1 row_mask:0xf bank_mask:0xf
	v_mov_b32_dpp v231, v37 row_shr:2 row_mask:0xf bank_mask:0xf
	v_mov_b32_dpp v232, v38 row_shr:1 row_mask:0xf bank_mask:0xf
	v_mov_b32_dpp v233, v38 row_shr:2 row_mask:0xf bank_mask:0xf
	v_mov_b32_dpp v234, v39 row_shr:1 row_mask:0xf bank_mask:0xf
	v_mov_b32_dpp v235, v39 row_shr:2 row_mask:0xf bank_mask:0xf
	v_cndmask_b32_e64 v228, 0, v228, vcc
	v_cndmask_b32_e64 v229, 0, v229, s[8:9]
	v_cndmask_b32_e64 v230, 0, v230, vcc
	v_cndmask_b32_e64 v231, 0, v231, s[8:9]
	v_cndmask_b32_e64 v232, 0, v232, vcc
	v_cndmask_b32_e64 v233, 0, v233, s[8:9]
	v_cndmask_b32_e64 v234, 0, v234, vcc
	v_cndmask_b32_e64 v235, 0, v235, s[8:9]
	v_fma_f32 v240, v229, v132, v156
	v_fma_f32 v241, v231, v133, v157
	v_fma_f32 v242, v233, v134, v158
	v_fma_f32 v243, v235, v135, v159
	v_fmac_f32_e32 v240, v228, v140
	v_fmac_f32_e32 v241, v230, v141
	v_fmac_f32_e32 v242, v232, v142
	v_fmac_f32_e32 v243, v234, v143
	v_fmac_f32_e32 v240, v36, v148
	v_fmac_f32_e32 v241, v37, v149
	v_fmac_f32_e32 v242, v38, v150
	v_fmac_f32_e32 v243, v39, v151
	v_mov_b32_e32 v228, 0xbdd2d3e8
	v_mul_f32_e32 v244, v236, v236
	v_mul_f32_e32 v245, v237, v237
	v_mul_f32_e32 v246, v238, v238
	v_mul_f32_e32 v247, v239, v239
	v_fmaak_f32 v244, v244, v228, 0xc0135761
	v_fmaak_f32 v245, v245, v228, 0xc0135761
	v_fmaak_f32 v246, v246, v228, 0xc0135761
	v_fmaak_f32 v247, v247, v228, 0xc0135761
	v_mul_f32_e32 v244, v236, v244
	v_mul_f32_e32 v245, v237, v245
	v_mul_f32_e32 v246, v238, v246
	v_mul_f32_e32 v247, v239, v247
	v_exp_f32_e32 v244, v244
	v_exp_f32_e32 v245, v245
	v_exp_f32_e32 v246, v246
	v_exp_f32_e32 v247, v247
	v_add_f32_e32 v244, 1.0, v244
	v_add_f32_e32 v245, 1.0, v245
	v_add_f32_e32 v246, 1.0, v246
	v_add_f32_e32 v247, 1.0, v247
	v_rcp_f32_e32 v244, v244
	v_rcp_f32_e32 v245, v245
	v_rcp_f32_e32 v246, v246
	v_rcp_f32_e32 v247, v247
	v_mul_f32_e32 v244, v236, v244
	v_mul_f32_e32 v245, v237, v245
	v_mul_f32_e32 v246, v238, v246
	v_mul_f32_e32 v247, v239, v247
	v_mul_f32_e32 v248, v240, v244
	v_mul_f32_e32 v249, v241, v245
	v_mul_f32_e32 v250, v242, v246
	v_mul_f32_e32 v251, v243, v247
	v_cvt_pk_bf16_f32 v220, v248, v249
	v_cvt_pk_bf16_f32 v221, v250, v251
	s_branch .Lffn1e_join0_5
.Lffn1e_old0_5:
	v_mov_b32_dpp v228, v60 row_ror:1 row_mask:0xf bank_mask:0xf
	v_mov_b32_dpp v229, v60 row_ror:2 row_mask:0xf bank_mask:0xf
	v_mov_b32_dpp v230, v61 row_ror:1 row_mask:0xf bank_mask:0xf
	v_mov_b32_dpp v231, v61 row_ror:2 row_mask:0xf bank_mask:0xf
	v_mov_b32_dpp v232, v62 row_ror:1 row_mask:0xf bank_mask:0xf
	v_mov_b32_dpp v233, v62 row_ror:2 row_mask:0xf bank_mask:0xf
	v_mov_b32_dpp v234, v63 row_ror:1 row_mask:0xf bank_mask:0xf
	v_mov_b32_dpp v235, v63 row_ror:2 row_mask:0xf bank_mask:0xf
	v_mov_b32_dpp v228, v44 row_shr:1 row_mask:0xf bank_mask:0xf
	v_mov_b32_dpp v229, v44 row_shr:2 row_mask:0xf bank_mask:0xf
	v_mov_b32_dpp v230, v45 row_shr:1 row_mask:0xf bank_mask:0xf
	v_mov_b32_dpp v231, v45 row_shr:2 row_mask:0xf bank_mask:0xf
	v_mov_b32_dpp v232, v46 row_shr:1 row_mask:0xf bank_mask:0xf
	v_mov_b32_dpp v233, v46 row_shr:2 row_mask:0xf bank_mask:0xf
	v_mov_b32_dpp v234, v47 row_shr:1 row_mask:0xf bank_mask:0xf
	v_mov_b32_dpp v235, v47 row_shr:2 row_mask:0xf bank_mask:0xf
	v_fma_f32 v236, v229, v128, v152
	v_fma_f32 v237, v231, v129, v153
	v_fma_f32 v238, v233, v130, v154
	v_fma_f32 v239, v235, v131, v155
	v_fmac_f32_e32 v236, v228, v136
	v_fmac_f32_e32 v237, v230, v137
	v_fmac_f32_e32 v238, v232, v138
	v_fmac_f32_e32 v239, v234, v139
	v_fmac_f32_e32 v236, v44, v144
	v_fmac_f32_e32 v237, v45, v145
	v_fmac_f32_e32 v238, v46, v146
	v_fmac_f32_e32 v239, v47, v147
	v_mov_b32_dpp v228, v52 row_ror:1 row_mask:0xf bank_mask:0xf
	v_mov_b32_dpp v229, v52 row_ror:2 row_mask:0xf bank_mask:0xf
	v_mov_b32_dpp v230, v53 row_ror:1 row_mask:0xf bank_mask:0xf
	v_mov_b32_dpp v231, v53 row_ror:2 row_mask:0xf bank_mask:0xf
	v_mov_b32_dpp v232, v54 row_ror:1 row_mask:0xf bank_mask:0xf
	v_mov_b32_dpp v233, v54 row_ror:2 row_mask:0xf bank_mask:0xf
	v_mov_b32_dpp v234, v55 row_ror:1 row_mask:0xf bank_mask:0xf
	v_mov_b32_dpp v235, v55 row_ror:2 row_mask:0xf bank_mask:0xf
	v_mov_b32_dpp v228, v36 row_shr:1 row_mask:0xf bank_mask:0xf
	v_mov_b32_dpp v229, v36 row_shr:2 row_mask:0xf bank_mask:0xf
	v_mov_b32_dpp v230, v37 row_shr:1 row_mask:0xf bank_mask:0xf
	v_mov_b32_dpp v231, v37 row_shr:2 row_mask:0xf bank_mask:0xf
	v_mov_b32_dpp v232, v38 row_shr:1 row_mask:0xf bank_mask:0xf
	v_mov_b32_dpp v233, v38 row_shr:2 row_mask:0xf bank_mask:0xf
	v_mov_b32_dpp v234, v39 row_shr:1 row_mask:0xf bank_mask:0xf
	v_mov_b32_dpp v235, v39 row_shr:2 row_mask:0xf bank_mask:0xf
	v_fma_f32 v240, v229, v132, v156
	v_fma_f32 v241, v231, v133, v157
	v_fma_f32 v242, v233, v134, v158
	v_fma_f32 v243, v235, v135, v159
	v_fmac_f32_e32 v240, v228, v140
	v_fmac_f32_e32 v241, v230, v141
	v_fmac_f32_e32 v242, v232, v142
	v_fmac_f32_e32 v243, v234, v143
	v_fmac_f32_e32 v240, v36, v148
	v_fmac_f32_e32 v241, v37, v149
	v_fmac_f32_e32 v242, v38, v150
	v_fmac_f32_e32 v243, v39, v151
	v_mov_b32_e32 v228, 0xbdd2d3e8
	v_mul_f32_e32 v244, v236, v236
	v_mul_f32_e32 v245, v237, v237
	v_mul_f32_e32 v246, v238, v238
	v_mul_f32_e32 v247, v239, v239
	v_fmaak_f32 v244, v244, v228, 0xc0135761
	v_fmaak_f32 v245, v245, v228, 0xc0135761
	v_fmaak_f32 v246, v246, v228, 0xc0135761
	v_fmaak_f32 v247, v247, v228, 0xc0135761
	v_mul_f32_e32 v244, v236, v244
	v_mul_f32_e32 v245, v237, v245
	v_mul_f32_e32 v246, v238, v246
	v_mul_f32_e32 v247, v239, v247
	v_exp_f32_e32 v244, v244
	v_exp_f32_e32 v245, v245
	v_exp_f32_e32 v246, v246
	v_exp_f32_e32 v247, v247
	v_add_f32_e32 v244, 1.0, v244
	v_add_f32_e32 v245, 1.0, v245
	v_add_f32_e32 v246, 1.0, v246
	v_add_f32_e32 v247, 1.0, v247
	v_rcp_f32_e32 v244, v244
	v_rcp_f32_e32 v245, v245
	v_rcp_f32_e32 v246, v246
	v_rcp_f32_e32 v247, v247
	v_mul_f32_e32 v244, v236, v244
	v_mul_f32_e32 v245, v237, v245
	v_mul_f32_e32 v246, v238, v246
	v_mul_f32_e32 v247, v239, v247
	v_mul_f32_e32 v248, v240, v244
	v_mul_f32_e32 v249, v241, v245
	v_mul_f32_e32 v250, v242, v246
	v_mul_f32_e32 v251, v243, v247
	v_cvt_pk_bf16_f32 v220, v248, v249
	v_cvt_pk_bf16_f32 v221, v250, v251
	s_branch .Lffn1e_join0_5
.Lffn1e_slow0_6:
	v_add_u32_e32 v189, 2160, v218
	v_mul_hi_u32 v203, v189, s59
	v_lshrrev_b32_e32 v203, 7, v203
	v_mul_u32_u24_e32 v203, 0x810, v203
	v_sub_u32_e32 v189, v189, v203
	v_cmp_lt_u32_e32 vcc, 0, v189
	v_cmp_lt_u32_e64 s[8:9], 1, v189
	s_nop 1
	v_mov_b32_dpp v228, v44 row_ror:1 row_mask:0xf bank_mask:0xf
	v_mov_b32_dpp v229, v44 row_ror:2 row_mask:0xf bank_mask:0xf
	v_mov_b32_dpp v230, v45 row_ror:1 row_mask:0xf bank_mask:0xf
	v_mov_b32_dpp v231, v45 row_ror:2 row_mask:0xf bank_mask:0xf
	v_mov_b32_dpp v232, v46 row_ror:1 row_mask:0xf bank_mask:0xf
	v_mov_b32_dpp v233, v46 row_ror:2 row_mask:0xf bank_mask:0xf
	v_mov_b32_dpp v234, v47 row_ror:1 row_mask:0xf bank_mask:0xf
	v_mov_b32_dpp v235, v47 row_ror:2 row_mask:0xf bank_mask:0xf
	v_mov_b32_dpp v228, v28 row_shr:1 row_mask:0xf bank_mask:0xf
	v_mov_b32_dpp v229, v28 row_shr:2 row_mask:0xf bank_mask:0xf
	v_mov_b32_dpp v230, v29 row_shr:1 row_mask:0xf bank_mask:0xf
	v_mov_b32_dpp v231, v29 row_shr:2 row_mask:0xf bank_mask:0xf
	v_mov_b32_dpp v232, v30 row_shr:1 row_mask:0xf bank_mask:0xf
	v_mov_b32_dpp v233, v30 row_shr:2 row_mask:0xf bank_mask:0xf
	v_mov_b32_dpp v234, v31 row_shr:1 row_mask:0xf bank_mask:0xf
	v_mov_b32_dpp v235, v31 row_shr:2 row_mask:0xf bank_mask:0xf
	v_cndmask_b32_e64 v228, 0, v228, vcc
	v_cndmask_b32_e64 v229, 0, v229, s[8:9]
	v_cndmask_b32_e64 v230, 0, v230, vcc
	v_cndmask_b32_e64 v231, 0, v231, s[8:9]
	v_cndmask_b32_e64 v232, 0, v232, vcc
	v_cndmask_b32_e64 v233, 0, v233, s[8:9]
	v_cndmask_b32_e64 v234, 0, v234, vcc
	v_cndmask_b32_e64 v235, 0, v235, s[8:9]
	v_fma_f32 v236, v229, v128, v152
	v_fma_f32 v237, v231, v129, v153
	v_fma_f32 v238, v233, v130, v154
	v_fma_f32 v239, v235, v131, v155
	v_fmac_f32_e32 v236, v228, v136
	v_fmac_f32_e32 v237, v230, v137
	v_fmac_f32_e32 v238, v232, v138
	v_fmac_f32_e32 v239, v234, v139
	v_fmac_f32_e32 v236, v28, v144
	v_fmac_f32_e32 v237, v29, v145
	v_fmac_f32_e32 v238, v30, v146
	v_fmac_f32_e32 v239, v31, v147
	v_mov_b32_dpp v228, v36 row_ror:1 row_mask:0xf bank_mask:0xf
	v_mov_b32_dpp v229, v36 row_ror:2 row_mask:0xf bank_mask:0xf
	v_mov_b32_dpp v230, v37 row_ror:1 row_mask:0xf bank_mask:0xf
	v_mov_b32_dpp v231, v37 row_ror:2 row_mask:0xf bank_mask:0xf
	v_mov_b32_dpp v232, v38 row_ror:1 row_mask:0xf bank_mask:0xf
	v_mov_b32_dpp v233, v38 row_ror:2 row_mask:0xf bank_mask:0xf
	v_mov_b32_dpp v234, v39 row_ror:1 row_mask:0xf bank_mask:0xf
	v_mov_b32_dpp v235, v39 row_ror:2 row_mask:0xf bank_mask:0xf
	v_mov_b32_dpp v228, v20 row_shr:1 row_mask:0xf bank_mask:0xf
	v_mov_b32_dpp v229, v20 row_shr:2 row_mask:0xf bank_mask:0xf
	v_mov_b32_dpp v230, v21 row_shr:1 row_mask:0xf bank_mask:0xf
	v_mov_b32_dpp v231, v21 row_shr:2 row_mask:0xf bank_mask:0xf
	v_mov_b32_dpp v232, v22 row_shr:1 row_mask:0xf bank_mask:0xf
	v_mov_b32_dpp v233, v22 row_shr:2 row_mask:0xf bank_mask:0xf
	v_mov_b32_dpp v234, v23 row_shr:1 row_mask:0xf bank_mask:0xf
	v_mov_b32_dpp v235, v23 row_shr:2 row_mask:0xf bank_mask:0xf
	v_cndmask_b32_e64 v228, 0, v228, vcc
	v_cndmask_b32_e64 v229, 0, v229, s[8:9]
	v_cndmask_b32_e64 v230, 0, v230, vcc
	v_cndmask_b32_e64 v231, 0, v231, s[8:9]
	v_cndmask_b32_e64 v232, 0, v232, vcc
	v_cndmask_b32_e64 v233, 0, v233, s[8:9]
	v_cndmask_b32_e64 v234, 0, v234, vcc
	v_cndmask_b32_e64 v235, 0, v235, s[8:9]
	v_fma_f32 v240, v229, v132, v156
	v_fma_f32 v241, v231, v133, v157
	v_fma_f32 v242, v233, v134, v158
	v_fma_f32 v243, v235, v135, v159
	v_fmac_f32_e32 v240, v228, v140
	v_fmac_f32_e32 v241, v230, v141
	v_fmac_f32_e32 v242, v232, v142
	v_fmac_f32_e32 v243, v234, v143
	v_fmac_f32_e32 v240, v20, v148
	v_fmac_f32_e32 v241, v21, v149
	v_fmac_f32_e32 v242, v22, v150
	v_fmac_f32_e32 v243, v23, v151
	v_mov_b32_e32 v228, 0xbdd2d3e8
	v_mul_f32_e32 v244, v236, v236
	v_mul_f32_e32 v245, v237, v237
	v_mul_f32_e32 v246, v238, v238
	v_mul_f32_e32 v247, v239, v239
	v_fmaak_f32 v244, v244, v228, 0xc0135761
	v_fmaak_f32 v245, v245, v228, 0xc0135761
	v_fmaak_f32 v246, v246, v228, 0xc0135761
	v_fmaak_f32 v247, v247, v228, 0xc0135761
	v_mul_f32_e32 v244, v236, v244
	v_mul_f32_e32 v245, v237, v245
	v_mul_f32_e32 v246, v238, v246
	v_mul_f32_e32 v247, v239, v247
	v_exp_f32_e32 v244, v244
	v_exp_f32_e32 v245, v245
	v_exp_f32_e32 v246, v246
	v_exp_f32_e32 v247, v247
	v_add_f32_e32 v244, 1.0, v244
	v_add_f32_e32 v245, 1.0, v245
	v_add_f32_e32 v246, 1.0, v246
	v_add_f32_e32 v247, 1.0, v247
	v_rcp_f32_e32 v244, v244
	v_rcp_f32_e32 v245, v245
	v_rcp_f32_e32 v246, v246
	v_rcp_f32_e32 v247, v247
	v_mul_f32_e32 v244, v236, v244
	v_mul_f32_e32 v245, v237, v245
	v_mul_f32_e32 v246, v238, v246
	v_mul_f32_e32 v247, v239, v247
	v_mul_f32_e32 v248, v240, v244
	v_mul_f32_e32 v249, v241, v245
	v_mul_f32_e32 v250, v242, v246
	v_mul_f32_e32 v251, v243, v247
	v_cvt_pk_bf16_f32 v222, v248, v249
	v_cvt_pk_bf16_f32 v223, v250, v251
	s_branch .Lffn1e_join0_6
.Lffn1e_old0_6:
	v_mov_b32_dpp v228, v44 row_ror:1 row_mask:0xf bank_mask:0xf
	v_mov_b32_dpp v229, v44 row_ror:2 row_mask:0xf bank_mask:0xf
	v_mov_b32_dpp v230, v45 row_ror:1 row_mask:0xf bank_mask:0xf
	v_mov_b32_dpp v231, v45 row_ror:2 row_mask:0xf bank_mask:0xf
	v_mov_b32_dpp v232, v46 row_ror:1 row_mask:0xf bank_mask:0xf
	v_mov_b32_dpp v233, v46 row_ror:2 row_mask:0xf bank_mask:0xf
	v_mov_b32_dpp v234, v47 row_ror:1 row_mask:0xf bank_mask:0xf
	v_mov_b32_dpp v235, v47 row_ror:2 row_mask:0xf bank_mask:0xf
	v_mov_b32_dpp v228, v28 row_shr:1 row_mask:0xf bank_mask:0xf
	v_mov_b32_dpp v229, v28 row_shr:2 row_mask:0xf bank_mask:0xf
	v_mov_b32_dpp v230, v29 row_shr:1 row_mask:0xf bank_mask:0xf
	v_mov_b32_dpp v231, v29 row_shr:2 row_mask:0xf bank_mask:0xf
	v_mov_b32_dpp v232, v30 row_shr:1 row_mask:0xf bank_mask:0xf
	v_mov_b32_dpp v233, v30 row_shr:2 row_mask:0xf bank_mask:0xf
	v_mov_b32_dpp v234, v31 row_shr:1 row_mask:0xf bank_mask:0xf
	v_mov_b32_dpp v235, v31 row_shr:2 row_mask:0xf bank_mask:0xf
	v_fma_f32 v236, v229, v128, v152
	v_fma_f32 v237, v231, v129, v153
	v_fma_f32 v238, v233, v130, v154
	v_fma_f32 v239, v235, v131, v155
	v_fmac_f32_e32 v236, v228, v136
	v_fmac_f32_e32 v237, v230, v137
	v_fmac_f32_e32 v238, v232, v138
	v_fmac_f32_e32 v239, v234, v139
	v_fmac_f32_e32 v236, v28, v144
	v_fmac_f32_e32 v237, v29, v145
	v_fmac_f32_e32 v238, v30, v146
	v_fmac_f32_e32 v239, v31, v147
	v_mov_b32_dpp v228, v36 row_ror:1 row_mask:0xf bank_mask:0xf
	v_mov_b32_dpp v229, v36 row_ror:2 row_mask:0xf bank_mask:0xf
	v_mov_b32_dpp v230, v37 row_ror:1 row_mask:0xf bank_mask:0xf
	v_mov_b32_dpp v231, v37 row_ror:2 row_mask:0xf bank_mask:0xf
	v_mov_b32_dpp v232, v38 row_ror:1 row_mask:0xf bank_mask:0xf
	v_mov_b32_dpp v233, v38 row_ror:2 row_mask:0xf bank_mask:0xf
	v_mov_b32_dpp v234, v39 row_ror:1 row_mask:0xf bank_mask:0xf
	v_mov_b32_dpp v235, v39 row_ror:2 row_mask:0xf bank_mask:0xf
	v_mov_b32_dpp v228, v20 row_shr:1 row_mask:0xf bank_mask:0xf
	v_mov_b32_dpp v229, v20 row_shr:2 row_mask:0xf bank_mask:0xf
	v_mov_b32_dpp v230, v21 row_shr:1 row_mask:0xf bank_mask:0xf
	v_mov_b32_dpp v231, v21 row_shr:2 row_mask:0xf bank_mask:0xf
	v_mov_b32_dpp v232, v22 row_shr:1 row_mask:0xf bank_mask:0xf
	v_mov_b32_dpp v233, v22 row_shr:2 row_mask:0xf bank_mask:0xf
	v_mov_b32_dpp v234, v23 row_shr:1 row_mask:0xf bank_mask:0xf
	v_mov_b32_dpp v235, v23 row_shr:2 row_mask:0xf bank_mask:0xf
	v_fma_f32 v240, v229, v132, v156
	v_fma_f32 v241, v231, v133, v157
	v_fma_f32 v242, v233, v134, v158
	v_fma_f32 v243, v235, v135, v159
	v_fmac_f32_e32 v240, v228, v140
	v_fmac_f32_e32 v241, v230, v141
	v_fmac_f32_e32 v242, v232, v142
	v_fmac_f32_e32 v243, v234, v143
	v_fmac_f32_e32 v240, v20, v148
	v_fmac_f32_e32 v241, v21, v149
	v_fmac_f32_e32 v242, v22, v150
	v_fmac_f32_e32 v243, v23, v151
	v_mov_b32_e32 v228, 0xbdd2d3e8
	v_mul_f32_e32 v244, v236, v236
	v_mul_f32_e32 v245, v237, v237
	v_mul_f32_e32 v246, v238, v238
	v_mul_f32_e32 v247, v239, v239
	v_fmaak_f32 v244, v244, v228, 0xc0135761
	v_fmaak_f32 v245, v245, v228, 0xc0135761
	v_fmaak_f32 v246, v246, v228, 0xc0135761
	v_fmaak_f32 v247, v247, v228, 0xc0135761
	v_mul_f32_e32 v244, v236, v244
	v_mul_f32_e32 v245, v237, v245
	v_mul_f32_e32 v246, v238, v246
	v_mul_f32_e32 v247, v239, v247
	v_exp_f32_e32 v244, v244
	v_exp_f32_e32 v245, v245
	v_exp_f32_e32 v246, v246
	v_exp_f32_e32 v247, v247
	v_add_f32_e32 v244, 1.0, v244
	v_add_f32_e32 v245, 1.0, v245
	v_add_f32_e32 v246, 1.0, v246
	v_add_f32_e32 v247, 1.0, v247
	v_rcp_f32_e32 v244, v244
	v_rcp_f32_e32 v245, v245
	v_rcp_f32_e32 v246, v246
	v_rcp_f32_e32 v247, v247
	v_mul_f32_e32 v244, v236, v244
	v_mul_f32_e32 v245, v237, v245
	v_mul_f32_e32 v246, v238, v246
	v_mul_f32_e32 v247, v239, v247
	v_mul_f32_e32 v248, v240, v244
	v_mul_f32_e32 v249, v241, v245
	v_mul_f32_e32 v250, v242, v246
	v_mul_f32_e32 v251, v243, v247
	v_cvt_pk_bf16_f32 v222, v248, v249
	v_cvt_pk_bf16_f32 v223, v250, v251
	s_branch .Lffn1e_join0_6
.Lffn1e_slow0_7:
	v_add_u32_e32 v189, 2176, v218
	v_mul_hi_u32 v203, v189, s59
	v_lshrrev_b32_e32 v203, 7, v203
	v_mul_u32_u24_e32 v203, 0x810, v203
	v_sub_u32_e32 v189, v189, v203
	v_cmp_lt_u32_e32 vcc, 0, v189
	v_cmp_lt_u32_e64 s[8:9], 1, v189
	s_nop 1
	v_mov_b32_dpp v228, v28 row_ror:1 row_mask:0xf bank_mask:0xf
	v_mov_b32_dpp v229, v28 row_ror:2 row_mask:0xf bank_mask:0xf
	v_mov_b32_dpp v230, v29 row_ror:1 row_mask:0xf bank_mask:0xf
	v_mov_b32_dpp v231, v29 row_ror:2 row_mask:0xf bank_mask:0xf
	v_mov_b32_dpp v232, v30 row_ror:1 row_mask:0xf bank_mask:0xf
	v_mov_b32_dpp v233, v30 row_ror:2 row_mask:0xf bank_mask:0xf
	v_mov_b32_dpp v234, v31 row_ror:1 row_mask:0xf bank_mask:0xf
	v_mov_b32_dpp v235, v31 row_ror:2 row_mask:0xf bank_mask:0xf
	v_mov_b32_dpp v228, v4 row_shr:1 row_mask:0xf bank_mask:0xf
	v_mov_b32_dpp v229, v4 row_shr:2 row_mask:0xf bank_mask:0xf
	v_mov_b32_dpp v230, v5 row_shr:1 row_mask:0xf bank_mask:0xf
	v_mov_b32_dpp v231, v5 row_shr:2 row_mask:0xf bank_mask:0xf
	v_mov_b32_dpp v232, v6 row_shr:1 row_mask:0xf bank_mask:0xf
	v_mov_b32_dpp v233, v6 row_shr:2 row_mask:0xf bank_mask:0xf
	v_mov_b32_dpp v234, v7 row_shr:1 row_mask:0xf bank_mask:0xf
	v_mov_b32_dpp v235, v7 row_shr:2 row_mask:0xf bank_mask:0xf
	v_cndmask_b32_e64 v228, 0, v228, vcc
	v_cndmask_b32_e64 v229, 0, v229, s[8:9]
	v_cndmask_b32_e64 v230, 0, v230, vcc
	v_cndmask_b32_e64 v231, 0, v231, s[8:9]
	v_cndmask_b32_e64 v232, 0, v232, vcc
	v_cndmask_b32_e64 v233, 0, v233, s[8:9]
	v_cndmask_b32_e64 v234, 0, v234, vcc
	v_cndmask_b32_e64 v235, 0, v235, s[8:9]
	v_fma_f32 v236, v229, v128, v152
	v_fma_f32 v237, v231, v129, v153
	v_fma_f32 v238, v233, v130, v154
	v_fma_f32 v239, v235, v131, v155
	v_fmac_f32_e32 v236, v228, v136
	v_fmac_f32_e32 v237, v230, v137
	v_fmac_f32_e32 v238, v232, v138
	v_fmac_f32_e32 v239, v234, v139
	v_fmac_f32_e32 v236, v4, v144
	v_fmac_f32_e32 v237, v5, v145
	v_fmac_f32_e32 v238, v6, v146
	v_fmac_f32_e32 v239, v7, v147
	v_mov_b32_dpp v228, v20 row_ror:1 row_mask:0xf bank_mask:0xf
	v_mov_b32_dpp v229, v20 row_ror:2 row_mask:0xf bank_mask:0xf
	v_mov_b32_dpp v230, v21 row_ror:1 row_mask:0xf bank_mask:0xf
	v_mov_b32_dpp v231, v21 row_ror:2 row_mask:0xf bank_mask:0xf
	v_mov_b32_dpp v232, v22 row_ror:1 row_mask:0xf bank_mask:0xf
	v_mov_b32_dpp v233, v22 row_ror:2 row_mask:0xf bank_mask:0xf
	v_mov_b32_dpp v234, v23 row_ror:1 row_mask:0xf bank_mask:0xf
	v_mov_b32_dpp v235, v23 row_ror:2 row_mask:0xf bank_mask:0xf
	v_mov_b32_dpp v228, v8 row_shr:1 row_mask:0xf bank_mask:0xf
	v_mov_b32_dpp v229, v8 row_shr:2 row_mask:0xf bank_mask:0xf
	v_mov_b32_dpp v230, v9 row_shr:1 row_mask:0xf bank_mask:0xf
	v_mov_b32_dpp v231, v9 row_shr:2 row_mask:0xf bank_mask:0xf
	v_mov_b32_dpp v232, v10 row_shr:1 row_mask:0xf bank_mask:0xf
	v_mov_b32_dpp v233, v10 row_shr:2 row_mask:0xf bank_mask:0xf
	v_mov_b32_dpp v234, v11 row_shr:1 row_mask:0xf bank_mask:0xf
	v_mov_b32_dpp v235, v11 row_shr:2 row_mask:0xf bank_mask:0xf
	v_cndmask_b32_e64 v228, 0, v228, vcc
	v_cndmask_b32_e64 v229, 0, v229, s[8:9]
	v_cndmask_b32_e64 v230, 0, v230, vcc
	v_cndmask_b32_e64 v231, 0, v231, s[8:9]
	v_cndmask_b32_e64 v232, 0, v232, vcc
	v_cndmask_b32_e64 v233, 0, v233, s[8:9]
	v_cndmask_b32_e64 v234, 0, v234, vcc
	v_cndmask_b32_e64 v235, 0, v235, s[8:9]
	v_fma_f32 v240, v229, v132, v156
	v_fma_f32 v241, v231, v133, v157
	v_fma_f32 v242, v233, v134, v158
	v_fma_f32 v243, v235, v135, v159
	v_fmac_f32_e32 v240, v228, v140
	v_fmac_f32_e32 v241, v230, v141
	v_fmac_f32_e32 v242, v232, v142
	v_fmac_f32_e32 v243, v234, v143
	v_fmac_f32_e32 v240, v8, v148
	v_fmac_f32_e32 v241, v9, v149
	v_fmac_f32_e32 v242, v10, v150
	v_fmac_f32_e32 v243, v11, v151
	v_mov_b32_e32 v228, 0xbdd2d3e8
	v_mul_f32_e32 v244, v236, v236
	v_mul_f32_e32 v245, v237, v237
	v_mul_f32_e32 v246, v238, v238
	v_mul_f32_e32 v247, v239, v239
	v_fmaak_f32 v244, v244, v228, 0xc0135761
	v_fmaak_f32 v245, v245, v228, 0xc0135761
	v_fmaak_f32 v246, v246, v228, 0xc0135761
	v_fmaak_f32 v247, v247, v228, 0xc0135761
	v_mul_f32_e32 v244, v236, v244
	v_mul_f32_e32 v245, v237, v245
	v_mul_f32_e32 v246, v238, v246
	v_mul_f32_e32 v247, v239, v247
	v_exp_f32_e32 v244, v244
	v_exp_f32_e32 v245, v245
	v_exp_f32_e32 v246, v246
	v_exp_f32_e32 v247, v247
	v_add_f32_e32 v244, 1.0, v244
	v_add_f32_e32 v245, 1.0, v245
	v_add_f32_e32 v246, 1.0, v246
	v_add_f32_e32 v247, 1.0, v247
	v_rcp_f32_e32 v244, v244
	v_rcp_f32_e32 v245, v245
	v_rcp_f32_e32 v246, v246
	v_rcp_f32_e32 v247, v247
	v_mul_f32_e32 v244, v236, v244
	v_mul_f32_e32 v245, v237, v245
	v_mul_f32_e32 v246, v238, v246
	v_mul_f32_e32 v247, v239, v247
	v_mul_f32_e32 v248, v240, v244
	v_mul_f32_e32 v249, v241, v245
	v_mul_f32_e32 v250, v242, v246
	v_mul_f32_e32 v251, v243, v247
	v_cvt_pk_bf16_f32 v224, v248, v249
	v_cvt_pk_bf16_f32 v225, v250, v251
	s_branch .Lffn1e_join0_7
.Lffn1e_old0_7:
	v_mov_b32_dpp v228, v28 row_ror:1 row_mask:0xf bank_mask:0xf
	v_mov_b32_dpp v229, v28 row_ror:2 row_mask:0xf bank_mask:0xf
	v_mov_b32_dpp v230, v29 row_ror:1 row_mask:0xf bank_mask:0xf
	v_mov_b32_dpp v231, v29 row_ror:2 row_mask:0xf bank_mask:0xf
	v_mov_b32_dpp v232, v30 row_ror:1 row_mask:0xf bank_mask:0xf
	v_mov_b32_dpp v233, v30 row_ror:2 row_mask:0xf bank_mask:0xf
	v_mov_b32_dpp v234, v31 row_ror:1 row_mask:0xf bank_mask:0xf
	v_mov_b32_dpp v235, v31 row_ror:2 row_mask:0xf bank_mask:0xf
	v_mov_b32_dpp v228, v4 row_shr:1 row_mask:0xf bank_mask:0xf
	v_mov_b32_dpp v229, v4 row_shr:2 row_mask:0xf bank_mask:0xf
	v_mov_b32_dpp v230, v5 row_shr:1 row_mask:0xf bank_mask:0xf
	v_mov_b32_dpp v231, v5 row_shr:2 row_mask:0xf bank_mask:0xf
	v_mov_b32_dpp v232, v6 row_shr:1 row_mask:0xf bank_mask:0xf
	v_mov_b32_dpp v233, v6 row_shr:2 row_mask:0xf bank_mask:0xf
	v_mov_b32_dpp v234, v7 row_shr:1 row_mask:0xf bank_mask:0xf
	v_mov_b32_dpp v235, v7 row_shr:2 row_mask:0xf bank_mask:0xf
	v_fma_f32 v236, v229, v128, v152
	v_fma_f32 v237, v231, v129, v153
	v_fma_f32 v238, v233, v130, v154
	v_fma_f32 v239, v235, v131, v155
	v_fmac_f32_e32 v236, v228, v136
	v_fmac_f32_e32 v237, v230, v137
	v_fmac_f32_e32 v238, v232, v138
	v_fmac_f32_e32 v239, v234, v139
	v_fmac_f32_e32 v236, v4, v144
	v_fmac_f32_e32 v237, v5, v145
	v_fmac_f32_e32 v238, v6, v146
	v_fmac_f32_e32 v239, v7, v147
	v_mov_b32_dpp v228, v20 row_ror:1 row_mask:0xf bank_mask:0xf
	v_mov_b32_dpp v229, v20 row_ror:2 row_mask:0xf bank_mask:0xf
	v_mov_b32_dpp v230, v21 row_ror:1 row_mask:0xf bank_mask:0xf
	v_mov_b32_dpp v231, v21 row_ror:2 row_mask:0xf bank_mask:0xf
	v_mov_b32_dpp v232, v22 row_ror:1 row_mask:0xf bank_mask:0xf
	v_mov_b32_dpp v233, v22 row_ror:2 row_mask:0xf bank_mask:0xf
	v_mov_b32_dpp v234, v23 row_ror:1 row_mask:0xf bank_mask:0xf
	v_mov_b32_dpp v235, v23 row_ror:2 row_mask:0xf bank_mask:0xf
	v_mov_b32_dpp v228, v8 row_shr:1 row_mask:0xf bank_mask:0xf
	v_mov_b32_dpp v229, v8 row_shr:2 row_mask:0xf bank_mask:0xf
	v_mov_b32_dpp v230, v9 row_shr:1 row_mask:0xf bank_mask:0xf
	v_mov_b32_dpp v231, v9 row_shr:2 row_mask:0xf bank_mask:0xf
	v_mov_b32_dpp v232, v10 row_shr:1 row_mask:0xf bank_mask:0xf
	v_mov_b32_dpp v233, v10 row_shr:2 row_mask:0xf bank_mask:0xf
	v_mov_b32_dpp v234, v11 row_shr:1 row_mask:0xf bank_mask:0xf
	v_mov_b32_dpp v235, v11 row_shr:2 row_mask:0xf bank_mask:0xf
	v_fma_f32 v240, v229, v132, v156
	v_fma_f32 v241, v231, v133, v157
	v_fma_f32 v242, v233, v134, v158
	v_fma_f32 v243, v235, v135, v159
	v_fmac_f32_e32 v240, v228, v140
	v_fmac_f32_e32 v241, v230, v141
	v_fmac_f32_e32 v242, v232, v142
	v_fmac_f32_e32 v243, v234, v143
	v_fmac_f32_e32 v240, v8, v148
	v_fmac_f32_e32 v241, v9, v149
	v_fmac_f32_e32 v242, v10, v150
	v_fmac_f32_e32 v243, v11, v151
	v_mov_b32_e32 v228, 0xbdd2d3e8
	v_mul_f32_e32 v244, v236, v236
	v_mul_f32_e32 v245, v237, v237
	v_mul_f32_e32 v246, v238, v238
	v_mul_f32_e32 v247, v239, v239
	v_fmaak_f32 v244, v244, v228, 0xc0135761
	v_fmaak_f32 v245, v245, v228, 0xc0135761
	v_fmaak_f32 v246, v246, v228, 0xc0135761
	v_fmaak_f32 v247, v247, v228, 0xc0135761
	v_mul_f32_e32 v244, v236, v244
	v_mul_f32_e32 v245, v237, v245
	v_mul_f32_e32 v246, v238, v246
	v_mul_f32_e32 v247, v239, v247
	v_exp_f32_e32 v244, v244
	v_exp_f32_e32 v245, v245
	v_exp_f32_e32 v246, v246
	v_exp_f32_e32 v247, v247
	v_add_f32_e32 v244, 1.0, v244
	v_add_f32_e32 v245, 1.0, v245
	v_add_f32_e32 v246, 1.0, v246
	v_add_f32_e32 v247, 1.0, v247
	v_rcp_f32_e32 v244, v244
	v_rcp_f32_e32 v245, v245
	v_rcp_f32_e32 v246, v246
	v_rcp_f32_e32 v247, v247
	v_mul_f32_e32 v244, v236, v244
	v_mul_f32_e32 v245, v237, v245
	v_mul_f32_e32 v246, v238, v246
	v_mul_f32_e32 v247, v239, v247
	v_mul_f32_e32 v248, v240, v244
	v_mul_f32_e32 v249, v241, v245
	v_mul_f32_e32 v250, v242, v246
	v_mul_f32_e32 v251, v243, v247
	v_cvt_pk_bf16_f32 v224, v248, v249
	v_cvt_pk_bf16_f32 v225, v250, v251
	s_branch .Lffn1e_join0_7
.Lffn1e_slow1_0:
	v_add_u32_e32 v189, 2064, v218
	v_mul_hi_u32 v203, v189, s59
	v_lshrrev_b32_e32 v203, 7, v203
	v_mul_u32_u24_e32 v203, 0x810, v203
	v_sub_u32_e32 v189, v189, v203
	v_cmp_lt_u32_e32 vcc, 0, v189
	v_cmp_lt_u32_e64 s[8:9], 1, v189
	s_nop 1
	v_mov_b32_dpp v228, v120 row_shr:1 row_mask:0xf bank_mask:0xf bound_ctrl:1
	v_mov_b32_dpp v229, v120 row_shr:2 row_mask:0xf bank_mask:0xf bound_ctrl:1
	v_mov_b32_dpp v230, v121 row_shr:1 row_mask:0xf bank_mask:0xf bound_ctrl:1
	v_mov_b32_dpp v231, v121 row_shr:2 row_mask:0xf bank_mask:0xf bound_ctrl:1
	v_mov_b32_dpp v232, v122 row_shr:1 row_mask:0xf bank_mask:0xf bound_ctrl:1
	v_mov_b32_dpp v233, v122 row_shr:2 row_mask:0xf bank_mask:0xf bound_ctrl:1
	v_mov_b32_dpp v234, v123 row_shr:1 row_mask:0xf bank_mask:0xf bound_ctrl:1
	v_mov_b32_dpp v235, v123 row_shr:2 row_mask:0xf bank_mask:0xf bound_ctrl:1
	v_cndmask_b32_e64 v228, 0, v228, vcc
	v_cndmask_b32_e64 v229, 0, v229, s[8:9]
	v_cndmask_b32_e64 v230, 0, v230, vcc
	v_cndmask_b32_e64 v231, 0, v231, s[8:9]
	v_cndmask_b32_e64 v232, 0, v232, vcc
	v_cndmask_b32_e64 v233, 0, v233, s[8:9]
	v_cndmask_b32_e64 v234, 0, v234, vcc
	v_cndmask_b32_e64 v235, 0, v235, s[8:9]
	v_fma_f32 v236, v229, v128, v152
	v_fma_f32 v237, v231, v129, v153
	v_fma_f32 v238, v233, v130, v154
	v_fma_f32 v239, v235, v131, v155
	v_fmac_f32_e32 v236, v228, v136
	v_fmac_f32_e32 v237, v230, v137
	v_fmac_f32_e32 v238, v232, v138
	v_fmac_f32_e32 v239, v234, v139
	v_fmac_f32_e32 v236, v120, v144
	v_fmac_f32_e32 v237, v121, v145
	v_fmac_f32_e32 v238, v122, v146
	v_fmac_f32_e32 v239, v123, v147
	v_mov_b32_dpp v228, v112 row_shr:1 row_mask:0xf bank_mask:0xf bound_ctrl:1
	v_mov_b32_dpp v229, v112 row_shr:2 row_mask:0xf bank_mask:0xf bound_ctrl:1
	v_mov_b32_dpp v230, v113 row_shr:1 row_mask:0xf bank_mask:0xf bound_ctrl:1
	v_mov_b32_dpp v231, v113 row_shr:2 row_mask:0xf bank_mask:0xf bound_ctrl:1
	v_mov_b32_dpp v232, v114 row_shr:1 row_mask:0xf bank_mask:0xf bound_ctrl:1
	v_mov_b32_dpp v233, v114 row_shr:2 row_mask:0xf bank_mask:0xf bound_ctrl:1
	v_mov_b32_dpp v234, v115 row_shr:1 row_mask:0xf bank_mask:0xf bound_ctrl:1
	v_mov_b32_dpp v235, v115 row_shr:2 row_mask:0xf bank_mask:0xf bound_ctrl:1
	v_cndmask_b32_e64 v228, 0, v228, vcc
	v_cndmask_b32_e64 v229, 0, v229, s[8:9]
	v_cndmask_b32_e64 v230, 0, v230, vcc
	v_cndmask_b32_e64 v231, 0, v231, s[8:9]
	v_cndmask_b32_e64 v232, 0, v232, vcc
	v_cndmask_b32_e64 v233, 0, v233, s[8:9]
	v_cndmask_b32_e64 v234, 0, v234, vcc
	v_cndmask_b32_e64 v235, 0, v235, s[8:9]
	v_fma_f32 v240, v229, v132, v156
	v_fma_f32 v241, v231, v133, v157
	v_fma_f32 v242, v233, v134, v158
	v_fma_f32 v243, v235, v135, v159
	v_fmac_f32_e32 v240, v228, v140
	v_fmac_f32_e32 v241, v230, v141
	v_fmac_f32_e32 v242, v232, v142
	v_fmac_f32_e32 v243, v234, v143
	v_fmac_f32_e32 v240, v112, v148
	v_fmac_f32_e32 v241, v113, v149
	v_fmac_f32_e32 v242, v114, v150
	v_fmac_f32_e32 v243, v115, v151
	v_mov_b32_e32 v228, 0xbdd2d3e8
	v_mul_f32_e32 v244, v236, v236
	v_mul_f32_e32 v245, v237, v237
	v_mul_f32_e32 v246, v238, v238
	v_mul_f32_e32 v247, v239, v239
	v_fmaak_f32 v244, v244, v228, 0xc0135761
	v_fmaak_f32 v245, v245, v228, 0xc0135761
	v_fmaak_f32 v246, v246, v228, 0xc0135761
	v_fmaak_f32 v247, v247, v228, 0xc0135761
	v_mul_f32_e32 v244, v236, v244
	v_mul_f32_e32 v245, v237, v245
	v_mul_f32_e32 v246, v238, v246
	v_mul_f32_e32 v247, v239, v247
	v_exp_f32_e32 v244, v244
	v_exp_f32_e32 v245, v245
	v_exp_f32_e32 v246, v246
	v_exp_f32_e32 v247, v247
	v_add_f32_e32 v244, 1.0, v244
	v_add_f32_e32 v245, 1.0, v245
	v_add_f32_e32 v246, 1.0, v246
	v_add_f32_e32 v247, 1.0, v247
	v_rcp_f32_e32 v244, v244
	v_rcp_f32_e32 v245, v245
	v_rcp_f32_e32 v246, v246
	v_rcp_f32_e32 v247, v247
	v_mul_f32_e32 v244, v236, v244
	v_mul_f32_e32 v245, v237, v245
	v_mul_f32_e32 v246, v238, v246
	v_mul_f32_e32 v247, v239, v247
	v_mul_f32_e32 v248, v240, v244
	v_mul_f32_e32 v249, v241, v245
	v_mul_f32_e32 v250, v242, v246
	v_mul_f32_e32 v251, v243, v247
	v_mov_b32_e32 v180, v208
	v_mov_b32_e32 v181, v209
	v_cvt_pk_bf16_f32 v182, v248, v249
	v_cvt_pk_bf16_f32 v183, v250, v251
	s_branch .Lffn1e_join1_0
.Lffn1e_slow1_1:
	v_add_u32_e32 v189, 2080, v218
	v_mul_hi_u32 v203, v189, s59
	v_lshrrev_b32_e32 v203, 7, v203
	v_mul_u32_u24_e32 v203, 0x810, v203
	v_sub_u32_e32 v189, v189, v203
	v_cmp_lt_u32_e32 vcc, 0, v189
	v_cmp_lt_u32_e64 s[8:9], 1, v189
	s_nop 1
	v_mov_b32_dpp v228, v120 row_ror:1 row_mask:0xf bank_mask:0xf
	v_mov_b32_dpp v229, v120 row_ror:2 row_mask:0xf bank_mask:0xf
	v_mov_b32_dpp v230, v121 row_ror:1 row_mask:0xf bank_mask:0xf
	v_mov_b32_dpp v231, v121 row_ror:2 row_mask:0xf bank_mask:0xf
	v_mov_b32_dpp v232, v122 row_ror:1 row_mask:0xf bank_mask:0xf
	v_mov_b32_dpp v233, v122 row_ror:2 row_mask:0xf bank_mask:0xf
	v_mov_b32_dpp v234, v123 row_ror:1 row_mask:0xf bank_mask:0xf
	v_mov_b32_dpp v235, v123 row_ror:2 row_mask:0xf bank_mask:0xf
	v_mov_b32_dpp v228, v104 row_shr:1 row_mask:0xf bank_mask:0xf
	v_mov_b32_dpp v229, v104 row_shr:2 row_mask:0xf bank_mask:0xf
	v_mov_b32_dpp v230, v105 row_shr:1 row_mask:0xf bank_mask:0xf
	v_mov_b32_dpp v231, v105 row_shr:2 row_mask:0xf bank_mask:0xf
	v_mov_b32_dpp v232, v106 row_shr:1 row_mask:0xf bank_mask:0xf
	v_mov_b32_dpp v233, v106 row_shr:2 row_mask:0xf bank_mask:0xf
	v_mov_b32_dpp v234, v107 row_shr:1 row_mask:0xf bank_mask:0xf
	v_mov_b32_dpp v235, v107 row_shr:2 row_mask:0xf bank_mask:0xf
	v_cndmask_b32_e64 v228, 0, v228, vcc
	v_cndmask_b32_e64 v229, 0, v229, s[8:9]
	v_cndmask_b32_e64 v230, 0, v230, vcc
	v_cndmask_b32_e64 v231, 0, v231, s[8:9]
	v_cndmask_b32_e64 v232, 0, v232, vcc
	v_cndmask_b32_e64 v233, 0, v233, s[8:9]
	v_cndmask_b32_e64 v234, 0, v234, vcc
	v_cndmask_b32_e64 v235, 0, v235, s[8:9]
	v_fma_f32 v236, v229, v128, v152
	v_fma_f32 v237, v231, v129, v153
	v_fma_f32 v238, v233, v130, v154
	v_fma_f32 v239, v235, v131, v155
	v_fmac_f32_e32 v236, v228, v136
	v_fmac_f32_e32 v237, v230, v137
	v_fmac_f32_e32 v238, v232, v138
	v_fmac_f32_e32 v239, v234, v139
	v_fmac_f32_e32 v236, v104, v144
	v_fmac_f32_e32 v237, v105, v145
	v_fmac_f32_e32 v238, v106, v146
	v_fmac_f32_e32 v239, v107, v147
	v_mov_b32_dpp v228, v112 row_ror:1 row_mask:0xf bank_mask:0xf
	v_mov_b32_dpp v229, v112 row_ror:2 row_mask:0xf bank_mask:0xf
	v_mov_b32_dpp v230, v113 row_ror:1 row_mask:0xf bank_mask:0xf
	v_mov_b32_dpp v231, v113 row_ror:2 row_mask:0xf bank_mask:0xf
	v_mov_b32_dpp v232, v114 row_ror:1 row_mask:0xf bank_mask:0xf
	v_mov_b32_dpp v233, v114 row_ror:2 row_mask:0xf bank_mask:0xf
	v_mov_b32_dpp v234, v115 row_ror:1 row_mask:0xf bank_mask:0xf
	v_mov_b32_dpp v235, v115 row_ror:2 row_mask:0xf bank_mask:0xf
	v_mov_b32_dpp v228, v96 row_shr:1 row_mask:0xf bank_mask:0xf
	v_mov_b32_dpp v229, v96 row_shr:2 row_mask:0xf bank_mask:0xf
	v_mov_b32_dpp v230, v97 row_shr:1 row_mask:0xf bank_mask:0xf
	v_mov_b32_dpp v231, v97 row_shr:2 row_mask:0xf bank_mask:0xf
	v_mov_b32_dpp v232, v98 row_shr:1 row_mask:0xf bank_mask:0xf
	v_mov_b32_dpp v233, v98 row_shr:2 row_mask:0xf bank_mask:0xf
	v_mov_b32_dpp v234, v99 row_shr:1 row_mask:0xf bank_mask:0xf
	v_mov_b32_dpp v235, v99 row_shr:2 row_mask:0xf bank_mask:0xf
	v_cndmask_b32_e64 v228, 0, v228, vcc
	v_cndmask_b32_e64 v229, 0, v229, s[8:9]
	v_cndmask_b32_e64 v230, 0, v230, vcc
	v_cndmask_b32_e64 v231, 0, v231, s[8:9]
	v_cndmask_b32_e64 v232, 0, v232, vcc
	v_cndmask_b32_e64 v233, 0, v233, s[8:9]
	v_cndmask_b32_e64 v234, 0, v234, vcc
	v_cndmask_b32_e64 v235, 0, v235, s[8:9]
	v_fma_f32 v240, v229, v132, v156
	v_fma_f32 v241, v231, v133, v157
	v_fma_f32 v242, v233, v134, v158
	v_fma_f32 v243, v235, v135, v159
	v_fmac_f32_e32 v240, v228, v140
	v_fmac_f32_e32 v241, v230, v141
	v_fmac_f32_e32 v242, v232, v142
	v_fmac_f32_e32 v243, v234, v143
	v_fmac_f32_e32 v240, v96, v148
	v_fmac_f32_e32 v241, v97, v149
	v_fmac_f32_e32 v242, v98, v150
	v_fmac_f32_e32 v243, v99, v151
	v_mov_b32_e32 v228, 0xbdd2d3e8
	v_mul_f32_e32 v244, v236, v236
	v_mul_f32_e32 v245, v237, v237
	v_mul_f32_e32 v246, v238, v238
	v_mul_f32_e32 v247, v239, v239
	v_fmaak_f32 v244, v244, v228, 0xc0135761
	v_fmaak_f32 v245, v245, v228, 0xc0135761
	v_fmaak_f32 v246, v246, v228, 0xc0135761
	v_fmaak_f32 v247, v247, v228, 0xc0135761
	v_mul_f32_e32 v244, v236, v244
	v_mul_f32_e32 v245, v237, v245
	v_mul_f32_e32 v246, v238, v246
	v_mul_f32_e32 v247, v239, v247
	v_exp_f32_e32 v244, v244
	v_exp_f32_e32 v245, v245
	v_exp_f32_e32 v246, v246
	v_exp_f32_e32 v247, v247
	v_add_f32_e32 v244, 1.0, v244
	v_add_f32_e32 v245, 1.0, v245
	v_add_f32_e32 v246, 1.0, v246
	v_add_f32_e32 v247, 1.0, v247
	v_rcp_f32_e32 v244, v244
	v_rcp_f32_e32 v245, v245
	v_rcp_f32_e32 v246, v246
	v_rcp_f32_e32 v247, v247
	v_mul_f32_e32 v244, v236, v244
	v_mul_f32_e32 v245, v237, v245
	v_mul_f32_e32 v246, v238, v246
	v_mul_f32_e32 v247, v239, v247
	v_mul_f32_e32 v248, v240, v244
	v_mul_f32_e32 v249, v241, v245
	v_mul_f32_e32 v250, v242, v246
	v_mul_f32_e32 v251, v243, v247
	v_mov_b32_e32 v180, v210
	v_mov_b32_e32 v181, v211
	v_cvt_pk_bf16_f32 v182, v248, v249
	v_cvt_pk_bf16_f32 v183, v250, v251
	s_branch .Lffn1e_join1_1
.Lffn1e_old1_1:
	v_mov_b32_dpp v228, v120 row_ror:1 row_mask:0xf bank_mask:0xf
	v_mov_b32_dpp v229, v120 row_ror:2 row_mask:0xf bank_mask:0xf
	v_mov_b32_dpp v230, v121 row_ror:1 row_mask:0xf bank_mask:0xf
	v_mov_b32_dpp v231, v121 row_ror:2 row_mask:0xf bank_mask:0xf
	v_mov_b32_dpp v232, v122 row_ror:1 row_mask:0xf bank_mask:0xf
	v_mov_b32_dpp v233, v122 row_ror:2 row_mask:0xf bank_mask:0xf
	v_mov_b32_dpp v234, v123 row_ror:1 row_mask:0xf bank_mask:0xf
	v_mov_b32_dpp v235, v123 row_ror:2 row_mask:0xf bank_mask:0xf
	v_mov_b32_dpp v228, v104 row_shr:1 row_mask:0xf bank_mask:0xf
	v_mov_b32_dpp v229, v104 row_shr:2 row_mask:0xf bank_mask:0xf
	v_mov_b32_dpp v230, v105 row_shr:1 row_mask:0xf bank_mask:0xf
	v_mov_b32_dpp v231, v105 row_shr:2 row_mask:0xf bank_mask:0xf
	v_mov_b32_dpp v232, v106 row_shr:1 row_mask:0xf bank_mask:0xf
	v_mov_b32_dpp v233, v106 row_shr:2 row_mask:0xf bank_mask:0xf
	v_mov_b32_dpp v234, v107 row_shr:1 row_mask:0xf bank_mask:0xf
	v_mov_b32_dpp v235, v107 row_shr:2 row_mask:0xf bank_mask:0xf
	v_fma_f32 v236, v229, v128, v152
	v_fma_f32 v237, v231, v129, v153
	v_fma_f32 v238, v233, v130, v154
	v_fma_f32 v239, v235, v131, v155
	v_fmac_f32_e32 v236, v228, v136
	v_fmac_f32_e32 v237, v230, v137
	v_fmac_f32_e32 v238, v232, v138
	v_fmac_f32_e32 v239, v234, v139
	v_fmac_f32_e32 v236, v104, v144
	v_fmac_f32_e32 v237, v105, v145
	v_fmac_f32_e32 v238, v106, v146
	v_fmac_f32_e32 v239, v107, v147
	v_mov_b32_dpp v228, v112 row_ror:1 row_mask:0xf bank_mask:0xf
	v_mov_b32_dpp v229, v112 row_ror:2 row_mask:0xf bank_mask:0xf
	v_mov_b32_dpp v230, v113 row_ror:1 row_mask:0xf bank_mask:0xf
	v_mov_b32_dpp v231, v113 row_ror:2 row_mask:0xf bank_mask:0xf
	v_mov_b32_dpp v232, v114 row_ror:1 row_mask:0xf bank_mask:0xf
	v_mov_b32_dpp v233, v114 row_ror:2 row_mask:0xf bank_mask:0xf
	v_mov_b32_dpp v234, v115 row_ror:1 row_mask:0xf bank_mask:0xf
	v_mov_b32_dpp v235, v115 row_ror:2 row_mask:0xf bank_mask:0xf
	v_mov_b32_dpp v228, v96 row_shr:1 row_mask:0xf bank_mask:0xf
	v_mov_b32_dpp v229, v96 row_shr:2 row_mask:0xf bank_mask:0xf
	v_mov_b32_dpp v230, v97 row_shr:1 row_mask:0xf bank_mask:0xf
	v_mov_b32_dpp v231, v97 row_shr:2 row_mask:0xf bank_mask:0xf
	v_mov_b32_dpp v232, v98 row_shr:1 row_mask:0xf bank_mask:0xf
	v_mov_b32_dpp v233, v98 row_shr:2 row_mask:0xf bank_mask:0xf
	v_mov_b32_dpp v234, v99 row_shr:1 row_mask:0xf bank_mask:0xf
	v_mov_b32_dpp v235, v99 row_shr:2 row_mask:0xf bank_mask:0xf
	v_fma_f32 v240, v229, v132, v156
	v_fma_f32 v241, v231, v133, v157
	v_fma_f32 v242, v233, v134, v158
	v_fma_f32 v243, v235, v135, v159
	v_fmac_f32_e32 v240, v228, v140
	v_fmac_f32_e32 v241, v230, v141
	v_fmac_f32_e32 v242, v232, v142
	v_fmac_f32_e32 v243, v234, v143
	v_fmac_f32_e32 v240, v96, v148
	v_fmac_f32_e32 v241, v97, v149
	v_fmac_f32_e32 v242, v98, v150
	v_fmac_f32_e32 v243, v99, v151
	v_mov_b32_e32 v228, 0xbdd2d3e8
	v_mul_f32_e32 v244, v236, v236
	v_mul_f32_e32 v245, v237, v237
	v_mul_f32_e32 v246, v238, v238
	v_mul_f32_e32 v247, v239, v239
	v_fmaak_f32 v244, v244, v228, 0xc0135761
	v_fmaak_f32 v245, v245, v228, 0xc0135761
	v_fmaak_f32 v246, v246, v228, 0xc0135761
	v_fmaak_f32 v247, v247, v228, 0xc0135761
	v_mul_f32_e32 v244, v236, v244
	v_mul_f32_e32 v245, v237, v245
	v_mul_f32_e32 v246, v238, v246
	v_mul_f32_e32 v247, v239, v247
	v_exp_f32_e32 v244, v244
	v_exp_f32_e32 v245, v245
	v_exp_f32_e32 v246, v246
	v_exp_f32_e32 v247, v247
	v_add_f32_e32 v244, 1.0, v244
	v_add_f32_e32 v245, 1.0, v245
	v_add_f32_e32 v246, 1.0, v246
	v_add_f32_e32 v247, 1.0, v247
	v_rcp_f32_e32 v244, v244
	v_rcp_f32_e32 v245, v245
	v_rcp_f32_e32 v246, v246
	v_rcp_f32_e32 v247, v247
	v_mul_f32_e32 v244, v236, v244
	v_mul_f32_e32 v245, v237, v245
	v_mul_f32_e32 v246, v238, v246
	v_mul_f32_e32 v247, v239, v247
	v_mul_f32_e32 v248, v240, v244
	v_mul_f32_e32 v249, v241, v245
	v_mul_f32_e32 v250, v242, v246
	v_mul_f32_e32 v251, v243, v247
	v_mov_b32_e32 v180, v210
	v_mov_b32_e32 v181, v211
	v_cvt_pk_bf16_f32 v182, v248, v249
	v_cvt_pk_bf16_f32 v183, v250, v251
	s_branch .Lffn1e_join1_1
.Lffn1e_slow1_2:
	v_add_u32_e32 v189, 2096, v218
	v_mul_hi_u32 v203, v189, s59
	v_lshrrev_b32_e32 v203, 7, v203
	v_mul_u32_u24_e32 v203, 0x810, v203
	v_sub_u32_e32 v189, v189, v203
	v_cmp_lt_u32_e32 vcc, 0, v189
	v_cmp_lt_u32_e64 s[8:9], 1, v189
	s_nop 1
	v_mov_b32_dpp v228, v104 row_ror:1 row_mask:0xf bank_mask:0xf
	v_mov_b32_dpp v229, v104 row_ror:2 row_mask:0xf bank_mask:0xf
	v_mov_b32_dpp v230, v105 row_ror:1 row_mask:0xf bank_mask:0xf
	v_mov_b32_dpp v231, v105 row_ror:2 row_mask:0xf bank_mask:0xf
	v_mov_b32_dpp v232, v106 row_ror:1 row_mask:0xf bank_mask:0xf
	v_mov_b32_dpp v233, v106 row_ror:2 row_mask:0xf bank_mask:0xf
	v_mov_b32_dpp v234, v107 row_ror:1 row_mask:0xf bank_mask:0xf
	v_mov_b32_dpp v235, v107 row_ror:2 row_mask:0xf bank_mask:0xf
	v_mov_b32_dpp v228, v88 row_shr:1 row_mask:0xf bank_mask:0xf
	v_mov_b32_dpp v229, v88 row_shr:2 row_mask:0xf bank_mask:0xf
	v_mov_b32_dpp v230, v89 row_shr:1 row_mask:0xf bank_mask:0xf
	v_mov_b32_dpp v231, v89 row_shr:2 row_mask:0xf bank_mask:0xf
	v_mov_b32_dpp v232, v90 row_shr:1 row_mask:0xf bank_mask:0xf
	v_mov_b32_dpp v233, v90 row_shr:2 row_mask:0xf bank_mask:0xf
	v_mov_b32_dpp v234, v91 row_shr:1 row_mask:0xf bank_mask:0xf
	v_mov_b32_dpp v235, v91 row_shr:2 row_mask:0xf bank_mask:0xf
	v_cndmask_b32_e64 v228, 0, v228, vcc
	v_cndmask_b32_e64 v229, 0, v229, s[8:9]
	v_cndmask_b32_e64 v230, 0, v230, vcc
	v_cndmask_b32_e64 v231, 0, v231, s[8:9]
	v_cndmask_b32_e64 v232, 0, v232, vcc
	v_cndmask_b32_e64 v233, 0, v233, s[8:9]
	v_cndmask_b32_e64 v234, 0, v234, vcc
	v_cndmask_b32_e64 v235, 0, v235, s[8:9]
	v_fma_f32 v236, v229, v128, v152
	v_fma_f32 v237, v231, v129, v153
	v_fma_f32 v238, v233, v130, v154
	v_fma_f32 v239, v235, v131, v155
	v_fmac_f32_e32 v236, v228, v136
	v_fmac_f32_e32 v237, v230, v137
	v_fmac_f32_e32 v238, v232, v138
	v_fmac_f32_e32 v239, v234, v139
	v_fmac_f32_e32 v236, v88, v144
	v_fmac_f32_e32 v237, v89, v145
	v_fmac_f32_e32 v238, v90, v146
	v_fmac_f32_e32 v239, v91, v147
	v_mov_b32_dpp v228, v96 row_ror:1 row_mask:0xf bank_mask:0xf
	v_mov_b32_dpp v229, v96 row_ror:2 row_mask:0xf bank_mask:0xf
	v_mov_b32_dpp v230, v97 row_ror:1 row_mask:0xf bank_mask:0xf
	v_mov_b32_dpp v231, v97 row_ror:2 row_mask:0xf bank_mask:0xf
	v_mov_b32_dpp v232, v98 row_ror:1 row_mask:0xf bank_mask:0xf
	v_mov_b32_dpp v233, v98 row_ror:2 row_mask:0xf bank_mask:0xf
	v_mov_b32_dpp v234, v99 row_ror:1 row_mask:0xf bank_mask:0xf
	v_mov_b32_dpp v235, v99 row_ror:2 row_mask:0xf bank_mask:0xf
	v_mov_b32_dpp v228, v80 row_shr:1 row_mask:0xf bank_mask:0xf
	v_mov_b32_dpp v229, v80 row_shr:2 row_mask:0xf bank_mask:0xf
	v_mov_b32_dpp v230, v81 row_shr:1 row_mask:0xf bank_mask:0xf
	v_mov_b32_dpp v231, v81 row_shr:2 row_mask:0xf bank_mask:0xf
	v_mov_b32_dpp v232, v82 row_shr:1 row_mask:0xf bank_mask:0xf
	v_mov_b32_dpp v233, v82 row_shr:2 row_mask:0xf bank_mask:0xf
	v_mov_b32_dpp v234, v83 row_shr:1 row_mask:0xf bank_mask:0xf
	v_mov_b32_dpp v235, v83 row_shr:2 row_mask:0xf bank_mask:0xf
	v_cndmask_b32_e64 v228, 0, v228, vcc
	v_cndmask_b32_e64 v229, 0, v229, s[8:9]
	v_cndmask_b32_e64 v230, 0, v230, vcc
	v_cndmask_b32_e64 v231, 0, v231, s[8:9]
	v_cndmask_b32_e64 v232, 0, v232, vcc
	v_cndmask_b32_e64 v233, 0, v233, s[8:9]
	v_cndmask_b32_e64 v234, 0, v234, vcc
	v_cndmask_b32_e64 v235, 0, v235, s[8:9]
	v_fma_f32 v240, v229, v132, v156
	v_fma_f32 v241, v231, v133, v157
	v_fma_f32 v242, v233, v134, v158
	v_fma_f32 v243, v235, v135, v159
	v_fmac_f32_e32 v240, v228, v140
	v_fmac_f32_e32 v241, v230, v141
	v_fmac_f32_e32 v242, v232, v142
	v_fmac_f32_e32 v243, v234, v143
	v_fmac_f32_e32 v240, v80, v148
	v_fmac_f32_e32 v241, v81, v149
	v_fmac_f32_e32 v242, v82, v150
	v_fmac_f32_e32 v243, v83, v151
	v_mov_b32_e32 v228, 0xbdd2d3e8
	v_mul_f32_e32 v244, v236, v236
	v_mul_f32_e32 v245, v237, v237
	v_mul_f32_e32 v246, v238, v238
	v_mul_f32_e32 v247, v239, v239
	v_fmaak_f32 v244, v244, v228, 0xc0135761
	v_fmaak_f32 v245, v245, v228, 0xc0135761
	v_fmaak_f32 v246, v246, v228, 0xc0135761
	v_fmaak_f32 v247, v247, v228, 0xc0135761
	v_mul_f32_e32 v244, v236, v244
	v_mul_f32_e32 v245, v237, v245
	v_mul_f32_e32 v246, v238, v246
	v_mul_f32_e32 v247, v239, v247
	v_exp_f32_e32 v244, v244
	v_exp_f32_e32 v245, v245
	v_exp_f32_e32 v246, v246
	v_exp_f32_e32 v247, v247
	v_add_f32_e32 v244, 1.0, v244
	v_add_f32_e32 v245, 1.0, v245
	v_add_f32_e32 v246, 1.0, v246
	v_add_f32_e32 v247, 1.0, v247
	v_rcp_f32_e32 v244, v244
	v_rcp_f32_e32 v245, v245
	v_rcp_f32_e32 v246, v246
	v_rcp_f32_e32 v247, v247
	v_mul_f32_e32 v244, v236, v244
	v_mul_f32_e32 v245, v237, v245
	v_mul_f32_e32 v246, v238, v246
	v_mul_f32_e32 v247, v239, v247
	v_mul_f32_e32 v248, v240, v244
	v_mul_f32_e32 v249, v241, v245
	v_mul_f32_e32 v250, v242, v246
	v_mul_f32_e32 v251, v243, v247
	v_mov_b32_e32 v180, v212
	v_mov_b32_e32 v181, v213
	v_cvt_pk_bf16_f32 v182, v248, v249
	v_cvt_pk_bf16_f32 v183, v250, v251
	s_branch .Lffn1e_join1_2
.Lffn1e_old1_2:
	v_mov_b32_dpp v228, v104 row_ror:1 row_mask:0xf bank_mask:0xf
	v_mov_b32_dpp v229, v104 row_ror:2 row_mask:0xf bank_mask:0xf
	v_mov_b32_dpp v230, v105 row_ror:1 row_mask:0xf bank_mask:0xf
	v_mov_b32_dpp v231, v105 row_ror:2 row_mask:0xf bank_mask:0xf
	v_mov_b32_dpp v232, v106 row_ror:1 row_mask:0xf bank_mask:0xf
	v_mov_b32_dpp v233, v106 row_ror:2 row_mask:0xf bank_mask:0xf
	v_mov_b32_dpp v234, v107 row_ror:1 row_mask:0xf bank_mask:0xf
	v_mov_b32_dpp v235, v107 row_ror:2 row_mask:0xf bank_mask:0xf
	v_mov_b32_dpp v228, v88 row_shr:1 row_mask:0xf bank_mask:0xf
	v_mov_b32_dpp v229, v88 row_shr:2 row_mask:0xf bank_mask:0xf
	v_mov_b32_dpp v230, v89 row_shr:1 row_mask:0xf bank_mask:0xf
	v_mov_b32_dpp v231, v89 row_shr:2 row_mask:0xf bank_mask:0xf
	v_mov_b32_dpp v232, v90 row_shr:1 row_mask:0xf bank_mask:0xf
	v_mov_b32_dpp v233, v90 row_shr:2 row_mask:0xf bank_mask:0xf
	v_mov_b32_dpp v234, v91 row_shr:1 row_mask:0xf bank_mask:0xf
	v_mov_b32_dpp v235, v91 row_shr:2 row_mask:0xf bank_mask:0xf
	v_fma_f32 v236, v229, v128, v152
	v_fma_f32 v237, v231, v129, v153
	v_fma_f32 v238, v233, v130, v154
	v_fma_f32 v239, v235, v131, v155
	v_fmac_f32_e32 v236, v228, v136
	v_fmac_f32_e32 v237, v230, v137
	v_fmac_f32_e32 v238, v232, v138
	v_fmac_f32_e32 v239, v234, v139
	v_fmac_f32_e32 v236, v88, v144
	v_fmac_f32_e32 v237, v89, v145
	v_fmac_f32_e32 v238, v90, v146
	v_fmac_f32_e32 v239, v91, v147
	v_mov_b32_dpp v228, v96 row_ror:1 row_mask:0xf bank_mask:0xf
	v_mov_b32_dpp v229, v96 row_ror:2 row_mask:0xf bank_mask:0xf
	v_mov_b32_dpp v230, v97 row_ror:1 row_mask:0xf bank_mask:0xf
	v_mov_b32_dpp v231, v97 row_ror:2 row_mask:0xf bank_mask:0xf
	v_mov_b32_dpp v232, v98 row_ror:1 row_mask:0xf bank_mask:0xf
	v_mov_b32_dpp v233, v98 row_ror:2 row_mask:0xf bank_mask:0xf
	v_mov_b32_dpp v234, v99 row_ror:1 row_mask:0xf bank_mask:0xf
	v_mov_b32_dpp v235, v99 row_ror:2 row_mask:0xf bank_mask:0xf
	v_mov_b32_dpp v228, v80 row_shr:1 row_mask:0xf bank_mask:0xf
	v_mov_b32_dpp v229, v80 row_shr:2 row_mask:0xf bank_mask:0xf
	v_mov_b32_dpp v230, v81 row_shr:1 row_mask:0xf bank_mask:0xf
	v_mov_b32_dpp v231, v81 row_shr:2 row_mask:0xf bank_mask:0xf
	v_mov_b32_dpp v232, v82 row_shr:1 row_mask:0xf bank_mask:0xf
	v_mov_b32_dpp v233, v82 row_shr:2 row_mask:0xf bank_mask:0xf
	v_mov_b32_dpp v234, v83 row_shr:1 row_mask:0xf bank_mask:0xf
	v_mov_b32_dpp v235, v83 row_shr:2 row_mask:0xf bank_mask:0xf
	v_fma_f32 v240, v229, v132, v156
	v_fma_f32 v241, v231, v133, v157
	v_fma_f32 v242, v233, v134, v158
	v_fma_f32 v243, v235, v135, v159
	v_fmac_f32_e32 v240, v228, v140
	v_fmac_f32_e32 v241, v230, v141
	v_fmac_f32_e32 v242, v232, v142
	v_fmac_f32_e32 v243, v234, v143
	v_fmac_f32_e32 v240, v80, v148
	v_fmac_f32_e32 v241, v81, v149
	v_fmac_f32_e32 v242, v82, v150
	v_fmac_f32_e32 v243, v83, v151
	v_mov_b32_e32 v228, 0xbdd2d3e8
	v_mul_f32_e32 v244, v236, v236
	v_mul_f32_e32 v245, v237, v237
	v_mul_f32_e32 v246, v238, v238
	v_mul_f32_e32 v247, v239, v239
	v_fmaak_f32 v244, v244, v228, 0xc0135761
	v_fmaak_f32 v245, v245, v228, 0xc0135761
	v_fmaak_f32 v246, v246, v228, 0xc0135761
	v_fmaak_f32 v247, v247, v228, 0xc0135761
	v_mul_f32_e32 v244, v236, v244
	v_mul_f32_e32 v245, v237, v245
	v_mul_f32_e32 v246, v238, v246
	v_mul_f32_e32 v247, v239, v247
	v_exp_f32_e32 v244, v244
	v_exp_f32_e32 v245, v245
	v_exp_f32_e32 v246, v246
	v_exp_f32_e32 v247, v247
	v_add_f32_e32 v244, 1.0, v244
	v_add_f32_e32 v245, 1.0, v245
	v_add_f32_e32 v246, 1.0, v246
	v_add_f32_e32 v247, 1.0, v247
	v_rcp_f32_e32 v244, v244
	v_rcp_f32_e32 v245, v245
	v_rcp_f32_e32 v246, v246
	v_rcp_f32_e32 v247, v247
	v_mul_f32_e32 v244, v236, v244
	v_mul_f32_e32 v245, v237, v245
	v_mul_f32_e32 v246, v238, v246
	v_mul_f32_e32 v247, v239, v247
	v_mul_f32_e32 v248, v240, v244
	v_mul_f32_e32 v249, v241, v245
	v_mul_f32_e32 v250, v242, v246
	v_mul_f32_e32 v251, v243, v247
	v_mov_b32_e32 v180, v212
	v_mov_b32_e32 v181, v213
	v_cvt_pk_bf16_f32 v182, v248, v249
	v_cvt_pk_bf16_f32 v183, v250, v251
	s_branch .Lffn1e_join1_2
.Lffn1e_slow1_3:
	v_add_u32_e32 v189, 2112, v218
	v_mul_hi_u32 v203, v189, s59
	v_lshrrev_b32_e32 v203, 7, v203
	v_mul_u32_u24_e32 v203, 0x810, v203
	v_sub_u32_e32 v189, v189, v203
	v_cmp_lt_u32_e32 vcc, 0, v189
	v_cmp_lt_u32_e64 s[8:9], 1, v189
	s_nop 1
	v_mov_b32_dpp v228, v88 row_ror:1 row_mask:0xf bank_mask:0xf
	v_mov_b32_dpp v229, v88 row_ror:2 row_mask:0xf bank_mask:0xf
	v_mov_b32_dpp v230, v89 row_ror:1 row_mask:0xf bank_mask:0xf
	v_mov_b32_dpp v231, v89 row_ror:2 row_mask:0xf bank_mask:0xf
	v_mov_b32_dpp v232, v90 row_ror:1 row_mask:0xf bank_mask:0xf
	v_mov_b32_dpp v233, v90 row_ror:2 row_mask:0xf bank_mask:0xf
	v_mov_b32_dpp v234, v91 row_ror:1 row_mask:0xf bank_mask:0xf
	v_mov_b32_dpp v235, v91 row_ror:2 row_mask:0xf bank_mask:0xf
	v_mov_b32_dpp v228, v72 row_shr:1 row_mask:0xf bank_mask:0xf
	v_mov_b32_dpp v229, v72 row_shr:2 row_mask:0xf bank_mask:0xf
	v_mov_b32_dpp v230, v73 row_shr:1 row_mask:0xf bank_mask:0xf
	v_mov_b32_dpp v231, v73 row_shr:2 row_mask:0xf bank_mask:0xf
	v_mov_b32_dpp v232, v74 row_shr:1 row_mask:0xf bank_mask:0xf
	v_mov_b32_dpp v233, v74 row_shr:2 row_mask:0xf bank_mask:0xf
	v_mov_b32_dpp v234, v75 row_shr:1 row_mask:0xf bank_mask:0xf
	v_mov_b32_dpp v235, v75 row_shr:2 row_mask:0xf bank_mask:0xf
	v_cndmask_b32_e64 v228, 0, v228, vcc
	v_cndmask_b32_e64 v229, 0, v229, s[8:9]
	v_cndmask_b32_e64 v230, 0, v230, vcc
	v_cndmask_b32_e64 v231, 0, v231, s[8:9]
	v_cndmask_b32_e64 v232, 0, v232, vcc
	v_cndmask_b32_e64 v233, 0, v233, s[8:9]
	v_cndmask_b32_e64 v234, 0, v234, vcc
	v_cndmask_b32_e64 v235, 0, v235, s[8:9]
	v_fma_f32 v236, v229, v128, v152
	v_fma_f32 v237, v231, v129, v153
	v_fma_f32 v238, v233, v130, v154
	v_fma_f32 v239, v235, v131, v155
	v_fmac_f32_e32 v236, v228, v136
	v_fmac_f32_e32 v237, v230, v137
	v_fmac_f32_e32 v238, v232, v138
	v_fmac_f32_e32 v239, v234, v139
	v_fmac_f32_e32 v236, v72, v144
	v_fmac_f32_e32 v237, v73, v145
	v_fmac_f32_e32 v238, v74, v146
	v_fmac_f32_e32 v239, v75, v147
	v_mov_b32_dpp v228, v80 row_ror:1 row_mask:0xf bank_mask:0xf
	v_mov_b32_dpp v229, v80 row_ror:2 row_mask:0xf bank_mask:0xf
	v_mov_b32_dpp v230, v81 row_ror:1 row_mask:0xf bank_mask:0xf
	v_mov_b32_dpp v231, v81 row_ror:2 row_mask:0xf bank_mask:0xf
	v_mov_b32_dpp v232, v82 row_ror:1 row_mask:0xf bank_mask:0xf
	v_mov_b32_dpp v233, v82 row_ror:2 row_mask:0xf bank_mask:0xf
	v_mov_b32_dpp v234, v83 row_ror:1 row_mask:0xf bank_mask:0xf
	v_mov_b32_dpp v235, v83 row_ror:2 row_mask:0xf bank_mask:0xf
	v_mov_b32_dpp v228, v64 row_shr:1 row_mask:0xf bank_mask:0xf
	v_mov_b32_dpp v229, v64 row_shr:2 row_mask:0xf bank_mask:0xf
	v_mov_b32_dpp v230, v65 row_shr:1 row_mask:0xf bank_mask:0xf
	v_mov_b32_dpp v231, v65 row_shr:2 row_mask:0xf bank_mask:0xf
	v_mov_b32_dpp v232, v66 row_shr:1 row_mask:0xf bank_mask:0xf
	v_mov_b32_dpp v233, v66 row_shr:2 row_mask:0xf bank_mask:0xf
	v_mov_b32_dpp v234, v67 row_shr:1 row_mask:0xf bank_mask:0xf
	v_mov_b32_dpp v235, v67 row_shr:2 row_mask:0xf bank_mask:0xf
	v_cndmask_b32_e64 v228, 0, v228, vcc
	v_cndmask_b32_e64 v229, 0, v229, s[8:9]
	v_cndmask_b32_e64 v230, 0, v230, vcc
	v_cndmask_b32_e64 v231, 0, v231, s[8:9]
	v_cndmask_b32_e64 v232, 0, v232, vcc
	v_cndmask_b32_e64 v233, 0, v233, s[8:9]
	v_cndmask_b32_e64 v234, 0, v234, vcc
	v_cndmask_b32_e64 v235, 0, v235, s[8:9]
	v_fma_f32 v240, v229, v132, v156
	v_fma_f32 v241, v231, v133, v157
	v_fma_f32 v242, v233, v134, v158
	v_fma_f32 v243, v235, v135, v159
	v_fmac_f32_e32 v240, v228, v140
	v_fmac_f32_e32 v241, v230, v141
	v_fmac_f32_e32 v242, v232, v142
	v_fmac_f32_e32 v243, v234, v143
	v_fmac_f32_e32 v240, v64, v148
	v_fmac_f32_e32 v241, v65, v149
	v_fmac_f32_e32 v242, v66, v150
	v_fmac_f32_e32 v243, v67, v151
	v_mov_b32_e32 v228, 0xbdd2d3e8
	v_mul_f32_e32 v244, v236, v236
	v_mul_f32_e32 v245, v237, v237
	v_mul_f32_e32 v246, v238, v238
	v_mul_f32_e32 v247, v239, v239
	v_fmaak_f32 v244, v244, v228, 0xc0135761
	v_fmaak_f32 v245, v245, v228, 0xc0135761
	v_fmaak_f32 v246, v246, v228, 0xc0135761
	v_fmaak_f32 v247, v247, v228, 0xc0135761
	v_mul_f32_e32 v244, v236, v244
	v_mul_f32_e32 v245, v237, v245
	v_mul_f32_e32 v246, v238, v246
	v_mul_f32_e32 v247, v239, v247
	v_exp_f32_e32 v244, v244
	v_exp_f32_e32 v245, v245
	v_exp_f32_e32 v246, v246
	v_exp_f32_e32 v247, v247
	v_add_f32_e32 v244, 1.0, v244
	v_add_f32_e32 v245, 1.0, v245
	v_add_f32_e32 v246, 1.0, v246
	v_add_f32_e32 v247, 1.0, v247
	v_rcp_f32_e32 v244, v244
	v_rcp_f32_e32 v245, v245
	v_rcp_f32_e32 v246, v246
	v_rcp_f32_e32 v247, v247
	v_mul_f32_e32 v244, v236, v244
	v_mul_f32_e32 v245, v237, v245
	v_mul_f32_e32 v246, v238, v246
	v_mul_f32_e32 v247, v239, v247
	v_mul_f32_e32 v248, v240, v244
	v_mul_f32_e32 v249, v241, v245
	v_mul_f32_e32 v250, v242, v246
	v_mul_f32_e32 v251, v243, v247
	v_mov_b32_e32 v180, v214
	v_mov_b32_e32 v181, v215
	v_cvt_pk_bf16_f32 v182, v248, v249
	v_cvt_pk_bf16_f32 v183, v250, v251
	s_branch .Lffn1e_join1_3
.Lffn1e_old1_3:
	v_mov_b32_dpp v228, v88 row_ror:1 row_mask:0xf bank_mask:0xf
	v_mov_b32_dpp v229, v88 row_ror:2 row_mask:0xf bank_mask:0xf
	v_mov_b32_dpp v230, v89 row_ror:1 row_mask:0xf bank_mask:0xf
	v_mov_b32_dpp v231, v89 row_ror:2 row_mask:0xf bank_mask:0xf
	v_mov_b32_dpp v232, v90 row_ror:1 row_mask:0xf bank_mask:0xf
	v_mov_b32_dpp v233, v90 row_ror:2 row_mask:0xf bank_mask:0xf
	v_mov_b32_dpp v234, v91 row_ror:1 row_mask:0xf bank_mask:0xf
	v_mov_b32_dpp v235, v91 row_ror:2 row_mask:0xf bank_mask:0xf
	v_mov_b32_dpp v228, v72 row_shr:1 row_mask:0xf bank_mask:0xf
	v_mov_b32_dpp v229, v72 row_shr:2 row_mask:0xf bank_mask:0xf
	v_mov_b32_dpp v230, v73 row_shr:1 row_mask:0xf bank_mask:0xf
	v_mov_b32_dpp v231, v73 row_shr:2 row_mask:0xf bank_mask:0xf
	v_mov_b32_dpp v232, v74 row_shr:1 row_mask:0xf bank_mask:0xf
	v_mov_b32_dpp v233, v74 row_shr:2 row_mask:0xf bank_mask:0xf
	v_mov_b32_dpp v234, v75 row_shr:1 row_mask:0xf bank_mask:0xf
	v_mov_b32_dpp v235, v75 row_shr:2 row_mask:0xf bank_mask:0xf
	v_fma_f32 v236, v229, v128, v152
	v_fma_f32 v237, v231, v129, v153
	v_fma_f32 v238, v233, v130, v154
	v_fma_f32 v239, v235, v131, v155
	v_fmac_f32_e32 v236, v228, v136
	v_fmac_f32_e32 v237, v230, v137
	v_fmac_f32_e32 v238, v232, v138
	v_fmac_f32_e32 v239, v234, v139
	v_fmac_f32_e32 v236, v72, v144
	v_fmac_f32_e32 v237, v73, v145
	v_fmac_f32_e32 v238, v74, v146
	v_fmac_f32_e32 v239, v75, v147
	v_mov_b32_dpp v228, v80 row_ror:1 row_mask:0xf bank_mask:0xf
	v_mov_b32_dpp v229, v80 row_ror:2 row_mask:0xf bank_mask:0xf
	v_mov_b32_dpp v230, v81 row_ror:1 row_mask:0xf bank_mask:0xf
	v_mov_b32_dpp v231, v81 row_ror:2 row_mask:0xf bank_mask:0xf
	v_mov_b32_dpp v232, v82 row_ror:1 row_mask:0xf bank_mask:0xf
	v_mov_b32_dpp v233, v82 row_ror:2 row_mask:0xf bank_mask:0xf
	v_mov_b32_dpp v234, v83 row_ror:1 row_mask:0xf bank_mask:0xf
	v_mov_b32_dpp v235, v83 row_ror:2 row_mask:0xf bank_mask:0xf
	v_mov_b32_dpp v228, v64 row_shr:1 row_mask:0xf bank_mask:0xf
	v_mov_b32_dpp v229, v64 row_shr:2 row_mask:0xf bank_mask:0xf
	v_mov_b32_dpp v230, v65 row_shr:1 row_mask:0xf bank_mask:0xf
	v_mov_b32_dpp v231, v65 row_shr:2 row_mask:0xf bank_mask:0xf
	v_mov_b32_dpp v232, v66 row_shr:1 row_mask:0xf bank_mask:0xf
	v_mov_b32_dpp v233, v66 row_shr:2 row_mask:0xf bank_mask:0xf
	v_mov_b32_dpp v234, v67 row_shr:1 row_mask:0xf bank_mask:0xf
	v_mov_b32_dpp v235, v67 row_shr:2 row_mask:0xf bank_mask:0xf
	v_fma_f32 v240, v229, v132, v156
	v_fma_f32 v241, v231, v133, v157
	v_fma_f32 v242, v233, v134, v158
	v_fma_f32 v243, v235, v135, v159
	v_fmac_f32_e32 v240, v228, v140
	v_fmac_f32_e32 v241, v230, v141
	v_fmac_f32_e32 v242, v232, v142
	v_fmac_f32_e32 v243, v234, v143
	v_fmac_f32_e32 v240, v64, v148
	v_fmac_f32_e32 v241, v65, v149
	v_fmac_f32_e32 v242, v66, v150
	v_fmac_f32_e32 v243, v67, v151
	v_mov_b32_e32 v228, 0xbdd2d3e8
	v_mul_f32_e32 v244, v236, v236
	v_mul_f32_e32 v245, v237, v237
	v_mul_f32_e32 v246, v238, v238
	v_mul_f32_e32 v247, v239, v239
	v_fmaak_f32 v244, v244, v228, 0xc0135761
	v_fmaak_f32 v245, v245, v228, 0xc0135761
	v_fmaak_f32 v246, v246, v228, 0xc0135761
	v_fmaak_f32 v247, v247, v228, 0xc0135761
	v_mul_f32_e32 v244, v236, v244
	v_mul_f32_e32 v245, v237, v245
	v_mul_f32_e32 v246, v238, v246
	v_mul_f32_e32 v247, v239, v247
	v_exp_f32_e32 v244, v244
	v_exp_f32_e32 v245, v245
	v_exp_f32_e32 v246, v246
	v_exp_f32_e32 v247, v247
	v_add_f32_e32 v244, 1.0, v244
	v_add_f32_e32 v245, 1.0, v245
	v_add_f32_e32 v246, 1.0, v246
	v_add_f32_e32 v247, 1.0, v247
	v_rcp_f32_e32 v244, v244
	v_rcp_f32_e32 v245, v245
	v_rcp_f32_e32 v246, v246
	v_rcp_f32_e32 v247, v247
	v_mul_f32_e32 v244, v236, v244
	v_mul_f32_e32 v245, v237, v245
	v_mul_f32_e32 v246, v238, v246
	v_mul_f32_e32 v247, v239, v247
	v_mul_f32_e32 v248, v240, v244
	v_mul_f32_e32 v249, v241, v245
	v_mul_f32_e32 v250, v242, v246
	v_mul_f32_e32 v251, v243, v247
	v_mov_b32_e32 v180, v214
	v_mov_b32_e32 v181, v215
	v_cvt_pk_bf16_f32 v182, v248, v249
	v_cvt_pk_bf16_f32 v183, v250, v251
	s_branch .Lffn1e_join1_3
.Lffn1e_slow1_4:
	v_add_u32_e32 v189, 2128, v218
	v_mul_hi_u32 v203, v189, s59
	v_lshrrev_b32_e32 v203, 7, v203
	v_mul_u32_u24_e32 v203, 0x810, v203
	v_sub_u32_e32 v189, v189, v203
	v_cmp_lt_u32_e32 vcc, 0, v189
	v_cmp_lt_u32_e64 s[8:9], 1, v189
	s_nop 1
	v_mov_b32_dpp v228, v72 row_ror:1 row_mask:0xf bank_mask:0xf
	v_mov_b32_dpp v229, v72 row_ror:2 row_mask:0xf bank_mask:0xf
	v_mov_b32_dpp v230, v73 row_ror:1 row_mask:0xf bank_mask:0xf
	v_mov_b32_dpp v231, v73 row_ror:2 row_mask:0xf bank_mask:0xf
	v_mov_b32_dpp v232, v74 row_ror:1 row_mask:0xf bank_mask:0xf
	v_mov_b32_dpp v233, v74 row_ror:2 row_mask:0xf bank_mask:0xf
	v_mov_b32_dpp v234, v75 row_ror:1 row_mask:0xf bank_mask:0xf
	v_mov_b32_dpp v235, v75 row_ror:2 row_mask:0xf bank_mask:0xf
	v_mov_b32_dpp v228, v56 row_shr:1 row_mask:0xf bank_mask:0xf
	v_mov_b32_dpp v229, v56 row_shr:2 row_mask:0xf bank_mask:0xf
	v_mov_b32_dpp v230, v57 row_shr:1 row_mask:0xf bank_mask:0xf
	v_mov_b32_dpp v231, v57 row_shr:2 row_mask:0xf bank_mask:0xf
	v_mov_b32_dpp v232, v58 row_shr:1 row_mask:0xf bank_mask:0xf
	v_mov_b32_dpp v233, v58 row_shr:2 row_mask:0xf bank_mask:0xf
	v_mov_b32_dpp v234, v59 row_shr:1 row_mask:0xf bank_mask:0xf
	v_mov_b32_dpp v235, v59 row_shr:2 row_mask:0xf bank_mask:0xf
	v_cndmask_b32_e64 v228, 0, v228, vcc
	v_cndmask_b32_e64 v229, 0, v229, s[8:9]
	v_cndmask_b32_e64 v230, 0, v230, vcc
	v_cndmask_b32_e64 v231, 0, v231, s[8:9]
	v_cndmask_b32_e64 v232, 0, v232, vcc
	v_cndmask_b32_e64 v233, 0, v233, s[8:9]
	v_cndmask_b32_e64 v234, 0, v234, vcc
	v_cndmask_b32_e64 v235, 0, v235, s[8:9]
	v_fma_f32 v236, v229, v128, v152
	v_fma_f32 v237, v231, v129, v153
	v_fma_f32 v238, v233, v130, v154
	v_fma_f32 v239, v235, v131, v155
	v_fmac_f32_e32 v236, v228, v136
	v_fmac_f32_e32 v237, v230, v137
	v_fmac_f32_e32 v238, v232, v138
	v_fmac_f32_e32 v239, v234, v139
	v_fmac_f32_e32 v236, v56, v144
	v_fmac_f32_e32 v237, v57, v145
	v_fmac_f32_e32 v238, v58, v146
	v_fmac_f32_e32 v239, v59, v147
	v_mov_b32_dpp v228, v64 row_ror:1 row_mask:0xf bank_mask:0xf
	v_mov_b32_dpp v229, v64 row_ror:2 row_mask:0xf bank_mask:0xf
	v_mov_b32_dpp v230, v65 row_ror:1 row_mask:0xf bank_mask:0xf
	v_mov_b32_dpp v231, v65 row_ror:2 row_mask:0xf bank_mask:0xf
	v_mov_b32_dpp v232, v66 row_ror:1 row_mask:0xf bank_mask:0xf
	v_mov_b32_dpp v233, v66 row_ror:2 row_mask:0xf bank_mask:0xf
	v_mov_b32_dpp v234, v67 row_ror:1 row_mask:0xf bank_mask:0xf
	v_mov_b32_dpp v235, v67 row_ror:2 row_mask:0xf bank_mask:0xf
	v_mov_b32_dpp v228, v48 row_shr:1 row_mask:0xf bank_mask:0xf
	v_mov_b32_dpp v229, v48 row_shr:2 row_mask:0xf bank_mask:0xf
	v_mov_b32_dpp v230, v49 row_shr:1 row_mask:0xf bank_mask:0xf
	v_mov_b32_dpp v231, v49 row_shr:2 row_mask:0xf bank_mask:0xf
	v_mov_b32_dpp v232, v50 row_shr:1 row_mask:0xf bank_mask:0xf
	v_mov_b32_dpp v233, v50 row_shr:2 row_mask:0xf bank_mask:0xf
	v_mov_b32_dpp v234, v51 row_shr:1 row_mask:0xf bank_mask:0xf
	v_mov_b32_dpp v235, v51 row_shr:2 row_mask:0xf bank_mask:0xf
	v_cndmask_b32_e64 v228, 0, v228, vcc
	v_cndmask_b32_e64 v229, 0, v229, s[8:9]
	v_cndmask_b32_e64 v230, 0, v230, vcc
	v_cndmask_b32_e64 v231, 0, v231, s[8:9]
	v_cndmask_b32_e64 v232, 0, v232, vcc
	v_cndmask_b32_e64 v233, 0, v233, s[8:9]
	v_cndmask_b32_e64 v234, 0, v234, vcc
	v_cndmask_b32_e64 v235, 0, v235, s[8:9]
	v_fma_f32 v240, v229, v132, v156
	v_fma_f32 v241, v231, v133, v157
	v_fma_f32 v242, v233, v134, v158
	v_fma_f32 v243, v235, v135, v159
	v_fmac_f32_e32 v240, v228, v140
	v_fmac_f32_e32 v241, v230, v141
	v_fmac_f32_e32 v242, v232, v142
	v_fmac_f32_e32 v243, v234, v143
	v_fmac_f32_e32 v240, v48, v148
	v_fmac_f32_e32 v241, v49, v149
	v_fmac_f32_e32 v242, v50, v150
	v_fmac_f32_e32 v243, v51, v151
	v_mov_b32_e32 v228, 0xbdd2d3e8
	v_mul_f32_e32 v244, v236, v236
	v_mul_f32_e32 v245, v237, v237
	v_mul_f32_e32 v246, v238, v238
	v_mul_f32_e32 v247, v239, v239
	v_fmaak_f32 v244, v244, v228, 0xc0135761
	v_fmaak_f32 v245, v245, v228, 0xc0135761
	v_fmaak_f32 v246, v246, v228, 0xc0135761
	v_fmaak_f32 v247, v247, v228, 0xc0135761
	v_mul_f32_e32 v244, v236, v244
	v_mul_f32_e32 v245, v237, v245
	v_mul_f32_e32 v246, v238, v246
	v_mul_f32_e32 v247, v239, v247
	v_exp_f32_e32 v244, v244
	v_exp_f32_e32 v245, v245
	v_exp_f32_e32 v246, v246
	v_exp_f32_e32 v247, v247
	v_add_f32_e32 v244, 1.0, v244
	v_add_f32_e32 v245, 1.0, v245
	v_add_f32_e32 v246, 1.0, v246
	v_add_f32_e32 v247, 1.0, v247
	v_rcp_f32_e32 v244, v244
	v_rcp_f32_e32 v245, v245
	v_rcp_f32_e32 v246, v246
	v_rcp_f32_e32 v247, v247
	v_mul_f32_e32 v244, v236, v244
	v_mul_f32_e32 v245, v237, v245
	v_mul_f32_e32 v246, v238, v246
	v_mul_f32_e32 v247, v239, v247
	v_mul_f32_e32 v248, v240, v244
	v_mul_f32_e32 v249, v241, v245
	v_mul_f32_e32 v250, v242, v246
	v_mul_f32_e32 v251, v243, v247
	v_mov_b32_e32 v180, v216
	v_mov_b32_e32 v181, v217
	v_cvt_pk_bf16_f32 v182, v248, v249
	v_cvt_pk_bf16_f32 v183, v250, v251
	s_branch .Lffn1e_join1_4
.Lffn1e_old1_4:
	v_mov_b32_dpp v228, v72 row_ror:1 row_mask:0xf bank_mask:0xf
	v_mov_b32_dpp v229, v72 row_ror:2 row_mask:0xf bank_mask:0xf
	v_mov_b32_dpp v230, v73 row_ror:1 row_mask:0xf bank_mask:0xf
	v_mov_b32_dpp v231, v73 row_ror:2 row_mask:0xf bank_mask:0xf
	v_mov_b32_dpp v232, v74 row_ror:1 row_mask:0xf bank_mask:0xf
	v_mov_b32_dpp v233, v74 row_ror:2 row_mask:0xf bank_mask:0xf
	v_mov_b32_dpp v234, v75 row_ror:1 row_mask:0xf bank_mask:0xf
	v_mov_b32_dpp v235, v75 row_ror:2 row_mask:0xf bank_mask:0xf
	v_mov_b32_dpp v228, v56 row_shr:1 row_mask:0xf bank_mask:0xf
	v_mov_b32_dpp v229, v56 row_shr:2 row_mask:0xf bank_mask:0xf
	v_mov_b32_dpp v230, v57 row_shr:1 row_mask:0xf bank_mask:0xf
	v_mov_b32_dpp v231, v57 row_shr:2 row_mask:0xf bank_mask:0xf
	v_mov_b32_dpp v232, v58 row_shr:1 row_mask:0xf bank_mask:0xf
	v_mov_b32_dpp v233, v58 row_shr:2 row_mask:0xf bank_mask:0xf
	v_mov_b32_dpp v234, v59 row_shr:1 row_mask:0xf bank_mask:0xf
	v_mov_b32_dpp v235, v59 row_shr:2 row_mask:0xf bank_mask:0xf
	v_fma_f32 v236, v229, v128, v152
	v_fma_f32 v237, v231, v129, v153
	v_fma_f32 v238, v233, v130, v154
	v_fma_f32 v239, v235, v131, v155
	v_fmac_f32_e32 v236, v228, v136
	v_fmac_f32_e32 v237, v230, v137
	v_fmac_f32_e32 v238, v232, v138
	v_fmac_f32_e32 v239, v234, v139
	v_fmac_f32_e32 v236, v56, v144
	v_fmac_f32_e32 v237, v57, v145
	v_fmac_f32_e32 v238, v58, v146
	v_fmac_f32_e32 v239, v59, v147
	v_mov_b32_dpp v228, v64 row_ror:1 row_mask:0xf bank_mask:0xf
	v_mov_b32_dpp v229, v64 row_ror:2 row_mask:0xf bank_mask:0xf
	v_mov_b32_dpp v230, v65 row_ror:1 row_mask:0xf bank_mask:0xf
	v_mov_b32_dpp v231, v65 row_ror:2 row_mask:0xf bank_mask:0xf
	v_mov_b32_dpp v232, v66 row_ror:1 row_mask:0xf bank_mask:0xf
	v_mov_b32_dpp v233, v66 row_ror:2 row_mask:0xf bank_mask:0xf
	v_mov_b32_dpp v234, v67 row_ror:1 row_mask:0xf bank_mask:0xf
	v_mov_b32_dpp v235, v67 row_ror:2 row_mask:0xf bank_mask:0xf
	v_mov_b32_dpp v228, v48 row_shr:1 row_mask:0xf bank_mask:0xf
	v_mov_b32_dpp v229, v48 row_shr:2 row_mask:0xf bank_mask:0xf
	v_mov_b32_dpp v230, v49 row_shr:1 row_mask:0xf bank_mask:0xf
	v_mov_b32_dpp v231, v49 row_shr:2 row_mask:0xf bank_mask:0xf
	v_mov_b32_dpp v232, v50 row_shr:1 row_mask:0xf bank_mask:0xf
	v_mov_b32_dpp v233, v50 row_shr:2 row_mask:0xf bank_mask:0xf
	v_mov_b32_dpp v234, v51 row_shr:1 row_mask:0xf bank_mask:0xf
	v_mov_b32_dpp v235, v51 row_shr:2 row_mask:0xf bank_mask:0xf
	v_fma_f32 v240, v229, v132, v156
	v_fma_f32 v241, v231, v133, v157
	v_fma_f32 v242, v233, v134, v158
	v_fma_f32 v243, v235, v135, v159
	v_fmac_f32_e32 v240, v228, v140
	v_fmac_f32_e32 v241, v230, v141
	v_fmac_f32_e32 v242, v232, v142
	v_fmac_f32_e32 v243, v234, v143
	v_fmac_f32_e32 v240, v48, v148
	v_fmac_f32_e32 v241, v49, v149
	v_fmac_f32_e32 v242, v50, v150
	v_fmac_f32_e32 v243, v51, v151
	v_mov_b32_e32 v228, 0xbdd2d3e8
	v_mul_f32_e32 v244, v236, v236
	v_mul_f32_e32 v245, v237, v237
	v_mul_f32_e32 v246, v238, v238
	v_mul_f32_e32 v247, v239, v239
	v_fmaak_f32 v244, v244, v228, 0xc0135761
	v_fmaak_f32 v245, v245, v228, 0xc0135761
	v_fmaak_f32 v246, v246, v228, 0xc0135761
	v_fmaak_f32 v247, v247, v228, 0xc0135761
	v_mul_f32_e32 v244, v236, v244
	v_mul_f32_e32 v245, v237, v245
	v_mul_f32_e32 v246, v238, v246
	v_mul_f32_e32 v247, v239, v247
	v_exp_f32_e32 v244, v244
	v_exp_f32_e32 v245, v245
	v_exp_f32_e32 v246, v246
	v_exp_f32_e32 v247, v247
	v_add_f32_e32 v244, 1.0, v244
	v_add_f32_e32 v245, 1.0, v245
	v_add_f32_e32 v246, 1.0, v246
	v_add_f32_e32 v247, 1.0, v247
	v_rcp_f32_e32 v244, v244
	v_rcp_f32_e32 v245, v245
	v_rcp_f32_e32 v246, v246
	v_rcp_f32_e32 v247, v247
	v_mul_f32_e32 v244, v236, v244
	v_mul_f32_e32 v245, v237, v245
	v_mul_f32_e32 v246, v238, v246
	v_mul_f32_e32 v247, v239, v247
	v_mul_f32_e32 v248, v240, v244
	v_mul_f32_e32 v249, v241, v245
	v_mul_f32_e32 v250, v242, v246
	v_mul_f32_e32 v251, v243, v247
	v_mov_b32_e32 v180, v216
	v_mov_b32_e32 v181, v217
	v_cvt_pk_bf16_f32 v182, v248, v249
	v_cvt_pk_bf16_f32 v183, v250, v251
	s_branch .Lffn1e_join1_4
.Lffn1e_slow1_5:
	v_add_u32_e32 v189, 2144, v218
	v_mul_hi_u32 v203, v189, s59
	v_lshrrev_b32_e32 v203, 7, v203
	v_mul_u32_u24_e32 v203, 0x810, v203
	v_sub_u32_e32 v189, v189, v203
	v_cmp_lt_u32_e32 vcc, 0, v189
	v_cmp_lt_u32_e64 s[8:9], 1, v189
	s_nop 1
	v_mov_b32_dpp v228, v56 row_ror:1 row_mask:0xf bank_mask:0xf
	v_mov_b32_dpp v229, v56 row_ror:2 row_mask:0xf bank_mask:0xf
	v_mov_b32_dpp v230, v57 row_ror:1 row_mask:0xf bank_mask:0xf
	v_mov_b32_dpp v231, v57 row_ror:2 row_mask:0xf bank_mask:0xf
	v_mov_b32_dpp v232, v58 row_ror:1 row_mask:0xf bank_mask:0xf
	v_mov_b32_dpp v233, v58 row_ror:2 row_mask:0xf bank_mask:0xf
	v_mov_b32_dpp v234, v59 row_ror:1 row_mask:0xf bank_mask:0xf
	v_mov_b32_dpp v235, v59 row_ror:2 row_mask:0xf bank_mask:0xf
	v_mov_b32_dpp v228, v40 row_shr:1 row_mask:0xf bank_mask:0xf
	v_mov_b32_dpp v229, v40 row_shr:2 row_mask:0xf bank_mask:0xf
	v_mov_b32_dpp v230, v41 row_shr:1 row_mask:0xf bank_mask:0xf
	v_mov_b32_dpp v231, v41 row_shr:2 row_mask:0xf bank_mask:0xf
	v_mov_b32_dpp v232, v42 row_shr:1 row_mask:0xf bank_mask:0xf
	v_mov_b32_dpp v233, v42 row_shr:2 row_mask:0xf bank_mask:0xf
	v_mov_b32_dpp v234, v43 row_shr:1 row_mask:0xf bank_mask:0xf
	v_mov_b32_dpp v235, v43 row_shr:2 row_mask:0xf bank_mask:0xf
	v_cndmask_b32_e64 v228, 0, v228, vcc
	v_cndmask_b32_e64 v229, 0, v229, s[8:9]
	v_cndmask_b32_e64 v230, 0, v230, vcc
	v_cndmask_b32_e64 v231, 0, v231, s[8:9]
	v_cndmask_b32_e64 v232, 0, v232, vcc
	v_cndmask_b32_e64 v233, 0, v233, s[8:9]
	v_cndmask_b32_e64 v234, 0, v234, vcc
	v_cndmask_b32_e64 v235, 0, v235, s[8:9]
	v_fma_f32 v236, v229, v128, v152
	v_fma_f32 v237, v231, v129, v153
	v_fma_f32 v238, v233, v130, v154
	v_fma_f32 v239, v235, v131, v155
	v_fmac_f32_e32 v236, v228, v136
	v_fmac_f32_e32 v237, v230, v137
	v_fmac_f32_e32 v238, v232, v138
	v_fmac_f32_e32 v239, v234, v139
	v_fmac_f32_e32 v236, v40, v144
	v_fmac_f32_e32 v237, v41, v145
	v_fmac_f32_e32 v238, v42, v146
	v_fmac_f32_e32 v239, v43, v147
	v_mov_b32_dpp v228, v48 row_ror:1 row_mask:0xf bank_mask:0xf
	v_mov_b32_dpp v229, v48 row_ror:2 row_mask:0xf bank_mask:0xf
	v_mov_b32_dpp v230, v49 row_ror:1 row_mask:0xf bank_mask:0xf
	v_mov_b32_dpp v231, v49 row_ror:2 row_mask:0xf bank_mask:0xf
	v_mov_b32_dpp v232, v50 row_ror:1 row_mask:0xf bank_mask:0xf
	v_mov_b32_dpp v233, v50 row_ror:2 row_mask:0xf bank_mask:0xf
	v_mov_b32_dpp v234, v51 row_ror:1 row_mask:0xf bank_mask:0xf
	v_mov_b32_dpp v235, v51 row_ror:2 row_mask:0xf bank_mask:0xf
	v_mov_b32_dpp v228, v32 row_shr:1 row_mask:0xf bank_mask:0xf
	v_mov_b32_dpp v229, v32 row_shr:2 row_mask:0xf bank_mask:0xf
	v_mov_b32_dpp v230, v33 row_shr:1 row_mask:0xf bank_mask:0xf
	v_mov_b32_dpp v231, v33 row_shr:2 row_mask:0xf bank_mask:0xf
	v_mov_b32_dpp v232, v34 row_shr:1 row_mask:0xf bank_mask:0xf
	v_mov_b32_dpp v233, v34 row_shr:2 row_mask:0xf bank_mask:0xf
	v_mov_b32_dpp v234, v35 row_shr:1 row_mask:0xf bank_mask:0xf
	v_mov_b32_dpp v235, v35 row_shr:2 row_mask:0xf bank_mask:0xf
	v_cndmask_b32_e64 v228, 0, v228, vcc
	v_cndmask_b32_e64 v229, 0, v229, s[8:9]
	v_cndmask_b32_e64 v230, 0, v230, vcc
	v_cndmask_b32_e64 v231, 0, v231, s[8:9]
	v_cndmask_b32_e64 v232, 0, v232, vcc
	v_cndmask_b32_e64 v233, 0, v233, s[8:9]
	v_cndmask_b32_e64 v234, 0, v234, vcc
	v_cndmask_b32_e64 v235, 0, v235, s[8:9]
	v_fma_f32 v240, v229, v132, v156
	v_fma_f32 v241, v231, v133, v157
	v_fma_f32 v242, v233, v134, v158
	v_fma_f32 v243, v235, v135, v159
	v_fmac_f32_e32 v240, v228, v140
	v_fmac_f32_e32 v241, v230, v141
	v_fmac_f32_e32 v242, v232, v142
	v_fmac_f32_e32 v243, v234, v143
	v_fmac_f32_e32 v240, v32, v148
	v_fmac_f32_e32 v241, v33, v149
	v_fmac_f32_e32 v242, v34, v150
	v_fmac_f32_e32 v243, v35, v151
	v_mov_b32_e32 v228, 0xbdd2d3e8
	v_mul_f32_e32 v244, v236, v236
	v_mul_f32_e32 v245, v237, v237
	v_mul_f32_e32 v246, v238, v238
	v_mul_f32_e32 v247, v239, v239
	v_fmaak_f32 v244, v244, v228, 0xc0135761
	v_fmaak_f32 v245, v245, v228, 0xc0135761
	v_fmaak_f32 v246, v246, v228, 0xc0135761
	v_fmaak_f32 v247, v247, v228, 0xc0135761
	v_mul_f32_e32 v244, v236, v244
	v_mul_f32_e32 v245, v237, v245
	v_mul_f32_e32 v246, v238, v246
	v_mul_f32_e32 v247, v239, v247
	v_exp_f32_e32 v244, v244
	v_exp_f32_e32 v245, v245
	v_exp_f32_e32 v246, v246
	v_exp_f32_e32 v247, v247
	v_add_f32_e32 v244, 1.0, v244
	v_add_f32_e32 v245, 1.0, v245
	v_add_f32_e32 v246, 1.0, v246
	v_add_f32_e32 v247, 1.0, v247
	v_rcp_f32_e32 v244, v244
	v_rcp_f32_e32 v245, v245
	v_rcp_f32_e32 v246, v246
	v_rcp_f32_e32 v247, v247
	v_mul_f32_e32 v244, v236, v244
	v_mul_f32_e32 v245, v237, v245
	v_mul_f32_e32 v246, v238, v246
	v_mul_f32_e32 v247, v239, v247
	v_mul_f32_e32 v248, v240, v244
	v_mul_f32_e32 v249, v241, v245
	v_mul_f32_e32 v250, v242, v246
	v_mul_f32_e32 v251, v243, v247
	v_mov_b32_e32 v180, v220
	v_mov_b32_e32 v181, v221
	v_cvt_pk_bf16_f32 v182, v248, v249
	v_cvt_pk_bf16_f32 v183, v250, v251
	s_branch .Lffn1e_join1_5
.Lffn1e_old1_5:
	v_mov_b32_dpp v228, v56 row_ror:1 row_mask:0xf bank_mask:0xf
	v_mov_b32_dpp v229, v56 row_ror:2 row_mask:0xf bank_mask:0xf
	v_mov_b32_dpp v230, v57 row_ror:1 row_mask:0xf bank_mask:0xf
	v_mov_b32_dpp v231, v57 row_ror:2 row_mask:0xf bank_mask:0xf
	v_mov_b32_dpp v232, v58 row_ror:1 row_mask:0xf bank_mask:0xf
	v_mov_b32_dpp v233, v58 row_ror:2 row_mask:0xf bank_mask:0xf
	v_mov_b32_dpp v234, v59 row_ror:1 row_mask:0xf bank_mask:0xf
	v_mov_b32_dpp v235, v59 row_ror:2 row_mask:0xf bank_mask:0xf
	v_mov_b32_dpp v228, v40 row_shr:1 row_mask:0xf bank_mask:0xf
	v_mov_b32_dpp v229, v40 row_shr:2 row_mask:0xf bank_mask:0xf
	v_mov_b32_dpp v230, v41 row_shr:1 row_mask:0xf bank_mask:0xf
	v_mov_b32_dpp v231, v41 row_shr:2 row_mask:0xf bank_mask:0xf
	v_mov_b32_dpp v232, v42 row_shr:1 row_mask:0xf bank_mask:0xf
	v_mov_b32_dpp v233, v42 row_shr:2 row_mask:0xf bank_mask:0xf
	v_mov_b32_dpp v234, v43 row_shr:1 row_mask:0xf bank_mask:0xf
	v_mov_b32_dpp v235, v43 row_shr:2 row_mask:0xf bank_mask:0xf
	v_fma_f32 v236, v229, v128, v152
	v_fma_f32 v237, v231, v129, v153
	v_fma_f32 v238, v233, v130, v154
	v_fma_f32 v239, v235, v131, v155
	v_fmac_f32_e32 v236, v228, v136
	v_fmac_f32_e32 v237, v230, v137
	v_fmac_f32_e32 v238, v232, v138
	v_fmac_f32_e32 v239, v234, v139
	v_fmac_f32_e32 v236, v40, v144
	v_fmac_f32_e32 v237, v41, v145
	v_fmac_f32_e32 v238, v42, v146
	v_fmac_f32_e32 v239, v43, v147
	v_mov_b32_dpp v228, v48 row_ror:1 row_mask:0xf bank_mask:0xf
	v_mov_b32_dpp v229, v48 row_ror:2 row_mask:0xf bank_mask:0xf
	v_mov_b32_dpp v230, v49 row_ror:1 row_mask:0xf bank_mask:0xf
	v_mov_b32_dpp v231, v49 row_ror:2 row_mask:0xf bank_mask:0xf
	v_mov_b32_dpp v232, v50 row_ror:1 row_mask:0xf bank_mask:0xf
	v_mov_b32_dpp v233, v50 row_ror:2 row_mask:0xf bank_mask:0xf
	v_mov_b32_dpp v234, v51 row_ror:1 row_mask:0xf bank_mask:0xf
	v_mov_b32_dpp v235, v51 row_ror:2 row_mask:0xf bank_mask:0xf
	v_mov_b32_dpp v228, v32 row_shr:1 row_mask:0xf bank_mask:0xf
	v_mov_b32_dpp v229, v32 row_shr:2 row_mask:0xf bank_mask:0xf
	v_mov_b32_dpp v230, v33 row_shr:1 row_mask:0xf bank_mask:0xf
	v_mov_b32_dpp v231, v33 row_shr:2 row_mask:0xf bank_mask:0xf
	v_mov_b32_dpp v232, v34 row_shr:1 row_mask:0xf bank_mask:0xf
	v_mov_b32_dpp v233, v34 row_shr:2 row_mask:0xf bank_mask:0xf
	v_mov_b32_dpp v234, v35 row_shr:1 row_mask:0xf bank_mask:0xf
	v_mov_b32_dpp v235, v35 row_shr:2 row_mask:0xf bank_mask:0xf
	v_fma_f32 v240, v229, v132, v156
	v_fma_f32 v241, v231, v133, v157
	v_fma_f32 v242, v233, v134, v158
	v_fma_f32 v243, v235, v135, v159
	v_fmac_f32_e32 v240, v228, v140
	v_fmac_f32_e32 v241, v230, v141
	v_fmac_f32_e32 v242, v232, v142
	v_fmac_f32_e32 v243, v234, v143
	v_fmac_f32_e32 v240, v32, v148
	v_fmac_f32_e32 v241, v33, v149
	v_fmac_f32_e32 v242, v34, v150
	v_fmac_f32_e32 v243, v35, v151
	v_mov_b32_e32 v228, 0xbdd2d3e8
	v_mul_f32_e32 v244, v236, v236
	v_mul_f32_e32 v245, v237, v237
	v_mul_f32_e32 v246, v238, v238
	v_mul_f32_e32 v247, v239, v239
	v_fmaak_f32 v244, v244, v228, 0xc0135761
	v_fmaak_f32 v245, v245, v228, 0xc0135761
	v_fmaak_f32 v246, v246, v228, 0xc0135761
	v_fmaak_f32 v247, v247, v228, 0xc0135761
	v_mul_f32_e32 v244, v236, v244
	v_mul_f32_e32 v245, v237, v245
	v_mul_f32_e32 v246, v238, v246
	v_mul_f32_e32 v247, v239, v247
	v_exp_f32_e32 v244, v244
	v_exp_f32_e32 v245, v245
	v_exp_f32_e32 v246, v246
	v_exp_f32_e32 v247, v247
	v_add_f32_e32 v244, 1.0, v244
	v_add_f32_e32 v245, 1.0, v245
	v_add_f32_e32 v246, 1.0, v246
	v_add_f32_e32 v247, 1.0, v247
	v_rcp_f32_e32 v244, v244
	v_rcp_f32_e32 v245, v245
	v_rcp_f32_e32 v246, v246
	v_rcp_f32_e32 v247, v247
	v_mul_f32_e32 v244, v236, v244
	v_mul_f32_e32 v245, v237, v245
	v_mul_f32_e32 v246, v238, v246
	v_mul_f32_e32 v247, v239, v247
	v_mul_f32_e32 v248, v240, v244
	v_mul_f32_e32 v249, v241, v245
	v_mul_f32_e32 v250, v242, v246
	v_mul_f32_e32 v251, v243, v247
	v_mov_b32_e32 v180, v220
	v_mov_b32_e32 v181, v221
	v_cvt_pk_bf16_f32 v182, v248, v249
	v_cvt_pk_bf16_f32 v183, v250, v251
	s_branch .Lffn1e_join1_5
.Lffn1e_slow1_6:
	v_add_u32_e32 v189, 2160, v218
	v_mul_hi_u32 v203, v189, s59
	v_lshrrev_b32_e32 v203, 7, v203
	v_mul_u32_u24_e32 v203, 0x810, v203
	v_sub_u32_e32 v189, v189, v203
	v_cmp_lt_u32_e32 vcc, 0, v189
	v_cmp_lt_u32_e64 s[8:9], 1, v189
	s_nop 1
	v_mov_b32_dpp v228, v40 row_ror:1 row_mask:0xf bank_mask:0xf
	v_mov_b32_dpp v229, v40 row_ror:2 row_mask:0xf bank_mask:0xf
	v_mov_b32_dpp v230, v41 row_ror:1 row_mask:0xf bank_mask:0xf
	v_mov_b32_dpp v231, v41 row_ror:2 row_mask:0xf bank_mask:0xf
	v_mov_b32_dpp v232, v42 row_ror:1 row_mask:0xf bank_mask:0xf
	v_mov_b32_dpp v233, v42 row_ror:2 row_mask:0xf bank_mask:0xf
	v_mov_b32_dpp v234, v43 row_ror:1 row_mask:0xf bank_mask:0xf
	v_mov_b32_dpp v235, v43 row_ror:2 row_mask:0xf bank_mask:0xf
	v_mov_b32_dpp v228, v24 row_shr:1 row_mask:0xf bank_mask:0xf
	v_mov_b32_dpp v229, v24 row_shr:2 row_mask:0xf bank_mask:0xf
	v_mov_b32_dpp v230, v25 row_shr:1 row_mask:0xf bank_mask:0xf
	v_mov_b32_dpp v231, v25 row_shr:2 row_mask:0xf bank_mask:0xf
	v_mov_b32_dpp v232, v26 row_shr:1 row_mask:0xf bank_mask:0xf
	v_mov_b32_dpp v233, v26 row_shr:2 row_mask:0xf bank_mask:0xf
	v_mov_b32_dpp v234, v27 row_shr:1 row_mask:0xf bank_mask:0xf
	v_mov_b32_dpp v235, v27 row_shr:2 row_mask:0xf bank_mask:0xf
	v_cndmask_b32_e64 v228, 0, v228, vcc
	v_cndmask_b32_e64 v229, 0, v229, s[8:9]
	v_cndmask_b32_e64 v230, 0, v230, vcc
	v_cndmask_b32_e64 v231, 0, v231, s[8:9]
	v_cndmask_b32_e64 v232, 0, v232, vcc
	v_cndmask_b32_e64 v233, 0, v233, s[8:9]
	v_cndmask_b32_e64 v234, 0, v234, vcc
	v_cndmask_b32_e64 v235, 0, v235, s[8:9]
	v_fma_f32 v236, v229, v128, v152
	v_fma_f32 v237, v231, v129, v153
	v_fma_f32 v238, v233, v130, v154
	v_fma_f32 v239, v235, v131, v155
	v_fmac_f32_e32 v236, v228, v136
	v_fmac_f32_e32 v237, v230, v137
	v_fmac_f32_e32 v238, v232, v138
	v_fmac_f32_e32 v239, v234, v139
	v_fmac_f32_e32 v236, v24, v144
	v_fmac_f32_e32 v237, v25, v145
	v_fmac_f32_e32 v238, v26, v146
	v_fmac_f32_e32 v239, v27, v147
	v_mov_b32_dpp v228, v32 row_ror:1 row_mask:0xf bank_mask:0xf
	v_mov_b32_dpp v229, v32 row_ror:2 row_mask:0xf bank_mask:0xf
	v_mov_b32_dpp v230, v33 row_ror:1 row_mask:0xf bank_mask:0xf
	v_mov_b32_dpp v231, v33 row_ror:2 row_mask:0xf bank_mask:0xf
	v_mov_b32_dpp v232, v34 row_ror:1 row_mask:0xf bank_mask:0xf
	v_mov_b32_dpp v233, v34 row_ror:2 row_mask:0xf bank_mask:0xf
	v_mov_b32_dpp v234, v35 row_ror:1 row_mask:0xf bank_mask:0xf
	v_mov_b32_dpp v235, v35 row_ror:2 row_mask:0xf bank_mask:0xf
	v_mov_b32_dpp v228, v16 row_shr:1 row_mask:0xf bank_mask:0xf
	v_mov_b32_dpp v229, v16 row_shr:2 row_mask:0xf bank_mask:0xf
	v_mov_b32_dpp v230, v17 row_shr:1 row_mask:0xf bank_mask:0xf
	v_mov_b32_dpp v231, v17 row_shr:2 row_mask:0xf bank_mask:0xf
	v_mov_b32_dpp v232, v18 row_shr:1 row_mask:0xf bank_mask:0xf
	v_mov_b32_dpp v233, v18 row_shr:2 row_mask:0xf bank_mask:0xf
	v_mov_b32_dpp v234, v19 row_shr:1 row_mask:0xf bank_mask:0xf
	v_mov_b32_dpp v235, v19 row_shr:2 row_mask:0xf bank_mask:0xf
	v_cndmask_b32_e64 v228, 0, v228, vcc
	v_cndmask_b32_e64 v229, 0, v229, s[8:9]
	v_cndmask_b32_e64 v230, 0, v230, vcc
	v_cndmask_b32_e64 v231, 0, v231, s[8:9]
	v_cndmask_b32_e64 v232, 0, v232, vcc
	v_cndmask_b32_e64 v233, 0, v233, s[8:9]
	v_cndmask_b32_e64 v234, 0, v234, vcc
	v_cndmask_b32_e64 v235, 0, v235, s[8:9]
	v_fma_f32 v240, v229, v132, v156
	v_fma_f32 v241, v231, v133, v157
	v_fma_f32 v242, v233, v134, v158
	v_fma_f32 v243, v235, v135, v159
	v_fmac_f32_e32 v240, v228, v140
	v_fmac_f32_e32 v241, v230, v141
	v_fmac_f32_e32 v242, v232, v142
	v_fmac_f32_e32 v243, v234, v143
	v_fmac_f32_e32 v240, v16, v148
	v_fmac_f32_e32 v241, v17, v149
	v_fmac_f32_e32 v242, v18, v150
	v_fmac_f32_e32 v243, v19, v151
	v_mov_b32_e32 v228, 0xbdd2d3e8
	v_mul_f32_e32 v244, v236, v236
	v_mul_f32_e32 v245, v237, v237
	v_mul_f32_e32 v246, v238, v238
	v_mul_f32_e32 v247, v239, v239
	v_fmaak_f32 v244, v244, v228, 0xc0135761
	v_fmaak_f32 v245, v245, v228, 0xc0135761
	v_fmaak_f32 v246, v246, v228, 0xc0135761
	v_fmaak_f32 v247, v247, v228, 0xc0135761
	v_mul_f32_e32 v244, v236, v244
	v_mul_f32_e32 v245, v237, v245
	v_mul_f32_e32 v246, v238, v246
	v_mul_f32_e32 v247, v239, v247
	v_exp_f32_e32 v244, v244
	v_exp_f32_e32 v245, v245
	v_exp_f32_e32 v246, v246
	v_exp_f32_e32 v247, v247
	v_add_f32_e32 v244, 1.0, v244
	v_add_f32_e32 v245, 1.0, v245
	v_add_f32_e32 v246, 1.0, v246
	v_add_f32_e32 v247, 1.0, v247
	v_rcp_f32_e32 v244, v244
	v_rcp_f32_e32 v245, v245
	v_rcp_f32_e32 v246, v246
	v_rcp_f32_e32 v247, v247
	v_mul_f32_e32 v244, v236, v244
	v_mul_f32_e32 v245, v237, v245
	v_mul_f32_e32 v246, v238, v246
	v_mul_f32_e32 v247, v239, v247
	v_mul_f32_e32 v248, v240, v244
	v_mul_f32_e32 v249, v241, v245
	v_mul_f32_e32 v250, v242, v246
	v_mul_f32_e32 v251, v243, v247
	v_mov_b32_e32 v180, v222
	v_mov_b32_e32 v181, v223
	v_cvt_pk_bf16_f32 v182, v248, v249
	v_cvt_pk_bf16_f32 v183, v250, v251
	s_branch .Lffn1e_join1_6
.Lffn1e_old1_6:
	v_mov_b32_dpp v228, v40 row_ror:1 row_mask:0xf bank_mask:0xf
	v_mov_b32_dpp v229, v40 row_ror:2 row_mask:0xf bank_mask:0xf
	v_mov_b32_dpp v230, v41 row_ror:1 row_mask:0xf bank_mask:0xf
	v_mov_b32_dpp v231, v41 row_ror:2 row_mask:0xf bank_mask:0xf
	v_mov_b32_dpp v232, v42 row_ror:1 row_mask:0xf bank_mask:0xf
	v_mov_b32_dpp v233, v42 row_ror:2 row_mask:0xf bank_mask:0xf
	v_mov_b32_dpp v234, v43 row_ror:1 row_mask:0xf bank_mask:0xf
	v_mov_b32_dpp v235, v43 row_ror:2 row_mask:0xf bank_mask:0xf
	v_mov_b32_dpp v228, v24 row_shr:1 row_mask:0xf bank_mask:0xf
	v_mov_b32_dpp v229, v24 row_shr:2 row_mask:0xf bank_mask:0xf
	v_mov_b32_dpp v230, v25 row_shr:1 row_mask:0xf bank_mask:0xf
	v_mov_b32_dpp v231, v25 row_shr:2 row_mask:0xf bank_mask:0xf
	v_mov_b32_dpp v232, v26 row_shr:1 row_mask:0xf bank_mask:0xf
	v_mov_b32_dpp v233, v26 row_shr:2 row_mask:0xf bank_mask:0xf
	v_mov_b32_dpp v234, v27 row_shr:1 row_mask:0xf bank_mask:0xf
	v_mov_b32_dpp v235, v27 row_shr:2 row_mask:0xf bank_mask:0xf
	v_fma_f32 v236, v229, v128, v152
	v_fma_f32 v237, v231, v129, v153
	v_fma_f32 v238, v233, v130, v154
	v_fma_f32 v239, v235, v131, v155
	v_fmac_f32_e32 v236, v228, v136
	v_fmac_f32_e32 v237, v230, v137
	v_fmac_f32_e32 v238, v232, v138
	v_fmac_f32_e32 v239, v234, v139
	v_fmac_f32_e32 v236, v24, v144
	v_fmac_f32_e32 v237, v25, v145
	v_fmac_f32_e32 v238, v26, v146
	v_fmac_f32_e32 v239, v27, v147
	v_mov_b32_dpp v228, v32 row_ror:1 row_mask:0xf bank_mask:0xf
	v_mov_b32_dpp v229, v32 row_ror:2 row_mask:0xf bank_mask:0xf
	v_mov_b32_dpp v230, v33 row_ror:1 row_mask:0xf bank_mask:0xf
	v_mov_b32_dpp v231, v33 row_ror:2 row_mask:0xf bank_mask:0xf
	v_mov_b32_dpp v232, v34 row_ror:1 row_mask:0xf bank_mask:0xf
	v_mov_b32_dpp v233, v34 row_ror:2 row_mask:0xf bank_mask:0xf
	v_mov_b32_dpp v234, v35 row_ror:1 row_mask:0xf bank_mask:0xf
	v_mov_b32_dpp v235, v35 row_ror:2 row_mask:0xf bank_mask:0xf
	v_mov_b32_dpp v228, v16 row_shr:1 row_mask:0xf bank_mask:0xf
	v_mov_b32_dpp v229, v16 row_shr:2 row_mask:0xf bank_mask:0xf
	v_mov_b32_dpp v230, v17 row_shr:1 row_mask:0xf bank_mask:0xf
	v_mov_b32_dpp v231, v17 row_shr:2 row_mask:0xf bank_mask:0xf
	v_mov_b32_dpp v232, v18 row_shr:1 row_mask:0xf bank_mask:0xf
	v_mov_b32_dpp v233, v18 row_shr:2 row_mask:0xf bank_mask:0xf
	v_mov_b32_dpp v234, v19 row_shr:1 row_mask:0xf bank_mask:0xf
	v_mov_b32_dpp v235, v19 row_shr:2 row_mask:0xf bank_mask:0xf
	v_fma_f32 v240, v229, v132, v156
	v_fma_f32 v241, v231, v133, v157
	v_fma_f32 v242, v233, v134, v158
	v_fma_f32 v243, v235, v135, v159
	v_fmac_f32_e32 v240, v228, v140
	v_fmac_f32_e32 v241, v230, v141
	v_fmac_f32_e32 v242, v232, v142
	v_fmac_f32_e32 v243, v234, v143
	v_fmac_f32_e32 v240, v16, v148
	v_fmac_f32_e32 v241, v17, v149
	v_fmac_f32_e32 v242, v18, v150
	v_fmac_f32_e32 v243, v19, v151
	v_mov_b32_e32 v228, 0xbdd2d3e8
	v_mul_f32_e32 v244, v236, v236
	v_mul_f32_e32 v245, v237, v237
	v_mul_f32_e32 v246, v238, v238
	v_mul_f32_e32 v247, v239, v239
	v_fmaak_f32 v244, v244, v228, 0xc0135761
	v_fmaak_f32 v245, v245, v228, 0xc0135761
	v_fmaak_f32 v246, v246, v228, 0xc0135761
	v_fmaak_f32 v247, v247, v228, 0xc0135761
	v_mul_f32_e32 v244, v236, v244
	v_mul_f32_e32 v245, v237, v245
	v_mul_f32_e32 v246, v238, v246
	v_mul_f32_e32 v247, v239, v247
	v_exp_f32_e32 v244, v244
	v_exp_f32_e32 v245, v245
	v_exp_f32_e32 v246, v246
	v_exp_f32_e32 v247, v247
	v_add_f32_e32 v244, 1.0, v244
	v_add_f32_e32 v245, 1.0, v245
	v_add_f32_e32 v246, 1.0, v246
	v_add_f32_e32 v247, 1.0, v247
	v_rcp_f32_e32 v244, v244
	v_rcp_f32_e32 v245, v245
	v_rcp_f32_e32 v246, v246
	v_rcp_f32_e32 v247, v247
	v_mul_f32_e32 v244, v236, v244
	v_mul_f32_e32 v245, v237, v245
	v_mul_f32_e32 v246, v238, v246
	v_mul_f32_e32 v247, v239, v247
	v_mul_f32_e32 v248, v240, v244
	v_mul_f32_e32 v249, v241, v245
	v_mul_f32_e32 v250, v242, v246
	v_mul_f32_e32 v251, v243, v247
	v_mov_b32_e32 v180, v222
	v_mov_b32_e32 v181, v223
	v_cvt_pk_bf16_f32 v182, v248, v249
	v_cvt_pk_bf16_f32 v183, v250, v251
	s_branch .Lffn1e_join1_6
.Lffn1e_slow1_7:
	v_add_u32_e32 v189, 2176, v218
	v_mul_hi_u32 v203, v189, s59
	v_lshrrev_b32_e32 v203, 7, v203
	v_mul_u32_u24_e32 v203, 0x810, v203
	v_sub_u32_e32 v189, v189, v203
	v_cmp_lt_u32_e32 vcc, 0, v189
	v_cmp_lt_u32_e64 s[8:9], 1, v189
	s_nop 1
	v_mov_b32_dpp v228, v24 row_ror:1 row_mask:0xf bank_mask:0xf
	v_mov_b32_dpp v229, v24 row_ror:2 row_mask:0xf bank_mask:0xf
	v_mov_b32_dpp v230, v25 row_ror:1 row_mask:0xf bank_mask:0xf
	v_mov_b32_dpp v231, v25 row_ror:2 row_mask:0xf bank_mask:0xf
	v_mov_b32_dpp v232, v26 row_ror:1 row_mask:0xf bank_mask:0xf
	v_mov_b32_dpp v233, v26 row_ror:2 row_mask:0xf bank_mask:0xf
	v_mov_b32_dpp v234, v27 row_ror:1 row_mask:0xf bank_mask:0xf
	v_mov_b32_dpp v235, v27 row_ror:2 row_mask:0xf bank_mask:0xf
	v_mov_b32_dpp v228, v12 row_shr:1 row_mask:0xf bank_mask:0xf
	v_mov_b32_dpp v229, v12 row_shr:2 row_mask:0xf bank_mask:0xf
	v_mov_b32_dpp v230, v13 row_shr:1 row_mask:0xf bank_mask:0xf
	v_mov_b32_dpp v231, v13 row_shr:2 row_mask:0xf bank_mask:0xf
	v_mov_b32_dpp v232, v14 row_shr:1 row_mask:0xf bank_mask:0xf
	v_mov_b32_dpp v233, v14 row_shr:2 row_mask:0xf bank_mask:0xf
	v_mov_b32_dpp v234, v15 row_shr:1 row_mask:0xf bank_mask:0xf
	v_mov_b32_dpp v235, v15 row_shr:2 row_mask:0xf bank_mask:0xf
	v_cndmask_b32_e64 v228, 0, v228, vcc
	v_cndmask_b32_e64 v229, 0, v229, s[8:9]
	v_cndmask_b32_e64 v230, 0, v230, vcc
	v_cndmask_b32_e64 v231, 0, v231, s[8:9]
	v_cndmask_b32_e64 v232, 0, v232, vcc
	v_cndmask_b32_e64 v233, 0, v233, s[8:9]
	v_cndmask_b32_e64 v234, 0, v234, vcc
	v_cndmask_b32_e64 v235, 0, v235, s[8:9]
	v_fma_f32 v236, v229, v128, v152
	v_fma_f32 v237, v231, v129, v153
	v_fma_f32 v238, v233, v130, v154
	v_fma_f32 v239, v235, v131, v155
	v_fmac_f32_e32 v236, v228, v136
	v_fmac_f32_e32 v237, v230, v137
	v_fmac_f32_e32 v238, v232, v138
	v_fmac_f32_e32 v239, v234, v139
	v_fmac_f32_e32 v236, v12, v144
	v_fmac_f32_e32 v237, v13, v145
	v_fmac_f32_e32 v238, v14, v146
	v_fmac_f32_e32 v239, v15, v147
	v_mov_b32_dpp v228, v16 row_ror:1 row_mask:0xf bank_mask:0xf
	v_mov_b32_dpp v229, v16 row_ror:2 row_mask:0xf bank_mask:0xf
	v_mov_b32_dpp v230, v17 row_ror:1 row_mask:0xf bank_mask:0xf
	v_mov_b32_dpp v231, v17 row_ror:2 row_mask:0xf bank_mask:0xf
	v_mov_b32_dpp v232, v18 row_ror:1 row_mask:0xf bank_mask:0xf
	v_mov_b32_dpp v233, v18 row_ror:2 row_mask:0xf bank_mask:0xf
	v_mov_b32_dpp v234, v19 row_ror:1 row_mask:0xf bank_mask:0xf
	v_mov_b32_dpp v235, v19 row_ror:2 row_mask:0xf bank_mask:0xf
	v_mov_b32_dpp v228, v0 row_shr:1 row_mask:0xf bank_mask:0xf
	v_mov_b32_dpp v229, v0 row_shr:2 row_mask:0xf bank_mask:0xf
	v_mov_b32_dpp v230, v1 row_shr:1 row_mask:0xf bank_mask:0xf
	v_mov_b32_dpp v231, v1 row_shr:2 row_mask:0xf bank_mask:0xf
	v_mov_b32_dpp v232, v2 row_shr:1 row_mask:0xf bank_mask:0xf
	v_mov_b32_dpp v233, v2 row_shr:2 row_mask:0xf bank_mask:0xf
	v_mov_b32_dpp v234, v3 row_shr:1 row_mask:0xf bank_mask:0xf
	v_mov_b32_dpp v235, v3 row_shr:2 row_mask:0xf bank_mask:0xf
	v_cndmask_b32_e64 v228, 0, v228, vcc
	v_cndmask_b32_e64 v229, 0, v229, s[8:9]
	v_cndmask_b32_e64 v230, 0, v230, vcc
	v_cndmask_b32_e64 v231, 0, v231, s[8:9]
	v_cndmask_b32_e64 v232, 0, v232, vcc
	v_cndmask_b32_e64 v233, 0, v233, s[8:9]
	v_cndmask_b32_e64 v234, 0, v234, vcc
	v_cndmask_b32_e64 v235, 0, v235, s[8:9]
	v_fma_f32 v240, v229, v132, v156
	v_fma_f32 v241, v231, v133, v157
	v_fma_f32 v242, v233, v134, v158
	v_fma_f32 v243, v235, v135, v159
	v_fmac_f32_e32 v240, v228, v140
	v_fmac_f32_e32 v241, v230, v141
	v_fmac_f32_e32 v242, v232, v142
	v_fmac_f32_e32 v243, v234, v143
	v_fmac_f32_e32 v240, v0, v148
	v_fmac_f32_e32 v241, v1, v149
	v_fmac_f32_e32 v242, v2, v150
	v_fmac_f32_e32 v243, v3, v151
	v_mov_b32_e32 v228, 0xbdd2d3e8
	v_mul_f32_e32 v244, v236, v236
	v_mul_f32_e32 v245, v237, v237
	v_mul_f32_e32 v246, v238, v238
	v_mul_f32_e32 v247, v239, v239
	v_fmaak_f32 v244, v244, v228, 0xc0135761
	v_fmaak_f32 v245, v245, v228, 0xc0135761
	v_fmaak_f32 v246, v246, v228, 0xc0135761
	v_fmaak_f32 v247, v247, v228, 0xc0135761
	v_mul_f32_e32 v244, v236, v244
	v_mul_f32_e32 v245, v237, v245
	v_mul_f32_e32 v246, v238, v246
	v_mul_f32_e32 v247, v239, v247
	v_exp_f32_e32 v244, v244
	v_exp_f32_e32 v245, v245
	v_exp_f32_e32 v246, v246
	v_exp_f32_e32 v247, v247
	v_add_f32_e32 v244, 1.0, v244
	v_add_f32_e32 v245, 1.0, v245
	v_add_f32_e32 v246, 1.0, v246
	v_add_f32_e32 v247, 1.0, v247
	v_rcp_f32_e32 v244, v244
	v_rcp_f32_e32 v245, v245
	v_rcp_f32_e32 v246, v246
	v_rcp_f32_e32 v247, v247
	v_mul_f32_e32 v244, v236, v244
	v_mul_f32_e32 v245, v237, v245
	v_mul_f32_e32 v246, v238, v246
	v_mul_f32_e32 v247, v239, v247
	v_mul_f32_e32 v248, v240, v244
	v_mul_f32_e32 v249, v241, v245
	v_mul_f32_e32 v250, v242, v246
	v_mul_f32_e32 v251, v243, v247
	v_mov_b32_e32 v180, v224
	v_mov_b32_e32 v181, v225
	v_cvt_pk_bf16_f32 v182, v248, v249
	v_cvt_pk_bf16_f32 v183, v250, v251
	s_branch .Lffn1e_join1_7
.Lffn1e_old1_7:
	v_mov_b32_dpp v228, v24 row_ror:1 row_mask:0xf bank_mask:0xf
	v_mov_b32_dpp v229, v24 row_ror:2 row_mask:0xf bank_mask:0xf
	v_mov_b32_dpp v230, v25 row_ror:1 row_mask:0xf bank_mask:0xf
	v_mov_b32_dpp v231, v25 row_ror:2 row_mask:0xf bank_mask:0xf
	v_mov_b32_dpp v232, v26 row_ror:1 row_mask:0xf bank_mask:0xf
	v_mov_b32_dpp v233, v26 row_ror:2 row_mask:0xf bank_mask:0xf
	v_mov_b32_dpp v234, v27 row_ror:1 row_mask:0xf bank_mask:0xf
	v_mov_b32_dpp v235, v27 row_ror:2 row_mask:0xf bank_mask:0xf
	v_mov_b32_dpp v228, v12 row_shr:1 row_mask:0xf bank_mask:0xf
	v_mov_b32_dpp v229, v12 row_shr:2 row_mask:0xf bank_mask:0xf
	v_mov_b32_dpp v230, v13 row_shr:1 row_mask:0xf bank_mask:0xf
	v_mov_b32_dpp v231, v13 row_shr:2 row_mask:0xf bank_mask:0xf
	v_mov_b32_dpp v232, v14 row_shr:1 row_mask:0xf bank_mask:0xf
	v_mov_b32_dpp v233, v14 row_shr:2 row_mask:0xf bank_mask:0xf
	v_mov_b32_dpp v234, v15 row_shr:1 row_mask:0xf bank_mask:0xf
	v_mov_b32_dpp v235, v15 row_shr:2 row_mask:0xf bank_mask:0xf
	v_fma_f32 v236, v229, v128, v152
	v_fma_f32 v237, v231, v129, v153
	v_fma_f32 v238, v233, v130, v154
	v_fma_f32 v239, v235, v131, v155
	v_fmac_f32_e32 v236, v228, v136
	v_fmac_f32_e32 v237, v230, v137
	v_fmac_f32_e32 v238, v232, v138
	v_fmac_f32_e32 v239, v234, v139
	v_fmac_f32_e32 v236, v12, v144
	v_fmac_f32_e32 v237, v13, v145
	v_fmac_f32_e32 v238, v14, v146
	v_fmac_f32_e32 v239, v15, v147
	v_mov_b32_dpp v228, v16 row_ror:1 row_mask:0xf bank_mask:0xf
	v_mov_b32_dpp v229, v16 row_ror:2 row_mask:0xf bank_mask:0xf
	v_mov_b32_dpp v230, v17 row_ror:1 row_mask:0xf bank_mask:0xf
	v_mov_b32_dpp v231, v17 row_ror:2 row_mask:0xf bank_mask:0xf
	v_mov_b32_dpp v232, v18 row_ror:1 row_mask:0xf bank_mask:0xf
	v_mov_b32_dpp v233, v18 row_ror:2 row_mask:0xf bank_mask:0xf
	v_mov_b32_dpp v234, v19 row_ror:1 row_mask:0xf bank_mask:0xf
	v_mov_b32_dpp v235, v19 row_ror:2 row_mask:0xf bank_mask:0xf
	v_mov_b32_dpp v228, v0 row_shr:1 row_mask:0xf bank_mask:0xf
	v_mov_b32_dpp v229, v0 row_shr:2 row_mask:0xf bank_mask:0xf
	v_mov_b32_dpp v230, v1 row_shr:1 row_mask:0xf bank_mask:0xf
	v_mov_b32_dpp v231, v1 row_shr:2 row_mask:0xf bank_mask:0xf
	v_mov_b32_dpp v232, v2 row_shr:1 row_mask:0xf bank_mask:0xf
	v_mov_b32_dpp v233, v2 row_shr:2 row_mask:0xf bank_mask:0xf
	v_mov_b32_dpp v234, v3 row_shr:1 row_mask:0xf bank_mask:0xf
	v_mov_b32_dpp v235, v3 row_shr:2 row_mask:0xf bank_mask:0xf
	v_fma_f32 v240, v229, v132, v156
	v_fma_f32 v241, v231, v133, v157
	v_fma_f32 v242, v233, v134, v158
	v_fma_f32 v243, v235, v135, v159
	v_fmac_f32_e32 v240, v228, v140
	v_fmac_f32_e32 v241, v230, v141
	v_fmac_f32_e32 v242, v232, v142
	v_fmac_f32_e32 v243, v234, v143
	v_fmac_f32_e32 v240, v0, v148
	v_fmac_f32_e32 v241, v1, v149
	v_fmac_f32_e32 v242, v2, v150
	v_fmac_f32_e32 v243, v3, v151
	v_mov_b32_e32 v228, 0xbdd2d3e8
	v_mul_f32_e32 v244, v236, v236
	v_mul_f32_e32 v245, v237, v237
	v_mul_f32_e32 v246, v238, v238
	v_mul_f32_e32 v247, v239, v239
	v_fmaak_f32 v244, v244, v228, 0xc0135761
	v_fmaak_f32 v245, v245, v228, 0xc0135761
	v_fmaak_f32 v246, v246, v228, 0xc0135761
	v_fmaak_f32 v247, v247, v228, 0xc0135761
	v_mul_f32_e32 v244, v236, v244
	v_mul_f32_e32 v245, v237, v245
	v_mul_f32_e32 v246, v238, v246
	v_mul_f32_e32 v247, v239, v247
	v_exp_f32_e32 v244, v244
	v_exp_f32_e32 v245, v245
	v_exp_f32_e32 v246, v246
	v_exp_f32_e32 v247, v247
	v_add_f32_e32 v244, 1.0, v244
	v_add_f32_e32 v245, 1.0, v245
	v_add_f32_e32 v246, 1.0, v246
	v_add_f32_e32 v247, 1.0, v247
	v_rcp_f32_e32 v244, v244
	v_rcp_f32_e32 v245, v245
	v_rcp_f32_e32 v246, v246
	v_rcp_f32_e32 v247, v247
	v_mul_f32_e32 v244, v236, v244
	v_mul_f32_e32 v245, v237, v245
	v_mul_f32_e32 v246, v238, v246
	v_mul_f32_e32 v247, v239, v247
	v_mul_f32_e32 v248, v240, v244
	v_mul_f32_e32 v249, v241, v245
	v_mul_f32_e32 v250, v242, v246
	v_mul_f32_e32 v251, v243, v247
	v_mov_b32_e32 v180, v224
	v_mov_b32_e32 v181, v225
	v_cvt_pk_bf16_f32 v182, v248, v249
	v_cvt_pk_bf16_f32 v183, v250, v251
	s_branch .Lffn1e_join1_7
